# hand-written input LayerNorm (wg 64..255) and final LayerNorm: all row loads in flight with counted vmcnt, DPP reductions, gamma/beta in registers; final LN rows shifted from workgroups 0..63 (2 rows/
# speedup vs baseline: 1.0173x; 1.0139x over previous
.LBB0_176:
	s_sub_i32 s4, s86, s10
	v_ashrrev_i32_e32 v1, 6, v2
	v_lshl_add_u32 v94, s4, 3, v1
	v_cmp_gt_i32_e32 vcc, s31, v94
	s_and_saveexec_b64 s[4:5], vcc
	s_cbranch_execz .LBB0_187
	s_cmp_eq_u32 s92, 0
	s_movk_i32 s6, 0xa0
	s_cselect_b32 s6, s6, 0xa8
	s_brev_b32 s7, 16
	s_cselect_b32 s11, s7, 0x14e0000
	s_add_u32 s6, s8, s6
	s_addc_u32 s7, s9, 0
	s_load_dwordx2 s[6:7], s[6:7], 0x0
	v_ashrrev_i32_e32 v1, 31, v0
	s_load_dwordx2 s[20:21], s[8:9], 0xa8
	v_lshlrev_b64 v[0:1], 17, v[0:1]
	s_load_dwordx4 s[40:43], s[8:9], 0x10
	s_waitcnt lgkmcnt(0)
	s_add_u32 s6, s6, s11
	s_addc_u32 s7, s7, 0
	v_lshl_add_u64 v[0:1], s[20:21], 0, v[0:1]
	s_mov_b64 s[20:21], 0x1480000
	s_sub_i32 s8, s56, s10
	v_lshl_add_u64 v[0:1], v[0:1], 0, s[20:21]
	s_lshl_b32 s20, s8, 3
	s_lshl_b32 s8, s10, 6
	v_readlane_b32 s9, v254, 27
	s_sub_i32 s21, s9, s8
	s_lshl_b32 s8, s10, 5
	v_readlane_b32 s10, v254, 25
	v_and_b32_e32 v68, 63, v2
	v_lshlrev_b32_e32 v70, 3, v94
	s_waitcnt vmcnt(0)
	v_lshlrev_b32_e32 v72, 2, v94
	s_sub_i32 s34, s10, s8
	s_mov_b64 s[8:9], 0
	v_readlane_b32 s11, v254, 26
	s_cmpk_lg_u32 s56, 0x100
	s_cbranch_scc1 .Lln_generic
	s_cmp_lt_i32 s92, 0
	s_cbranch_scc1 .Lln_generic
	v_readfirstlane_b32 s38, v0
	v_readfirstlane_b32 s39, v1
	v_mbcnt_lo_u32_b32 v0, -1, 0
	v_mbcnt_hi_u32_b32 v0, -1, v0
	v_lshlrev_b32_e32 v1, 4, v0
	v_lshlrev_b32_e32 v5, 3, v0
	v_mov_b32_e32 v2, 0x3a800000
	v_mov_b32_e32 v4, 0x3727c5ac
	s_lshr_b32 s10, s29, 6
	s_sub_u32 s11, s86, 64
	s_lshl_b32 s11, s11, 3
	s_add_i32 s10, s10, s11
	s_lshl_b32 s11, s10, 12
	s_add_u32 s4, s0, s11
	s_addc_u32 s5, s1, 0
	s_lshl_b32 s11, s10, 11
	s_add_u32 s8, s6, s11
	s_addc_u32 s9, s7, 0
	s_lshl_b32 s11, s10, 3
	s_add_u32 s38, s38, s11
	s_addc_u32 s39, s39, 0
	s_cmpk_lt_u32 s10, 0x400
	s_cbranch_scc0 .Lln_r10
	global_load_dwordx4 v[40:43], v1, s[4:5]
	global_load_dwordx4 v[44:47], v1, s[4:5] offset:1024
	global_load_dwordx4 v[48:51], v1, s[4:5] offset:2048
	global_load_dwordx4 v[52:55], v1, s[4:5] offset:3072
	global_load_dwordx4 v[8:11], v1, s[40:41]
	global_load_dwordx4 v[12:15], v1, s[40:41] offset:1024
	global_load_dwordx4 v[16:19], v1, s[40:41] offset:2048
	global_load_dwordx4 v[20:23], v1, s[40:41] offset:3072
	global_load_dwordx4 v[24:27], v1, s[42:43]
	global_load_dwordx4 v[28:31], v1, s[42:43] offset:1024
	global_load_dwordx4 v[32:35], v1, s[42:43] offset:2048
	global_load_dwordx4 v[36:39], v1, s[42:43] offset:3072
	v_add_u32_e32 v170, 0x600000, v1
	global_load_dwordx4 v[56:59], v170, s[4:5]
	global_load_dwordx4 v[60:63], v170, s[4:5] offset:1024
	global_load_dwordx4 v[64:67], v170, s[4:5] offset:2048
	global_load_dwordx4 v[68:71], v170, s[4:5] offset:3072
	v_add_u32_e32 v170, 0xc00000, v1
	global_load_dwordx4 v[72:75], v170, s[4:5]
	global_load_dwordx4 v[76:79], v170, s[4:5] offset:1024
	global_load_dwordx4 v[80:83], v170, s[4:5] offset:2048
	global_load_dwordx4 v[84:87], v170, s[4:5] offset:3072
	v_add_u32_e32 v170, 0x1200000, v1
	global_load_dwordx4 v[88:91], v170, s[4:5]
	global_load_dwordx4 v[92:95], v170, s[4:5] offset:1024
	global_load_dwordx4 v[96:99], v170, s[4:5] offset:2048
	global_load_dwordx4 v[100:103], v170, s[4:5] offset:3072
	v_add_u32_e32 v170, 0x1800000, v1
	global_load_dwordx4 v[104:107], v170, s[4:5]
	global_load_dwordx4 v[108:111], v170, s[4:5] offset:1024
	global_load_dwordx4 v[112:115], v170, s[4:5] offset:2048
	global_load_dwordx4 v[116:119], v170, s[4:5] offset:3072
	v_add_u32_e32 v170, 0x1e00000, v1
	global_load_dwordx4 v[120:123], v170, s[4:5]
	global_load_dwordx4 v[124:127], v170, s[4:5] offset:1024
	global_load_dwordx4 v[128:131], v170, s[4:5] offset:2048
	global_load_dwordx4 v[132:135], v170, s[4:5] offset:3072
	v_add_u32_e32 v170, 0x2400000, v1
	global_load_dwordx4 v[136:139], v170, s[4:5]
	global_load_dwordx4 v[140:143], v170, s[4:5] offset:1024
	global_load_dwordx4 v[144:147], v170, s[4:5] offset:2048
	global_load_dwordx4 v[148:151], v170, s[4:5] offset:3072
	v_add_u32_e32 v170, 0x2a00000, v1
	global_load_dwordx4 v[152:155], v170, s[4:5]
	global_load_dwordx4 v[156:159], v170, s[4:5] offset:1024
	global_load_dwordx4 v[160:163], v170, s[4:5] offset:2048
	global_load_dwordx4 v[164:167], v170, s[4:5] offset:3072
	s_waitcnt vmcnt(36)
	v_add_f32_e32 v180, v40, v41
	v_add_f32_e32 v181, v44, v45
	v_add_f32_e32 v182, v48, v49
	v_add_f32_e32 v183, v52, v53
	v_add_f32_e32 v180, v180, v42
	v_add_f32_e32 v181, v181, v46
	v_add_f32_e32 v182, v182, v50
	v_add_f32_e32 v183, v183, v54
	v_add_f32_e32 v180, v180, v43
	v_add_f32_e32 v181, v181, v47
	v_add_f32_e32 v182, v182, v51
	v_add_f32_e32 v183, v183, v55
	v_add_f32_e32 v180, v180, v181
	v_add_f32_e32 v182, v182, v183
	v_add_f32_e32 v180, v180, v182
	s_nop 1
	v_add_f32_dpp v180, v180, v180 quad_perm:[1,0,3,2] row_mask:0xf bank_mask:0xf
	s_nop 1
	v_add_f32_dpp v180, v180, v180 quad_perm:[2,3,0,1] row_mask:0xf bank_mask:0xf
	s_nop 1
	v_add_f32_dpp v180, v180, v180 row_half_mirror row_mask:0xf bank_mask:0xf
	s_nop 1
	v_add_f32_dpp v180, v180, v180 row_mirror row_mask:0xf bank_mask:0xf
	s_nop 1
	v_add_f32_dpp v180, v180, v180 row_bcast:15 row_mask:0xa bank_mask:0xf
	s_nop 1
	v_add_f32_dpp v180, v180, v180 row_bcast:31 row_mask:0xc bank_mask:0xf
	s_nop 0
	v_readlane_b32 s20, v180, 63
	s_nop 1
	v_mul_f32_e32 v184, s20, v2
	v_sub_f32_e32 v40, v40, v184
	v_sub_f32_e32 v41, v41, v184
	v_sub_f32_e32 v42, v42, v184
	v_sub_f32_e32 v43, v43, v184
	v_sub_f32_e32 v44, v44, v184
	v_sub_f32_e32 v45, v45, v184
	v_sub_f32_e32 v46, v46, v184
	v_sub_f32_e32 v47, v47, v184
	v_sub_f32_e32 v48, v48, v184
	v_sub_f32_e32 v49, v49, v184
	v_sub_f32_e32 v50, v50, v184
	v_sub_f32_e32 v51, v51, v184
	v_sub_f32_e32 v52, v52, v184
	v_sub_f32_e32 v53, v53, v184
	v_sub_f32_e32 v54, v54, v184
	v_sub_f32_e32 v55, v55, v184
	v_mul_f32_e32 v180, v40, v40
	v_mul_f32_e32 v181, v44, v44
	v_mul_f32_e32 v182, v48, v48
	v_mul_f32_e32 v183, v52, v52
	v_fmac_f32_e32 v180, v41, v41
	v_fmac_f32_e32 v181, v45, v45
	v_fmac_f32_e32 v182, v49, v49
	v_fmac_f32_e32 v183, v53, v53
	v_fmac_f32_e32 v180, v42, v42
	v_fmac_f32_e32 v181, v46, v46
	v_fmac_f32_e32 v182, v50, v50
	v_fmac_f32_e32 v183, v54, v54
	v_fmac_f32_e32 v180, v43, v43
	v_fmac_f32_e32 v181, v47, v47
	v_fmac_f32_e32 v182, v51, v51
	v_fmac_f32_e32 v183, v55, v55
	v_add_f32_e32 v180, v180, v181
	v_add_f32_e32 v182, v182, v183
	v_add_f32_e32 v180, v180, v182
	s_nop 1
	v_add_f32_dpp v180, v180, v180 quad_perm:[1,0,3,2] row_mask:0xf bank_mask:0xf
	s_nop 1
	v_add_f32_dpp v180, v180, v180 quad_perm:[2,3,0,1] row_mask:0xf bank_mask:0xf
	s_nop 1
	v_add_f32_dpp v180, v180, v180 row_half_mirror row_mask:0xf bank_mask:0xf
	s_nop 1
	v_add_f32_dpp v180, v180, v180 row_mirror row_mask:0xf bank_mask:0xf
	s_nop 1
	v_add_f32_dpp v180, v180, v180 row_bcast:15 row_mask:0xa bank_mask:0xf
	s_nop 1
	v_add_f32_dpp v180, v180, v180 row_bcast:31 row_mask:0xc bank_mask:0xf
	s_nop 0
	v_readlane_b32 s20, v180, 63
	s_nop 1
	v_mov_b32_e32 v185, s20
	v_fma_f32 v185, v185, v2, v4
	v_rsq_f32_e32 v185, v185
	s_nop 0
	v_mul_f32_e32 v40, v40, v185
	v_mul_f32_e32 v41, v41, v185
	v_mul_f32_e32 v42, v42, v185
	v_mul_f32_e32 v43, v43, v185
	v_mul_f32_e32 v44, v44, v185
	v_mul_f32_e32 v45, v45, v185
	v_mul_f32_e32 v46, v46, v185
	v_mul_f32_e32 v47, v47, v185
	v_mul_f32_e32 v48, v48, v185
	v_mul_f32_e32 v49, v49, v185
	v_mul_f32_e32 v50, v50, v185
	v_mul_f32_e32 v51, v51, v185
	v_mul_f32_e32 v52, v52, v185
	v_mul_f32_e32 v53, v53, v185
	v_mul_f32_e32 v54, v54, v185
	v_mul_f32_e32 v55, v55, v185
	s_waitcnt vmcnt(28)
	v_fma_f32 v40, v40, v8, v24
	v_fma_f32 v41, v41, v9, v25
	v_fma_f32 v42, v42, v10, v26
	v_fma_f32 v43, v43, v11, v27
	v_fma_f32 v44, v44, v12, v28
	v_fma_f32 v45, v45, v13, v29
	v_fma_f32 v46, v46, v14, v30
	v_fma_f32 v47, v47, v15, v31
	v_fma_f32 v48, v48, v16, v32
	v_fma_f32 v49, v49, v17, v33
	v_fma_f32 v50, v50, v18, v34
	v_fma_f32 v51, v51, v19, v35
	v_fma_f32 v52, v52, v20, v36
	v_fma_f32 v53, v53, v21, v37
	v_fma_f32 v54, v54, v22, v38
	v_fma_f32 v55, v55, v23, v39
	v_cvt_pk_bf16_f32 v40, v40, v41
	v_cvt_pk_bf16_f32 v41, v42, v43
	v_cvt_pk_bf16_f32 v44, v44, v45
	v_cvt_pk_bf16_f32 v45, v46, v47
	v_cvt_pk_bf16_f32 v48, v48, v49
	v_cvt_pk_bf16_f32 v49, v50, v51
	v_cvt_pk_bf16_f32 v52, v52, v53
	v_cvt_pk_bf16_f32 v53, v54, v55
	global_store_dwordx2 v5, v[40:41], s[8:9]
	global_store_dwordx2 v5, v[44:45], s[8:9] offset:512
	global_store_dwordx2 v5, v[48:49], s[8:9] offset:1024
	global_store_dwordx2 v5, v[52:53], s[8:9] offset:1536
	v_mov_b32_e32 v172, 0x0
	s_mov_b64 exec, 1
	global_store_dwordx2 v172, v[184:185], s[38:39]
	s_mov_b64 exec, -1
	s_nop 1
	v_add_u32_e32 v170, 0x3000000, v1
	global_load_dwordx4 v[40:43], v170, s[4:5]
	global_load_dwordx4 v[44:47], v170, s[4:5] offset:1024
	global_load_dwordx4 v[48:51], v170, s[4:5] offset:2048
	global_load_dwordx4 v[52:55], v170, s[4:5] offset:3072
	s_waitcnt vmcnt(33)
	v_add_f32_e32 v180, v56, v57
	v_add_f32_e32 v181, v60, v61
	v_add_f32_e32 v182, v64, v65
	v_add_f32_e32 v183, v68, v69
	v_add_f32_e32 v180, v180, v58
	v_add_f32_e32 v181, v181, v62
	v_add_f32_e32 v182, v182, v66
	v_add_f32_e32 v183, v183, v70
	v_add_f32_e32 v180, v180, v59
	v_add_f32_e32 v181, v181, v63
	v_add_f32_e32 v182, v182, v67
	v_add_f32_e32 v183, v183, v71
	v_add_f32_e32 v180, v180, v181
	v_add_f32_e32 v182, v182, v183
	v_add_f32_e32 v180, v180, v182
	s_nop 1
	v_add_f32_dpp v180, v180, v180 quad_perm:[1,0,3,2] row_mask:0xf bank_mask:0xf
	s_nop 1
	v_add_f32_dpp v180, v180, v180 quad_perm:[2,3,0,1] row_mask:0xf bank_mask:0xf
	s_nop 1
	v_add_f32_dpp v180, v180, v180 row_half_mirror row_mask:0xf bank_mask:0xf
	s_nop 1
	v_add_f32_dpp v180, v180, v180 row_mirror row_mask:0xf bank_mask:0xf
	s_nop 1
	v_add_f32_dpp v180, v180, v180 row_bcast:15 row_mask:0xa bank_mask:0xf
	s_nop 1
	v_add_f32_dpp v180, v180, v180 row_bcast:31 row_mask:0xc bank_mask:0xf
	s_nop 0
	v_readlane_b32 s20, v180, 63
	s_nop 1
	v_mul_f32_e32 v184, s20, v2
	v_sub_f32_e32 v56, v56, v184
	v_sub_f32_e32 v57, v57, v184
	v_sub_f32_e32 v58, v58, v184
	v_sub_f32_e32 v59, v59, v184
	v_sub_f32_e32 v60, v60, v184
	v_sub_f32_e32 v61, v61, v184
	v_sub_f32_e32 v62, v62, v184
	v_sub_f32_e32 v63, v63, v184
	v_sub_f32_e32 v64, v64, v184
	v_sub_f32_e32 v65, v65, v184
	v_sub_f32_e32 v66, v66, v184
	v_sub_f32_e32 v67, v67, v184
	v_sub_f32_e32 v68, v68, v184
	v_sub_f32_e32 v69, v69, v184
	v_sub_f32_e32 v70, v70, v184
	v_sub_f32_e32 v71, v71, v184
	v_mul_f32_e32 v180, v56, v56
	v_mul_f32_e32 v181, v60, v60
	v_mul_f32_e32 v182, v64, v64
	v_mul_f32_e32 v183, v68, v68
	v_fmac_f32_e32 v180, v57, v57
	v_fmac_f32_e32 v181, v61, v61
	v_fmac_f32_e32 v182, v65, v65
	v_fmac_f32_e32 v183, v69, v69
	v_fmac_f32_e32 v180, v58, v58
	v_fmac_f32_e32 v181, v62, v62
	v_fmac_f32_e32 v182, v66, v66
	v_fmac_f32_e32 v183, v70, v70
	v_fmac_f32_e32 v180, v59, v59
	v_fmac_f32_e32 v181, v63, v63
	v_fmac_f32_e32 v182, v67, v67
	v_fmac_f32_e32 v183, v71, v71
	v_add_f32_e32 v180, v180, v181
	v_add_f32_e32 v182, v182, v183
	v_add_f32_e32 v180, v180, v182
	s_nop 1
	v_add_f32_dpp v180, v180, v180 quad_perm:[1,0,3,2] row_mask:0xf bank_mask:0xf
	s_nop 1
	v_add_f32_dpp v180, v180, v180 quad_perm:[2,3,0,1] row_mask:0xf bank_mask:0xf
	s_nop 1
	v_add_f32_dpp v180, v180, v180 row_half_mirror row_mask:0xf bank_mask:0xf
	s_nop 1
	v_add_f32_dpp v180, v180, v180 row_mirror row_mask:0xf bank_mask:0xf
	s_nop 1
	v_add_f32_dpp v180, v180, v180 row_bcast:15 row_mask:0xa bank_mask:0xf
	s_nop 1
	v_add_f32_dpp v180, v180, v180 row_bcast:31 row_mask:0xc bank_mask:0xf
	s_nop 0
	v_readlane_b32 s20, v180, 63
	s_nop 1
	v_mov_b32_e32 v185, s20
	v_fma_f32 v185, v185, v2, v4
	v_rsq_f32_e32 v185, v185
	s_nop 0
	v_mul_f32_e32 v56, v56, v185
	v_mul_f32_e32 v57, v57, v185
	v_mul_f32_e32 v58, v58, v185
	v_mul_f32_e32 v59, v59, v185
	v_mul_f32_e32 v60, v60, v185
	v_mul_f32_e32 v61, v61, v185
	v_mul_f32_e32 v62, v62, v185
	v_mul_f32_e32 v63, v63, v185
	v_mul_f32_e32 v64, v64, v185
	v_mul_f32_e32 v65, v65, v185
	v_mul_f32_e32 v66, v66, v185
	v_mul_f32_e32 v67, v67, v185
	v_mul_f32_e32 v68, v68, v185
	v_mul_f32_e32 v69, v69, v185
	v_mul_f32_e32 v70, v70, v185
	v_mul_f32_e32 v71, v71, v185
	v_fma_f32 v56, v56, v8, v24
	v_fma_f32 v57, v57, v9, v25
	v_fma_f32 v58, v58, v10, v26
	v_fma_f32 v59, v59, v11, v27
	v_fma_f32 v60, v60, v12, v28
	v_fma_f32 v61, v61, v13, v29
	v_fma_f32 v62, v62, v14, v30
	v_fma_f32 v63, v63, v15, v31
	v_fma_f32 v64, v64, v16, v32
	v_fma_f32 v65, v65, v17, v33
	v_fma_f32 v66, v66, v18, v34
	v_fma_f32 v67, v67, v19, v35
	v_fma_f32 v68, v68, v20, v36
	v_fma_f32 v69, v69, v21, v37
	v_fma_f32 v70, v70, v22, v38
	v_fma_f32 v71, v71, v23, v39
	v_cvt_pk_bf16_f32 v56, v56, v57
	v_cvt_pk_bf16_f32 v57, v58, v59
	v_cvt_pk_bf16_f32 v60, v60, v61
	v_cvt_pk_bf16_f32 v61, v62, v63
	v_cvt_pk_bf16_f32 v64, v64, v65
	v_cvt_pk_bf16_f32 v65, v66, v67
	v_cvt_pk_bf16_f32 v68, v68, v69
	v_cvt_pk_bf16_f32 v69, v70, v71
	v_add_u32_e32 v171, 0x300000, v5
	global_store_dwordx2 v171, v[56:57], s[8:9]
	global_store_dwordx2 v171, v[60:61], s[8:9] offset:512
	global_store_dwordx2 v171, v[64:65], s[8:9] offset:1024
	global_store_dwordx2 v171, v[68:69], s[8:9] offset:1536
	v_mov_b32_e32 v172, 0x3000
	s_mov_b64 exec, 1
	global_store_dwordx2 v172, v[184:185], s[38:39]
	s_mov_b64 exec, -1
	s_nop 1
	v_add_u32_e32 v170, 0x3600000, v1
	global_load_dwordx4 v[56:59], v170, s[4:5]
	global_load_dwordx4 v[60:63], v170, s[4:5] offset:1024
	global_load_dwordx4 v[64:67], v170, s[4:5] offset:2048
	global_load_dwordx4 v[68:71], v170, s[4:5] offset:3072
	s_waitcnt vmcnt(38)
	v_add_f32_e32 v180, v72, v73
	v_add_f32_e32 v181, v76, v77
	v_add_f32_e32 v182, v80, v81
	v_add_f32_e32 v183, v84, v85
	v_add_f32_e32 v180, v180, v74
	v_add_f32_e32 v181, v181, v78
	v_add_f32_e32 v182, v182, v82
	v_add_f32_e32 v183, v183, v86
	v_add_f32_e32 v180, v180, v75
	v_add_f32_e32 v181, v181, v79
	v_add_f32_e32 v182, v182, v83
	v_add_f32_e32 v183, v183, v87
	v_add_f32_e32 v180, v180, v181
	v_add_f32_e32 v182, v182, v183
	v_add_f32_e32 v180, v180, v182
	s_nop 1
	v_add_f32_dpp v180, v180, v180 quad_perm:[1,0,3,2] row_mask:0xf bank_mask:0xf
	s_nop 1
	v_add_f32_dpp v180, v180, v180 quad_perm:[2,3,0,1] row_mask:0xf bank_mask:0xf
	s_nop 1
	v_add_f32_dpp v180, v180, v180 row_half_mirror row_mask:0xf bank_mask:0xf
	s_nop 1
	v_add_f32_dpp v180, v180, v180 row_mirror row_mask:0xf bank_mask:0xf
	s_nop 1
	v_add_f32_dpp v180, v180, v180 row_bcast:15 row_mask:0xa bank_mask:0xf
	s_nop 1
	v_add_f32_dpp v180, v180, v180 row_bcast:31 row_mask:0xc bank_mask:0xf
	s_nop 0
	v_readlane_b32 s20, v180, 63
	s_nop 1
	v_mul_f32_e32 v184, s20, v2
	v_sub_f32_e32 v72, v72, v184
	v_sub_f32_e32 v73, v73, v184
	v_sub_f32_e32 v74, v74, v184
	v_sub_f32_e32 v75, v75, v184
	v_sub_f32_e32 v76, v76, v184
	v_sub_f32_e32 v77, v77, v184
	v_sub_f32_e32 v78, v78, v184
	v_sub_f32_e32 v79, v79, v184
	v_sub_f32_e32 v80, v80, v184
	v_sub_f32_e32 v81, v81, v184
	v_sub_f32_e32 v82, v82, v184
	v_sub_f32_e32 v83, v83, v184
	v_sub_f32_e32 v84, v84, v184
	v_sub_f32_e32 v85, v85, v184
	v_sub_f32_e32 v86, v86, v184
	v_sub_f32_e32 v87, v87, v184
	v_mul_f32_e32 v180, v72, v72
	v_mul_f32_e32 v181, v76, v76
	v_mul_f32_e32 v182, v80, v80
	v_mul_f32_e32 v183, v84, v84
	v_fmac_f32_e32 v180, v73, v73
	v_fmac_f32_e32 v181, v77, v77
	v_fmac_f32_e32 v182, v81, v81
	v_fmac_f32_e32 v183, v85, v85
	v_fmac_f32_e32 v180, v74, v74
	v_fmac_f32_e32 v181, v78, v78
	v_fmac_f32_e32 v182, v82, v82
	v_fmac_f32_e32 v183, v86, v86
	v_fmac_f32_e32 v180, v75, v75
	v_fmac_f32_e32 v181, v79, v79
	v_fmac_f32_e32 v182, v83, v83
	v_fmac_f32_e32 v183, v87, v87
	v_add_f32_e32 v180, v180, v181
	v_add_f32_e32 v182, v182, v183
	v_add_f32_e32 v180, v180, v182
	s_nop 1
	v_add_f32_dpp v180, v180, v180 quad_perm:[1,0,3,2] row_mask:0xf bank_mask:0xf
	s_nop 1
	v_add_f32_dpp v180, v180, v180 quad_perm:[2,3,0,1] row_mask:0xf bank_mask:0xf
	s_nop 1
	v_add_f32_dpp v180, v180, v180 row_half_mirror row_mask:0xf bank_mask:0xf
	s_nop 1
	v_add_f32_dpp v180, v180, v180 row_mirror row_mask:0xf bank_mask:0xf
	s_nop 1
	v_add_f32_dpp v180, v180, v180 row_bcast:15 row_mask:0xa bank_mask:0xf
	s_nop 1
	v_add_f32_dpp v180, v180, v180 row_bcast:31 row_mask:0xc bank_mask:0xf
	s_nop 0
	v_readlane_b32 s20, v180, 63
	s_nop 1
	v_mov_b32_e32 v185, s20
	v_fma_f32 v185, v185, v2, v4
	v_rsq_f32_e32 v185, v185
	s_nop 0
	v_mul_f32_e32 v72, v72, v185
	v_mul_f32_e32 v73, v73, v185
	v_mul_f32_e32 v74, v74, v185
	v_mul_f32_e32 v75, v75, v185
	v_mul_f32_e32 v76, v76, v185
	v_mul_f32_e32 v77, v77, v185
	v_mul_f32_e32 v78, v78, v185
	v_mul_f32_e32 v79, v79, v185
	v_mul_f32_e32 v80, v80, v185
	v_mul_f32_e32 v81, v81, v185
	v_mul_f32_e32 v82, v82, v185
	v_mul_f32_e32 v83, v83, v185
	v_mul_f32_e32 v84, v84, v185
	v_mul_f32_e32 v85, v85, v185
	v_mul_f32_e32 v86, v86, v185
	v_mul_f32_e32 v87, v87, v185
	v_fma_f32 v72, v72, v8, v24
	v_fma_f32 v73, v73, v9, v25
	v_fma_f32 v74, v74, v10, v26
	v_fma_f32 v75, v75, v11, v27
	v_fma_f32 v76, v76, v12, v28
	v_fma_f32 v77, v77, v13, v29
	v_fma_f32 v78, v78, v14, v30
	v_fma_f32 v79, v79, v15, v31
	v_fma_f32 v80, v80, v16, v32
	v_fma_f32 v81, v81, v17, v33
	v_fma_f32 v82, v82, v18, v34
	v_fma_f32 v83, v83, v19, v35
	v_fma_f32 v84, v84, v20, v36
	v_fma_f32 v85, v85, v21, v37
	v_fma_f32 v86, v86, v22, v38
	v_fma_f32 v87, v87, v23, v39
	v_cvt_pk_bf16_f32 v72, v72, v73
	v_cvt_pk_bf16_f32 v73, v74, v75
	v_cvt_pk_bf16_f32 v76, v76, v77
	v_cvt_pk_bf16_f32 v77, v78, v79
	v_cvt_pk_bf16_f32 v80, v80, v81
	v_cvt_pk_bf16_f32 v81, v82, v83
	v_cvt_pk_bf16_f32 v84, v84, v85
	v_cvt_pk_bf16_f32 v85, v86, v87
	v_add_u32_e32 v171, 0x600000, v5
	global_store_dwordx2 v171, v[72:73], s[8:9]
	global_store_dwordx2 v171, v[76:77], s[8:9] offset:512
	global_store_dwordx2 v171, v[80:81], s[8:9] offset:1024
	global_store_dwordx2 v171, v[84:85], s[8:9] offset:1536
	v_mov_b32_e32 v172, 0x6000
	s_mov_b64 exec, 1
	global_store_dwordx2 v172, v[184:185], s[38:39]
	s_mov_b64 exec, -1
	s_nop 1
	v_add_u32_e32 v170, 0x3c00000, v1
	global_load_dwordx4 v[72:75], v170, s[4:5]
	global_load_dwordx4 v[76:79], v170, s[4:5] offset:1024
	global_load_dwordx4 v[80:83], v170, s[4:5] offset:2048
	global_load_dwordx4 v[84:87], v170, s[4:5] offset:3072
	s_waitcnt vmcnt(43)
	v_add_f32_e32 v180, v88, v89
	v_add_f32_e32 v181, v92, v93
	v_add_f32_e32 v182, v96, v97
	v_add_f32_e32 v183, v100, v101
	v_add_f32_e32 v180, v180, v90
	v_add_f32_e32 v181, v181, v94
	v_add_f32_e32 v182, v182, v98
	v_add_f32_e32 v183, v183, v102
	v_add_f32_e32 v180, v180, v91
	v_add_f32_e32 v181, v181, v95
	v_add_f32_e32 v182, v182, v99
	v_add_f32_e32 v183, v183, v103
	v_add_f32_e32 v180, v180, v181
	v_add_f32_e32 v182, v182, v183
	v_add_f32_e32 v180, v180, v182
	s_nop 1
	v_add_f32_dpp v180, v180, v180 quad_perm:[1,0,3,2] row_mask:0xf bank_mask:0xf
	s_nop 1
	v_add_f32_dpp v180, v180, v180 quad_perm:[2,3,0,1] row_mask:0xf bank_mask:0xf
	s_nop 1
	v_add_f32_dpp v180, v180, v180 row_half_mirror row_mask:0xf bank_mask:0xf
	s_nop 1
	v_add_f32_dpp v180, v180, v180 row_mirror row_mask:0xf bank_mask:0xf
	s_nop 1
	v_add_f32_dpp v180, v180, v180 row_bcast:15 row_mask:0xa bank_mask:0xf
	s_nop 1
	v_add_f32_dpp v180, v180, v180 row_bcast:31 row_mask:0xc bank_mask:0xf
	s_nop 0
	v_readlane_b32 s20, v180, 63
	s_nop 1
	v_mul_f32_e32 v184, s20, v2
	v_sub_f32_e32 v88, v88, v184
	v_sub_f32_e32 v89, v89, v184
	v_sub_f32_e32 v90, v90, v184
	v_sub_f32_e32 v91, v91, v184
	v_sub_f32_e32 v92, v92, v184
	v_sub_f32_e32 v93, v93, v184
	v_sub_f32_e32 v94, v94, v184
	v_sub_f32_e32 v95, v95, v184
	v_sub_f32_e32 v96, v96, v184
	v_sub_f32_e32 v97, v97, v184
	v_sub_f32_e32 v98, v98, v184
	v_sub_f32_e32 v99, v99, v184
	v_sub_f32_e32 v100, v100, v184
	v_sub_f32_e32 v101, v101, v184
	v_sub_f32_e32 v102, v102, v184
	v_sub_f32_e32 v103, v103, v184
	v_mul_f32_e32 v180, v88, v88
	v_mul_f32_e32 v181, v92, v92
	v_mul_f32_e32 v182, v96, v96
	v_mul_f32_e32 v183, v100, v100
	v_fmac_f32_e32 v180, v89, v89
	v_fmac_f32_e32 v181, v93, v93
	v_fmac_f32_e32 v182, v97, v97
	v_fmac_f32_e32 v183, v101, v101
	v_fmac_f32_e32 v180, v90, v90
	v_fmac_f32_e32 v181, v94, v94
	v_fmac_f32_e32 v182, v98, v98
	v_fmac_f32_e32 v183, v102, v102
	v_fmac_f32_e32 v180, v91, v91
	v_fmac_f32_e32 v181, v95, v95
	v_fmac_f32_e32 v182, v99, v99
	v_fmac_f32_e32 v183, v103, v103
	v_add_f32_e32 v180, v180, v181
	v_add_f32_e32 v182, v182, v183
	v_add_f32_e32 v180, v180, v182
	s_nop 1
	v_add_f32_dpp v180, v180, v180 quad_perm:[1,0,3,2] row_mask:0xf bank_mask:0xf
	s_nop 1
	v_add_f32_dpp v180, v180, v180 quad_perm:[2,3,0,1] row_mask:0xf bank_mask:0xf
	s_nop 1
	v_add_f32_dpp v180, v180, v180 row_half_mirror row_mask:0xf bank_mask:0xf
	s_nop 1
	v_add_f32_dpp v180, v180, v180 row_mirror row_mask:0xf bank_mask:0xf
	s_nop 1
	v_add_f32_dpp v180, v180, v180 row_bcast:15 row_mask:0xa bank_mask:0xf
	s_nop 1
	v_add_f32_dpp v180, v180, v180 row_bcast:31 row_mask:0xc bank_mask:0xf
	s_nop 0
	v_readlane_b32 s20, v180, 63
	s_nop 1
	v_mov_b32_e32 v185, s20
	v_fma_f32 v185, v185, v2, v4
	v_rsq_f32_e32 v185, v185
	s_nop 0
	v_mul_f32_e32 v88, v88, v185
	v_mul_f32_e32 v89, v89, v185
	v_mul_f32_e32 v90, v90, v185
	v_mul_f32_e32 v91, v91, v185
	v_mul_f32_e32 v92, v92, v185
	v_mul_f32_e32 v93, v93, v185
	v_mul_f32_e32 v94, v94, v185
	v_mul_f32_e32 v95, v95, v185
	v_mul_f32_e32 v96, v96, v185
	v_mul_f32_e32 v97, v97, v185
	v_mul_f32_e32 v98, v98, v185
	v_mul_f32_e32 v99, v99, v185
	v_mul_f32_e32 v100, v100, v185
	v_mul_f32_e32 v101, v101, v185
	v_mul_f32_e32 v102, v102, v185
	v_mul_f32_e32 v103, v103, v185
	v_fma_f32 v88, v88, v8, v24
	v_fma_f32 v89, v89, v9, v25
	v_fma_f32 v90, v90, v10, v26
	v_fma_f32 v91, v91, v11, v27
	v_fma_f32 v92, v92, v12, v28
	v_fma_f32 v93, v93, v13, v29
	v_fma_f32 v94, v94, v14, v30
	v_fma_f32 v95, v95, v15, v31
	v_fma_f32 v96, v96, v16, v32
	v_fma_f32 v97, v97, v17, v33
	v_fma_f32 v98, v98, v18, v34
	v_fma_f32 v99, v99, v19, v35
	v_fma_f32 v100, v100, v20, v36
	v_fma_f32 v101, v101, v21, v37
	v_fma_f32 v102, v102, v22, v38
	v_fma_f32 v103, v103, v23, v39
	v_cvt_pk_bf16_f32 v88, v88, v89
	v_cvt_pk_bf16_f32 v89, v90, v91
	v_cvt_pk_bf16_f32 v92, v92, v93
	v_cvt_pk_bf16_f32 v93, v94, v95
	v_cvt_pk_bf16_f32 v96, v96, v97
	v_cvt_pk_bf16_f32 v97, v98, v99
	v_cvt_pk_bf16_f32 v100, v100, v101
	v_cvt_pk_bf16_f32 v101, v102, v103
	v_add_u32_e32 v171, 0x900000, v5
	global_store_dwordx2 v171, v[88:89], s[8:9]
	global_store_dwordx2 v171, v[92:93], s[8:9] offset:512
	global_store_dwordx2 v171, v[96:97], s[8:9] offset:1024
	global_store_dwordx2 v171, v[100:101], s[8:9] offset:1536
	v_mov_b32_e32 v172, 0x9000
	s_mov_b64 exec, 1
	global_store_dwordx2 v172, v[184:185], s[38:39]
	s_mov_b64 exec, -1
	s_waitcnt vmcnt(44)
	v_add_f32_e32 v180, v104, v105
	v_add_f32_e32 v181, v108, v109
	v_add_f32_e32 v182, v112, v113
	v_add_f32_e32 v183, v116, v117
	v_add_f32_e32 v180, v180, v106
	v_add_f32_e32 v181, v181, v110
	v_add_f32_e32 v182, v182, v114
	v_add_f32_e32 v183, v183, v118
	v_add_f32_e32 v180, v180, v107
	v_add_f32_e32 v181, v181, v111
	v_add_f32_e32 v182, v182, v115
	v_add_f32_e32 v183, v183, v119
	v_add_f32_e32 v180, v180, v181
	v_add_f32_e32 v182, v182, v183
	v_add_f32_e32 v180, v180, v182
	s_nop 1
	v_add_f32_dpp v180, v180, v180 quad_perm:[1,0,3,2] row_mask:0xf bank_mask:0xf
	s_nop 1
	v_add_f32_dpp v180, v180, v180 quad_perm:[2,3,0,1] row_mask:0xf bank_mask:0xf
	s_nop 1
	v_add_f32_dpp v180, v180, v180 row_half_mirror row_mask:0xf bank_mask:0xf
	s_nop 1
	v_add_f32_dpp v180, v180, v180 row_mirror row_mask:0xf bank_mask:0xf
	s_nop 1
	v_add_f32_dpp v180, v180, v180 row_bcast:15 row_mask:0xa bank_mask:0xf
	s_nop 1
	v_add_f32_dpp v180, v180, v180 row_bcast:31 row_mask:0xc bank_mask:0xf
	s_nop 0
	v_readlane_b32 s20, v180, 63
	s_nop 1
	v_mul_f32_e32 v184, s20, v2
	v_sub_f32_e32 v104, v104, v184
	v_sub_f32_e32 v105, v105, v184
	v_sub_f32_e32 v106, v106, v184
	v_sub_f32_e32 v107, v107, v184
	v_sub_f32_e32 v108, v108, v184
	v_sub_f32_e32 v109, v109, v184
	v_sub_f32_e32 v110, v110, v184
	v_sub_f32_e32 v111, v111, v184
	v_sub_f32_e32 v112, v112, v184
	v_sub_f32_e32 v113, v113, v184
	v_sub_f32_e32 v114, v114, v184
	v_sub_f32_e32 v115, v115, v184
	v_sub_f32_e32 v116, v116, v184
	v_sub_f32_e32 v117, v117, v184
	v_sub_f32_e32 v118, v118, v184
	v_sub_f32_e32 v119, v119, v184
	v_mul_f32_e32 v180, v104, v104
	v_mul_f32_e32 v181, v108, v108
	v_mul_f32_e32 v182, v112, v112
	v_mul_f32_e32 v183, v116, v116
	v_fmac_f32_e32 v180, v105, v105
	v_fmac_f32_e32 v181, v109, v109
	v_fmac_f32_e32 v182, v113, v113
	v_fmac_f32_e32 v183, v117, v117
	v_fmac_f32_e32 v180, v106, v106
	v_fmac_f32_e32 v181, v110, v110
	v_fmac_f32_e32 v182, v114, v114
	v_fmac_f32_e32 v183, v118, v118
	v_fmac_f32_e32 v180, v107, v107
	v_fmac_f32_e32 v181, v111, v111
	v_fmac_f32_e32 v182, v115, v115
	v_fmac_f32_e32 v183, v119, v119
	v_add_f32_e32 v180, v180, v181
	v_add_f32_e32 v182, v182, v183
	v_add_f32_e32 v180, v180, v182
	s_nop 1
	v_add_f32_dpp v180, v180, v180 quad_perm:[1,0,3,2] row_mask:0xf bank_mask:0xf
	s_nop 1
	v_add_f32_dpp v180, v180, v180 quad_perm:[2,3,0,1] row_mask:0xf bank_mask:0xf
	s_nop 1
	v_add_f32_dpp v180, v180, v180 row_half_mirror row_mask:0xf bank_mask:0xf
	s_nop 1
	v_add_f32_dpp v180, v180, v180 row_mirror row_mask:0xf bank_mask:0xf
	s_nop 1
	v_add_f32_dpp v180, v180, v180 row_bcast:15 row_mask:0xa bank_mask:0xf
	s_nop 1
	v_add_f32_dpp v180, v180, v180 row_bcast:31 row_mask:0xc bank_mask:0xf
	s_nop 0
	v_readlane_b32 s20, v180, 63
	s_nop 1
	v_mov_b32_e32 v185, s20
	v_fma_f32 v185, v185, v2, v4
	v_rsq_f32_e32 v185, v185
	s_nop 0
	v_mul_f32_e32 v104, v104, v185
	v_mul_f32_e32 v105, v105, v185
	v_mul_f32_e32 v106, v106, v185
	v_mul_f32_e32 v107, v107, v185
	v_mul_f32_e32 v108, v108, v185
	v_mul_f32_e32 v109, v109, v185
	v_mul_f32_e32 v110, v110, v185
	v_mul_f32_e32 v111, v111, v185
	v_mul_f32_e32 v112, v112, v185
	v_mul_f32_e32 v113, v113, v185
	v_mul_f32_e32 v114, v114, v185
	v_mul_f32_e32 v115, v115, v185
	v_mul_f32_e32 v116, v116, v185
	v_mul_f32_e32 v117, v117, v185
	v_mul_f32_e32 v118, v118, v185
	v_mul_f32_e32 v119, v119, v185
	v_fma_f32 v104, v104, v8, v24
	v_fma_f32 v105, v105, v9, v25
	v_fma_f32 v106, v106, v10, v26
	v_fma_f32 v107, v107, v11, v27
	v_fma_f32 v108, v108, v12, v28
	v_fma_f32 v109, v109, v13, v29
	v_fma_f32 v110, v110, v14, v30
	v_fma_f32 v111, v111, v15, v31
	v_fma_f32 v112, v112, v16, v32
	v_fma_f32 v113, v113, v17, v33
	v_fma_f32 v114, v114, v18, v34
	v_fma_f32 v115, v115, v19, v35
	v_fma_f32 v116, v116, v20, v36
	v_fma_f32 v117, v117, v21, v37
	v_fma_f32 v118, v118, v22, v38
	v_fma_f32 v119, v119, v23, v39
	v_cvt_pk_bf16_f32 v104, v104, v105
	v_cvt_pk_bf16_f32 v105, v106, v107
	v_cvt_pk_bf16_f32 v108, v108, v109
	v_cvt_pk_bf16_f32 v109, v110, v111
	v_cvt_pk_bf16_f32 v112, v112, v113
	v_cvt_pk_bf16_f32 v113, v114, v115
	v_cvt_pk_bf16_f32 v116, v116, v117
	v_cvt_pk_bf16_f32 v117, v118, v119
	v_add_u32_e32 v171, 0xc00000, v5
	global_store_dwordx2 v171, v[104:105], s[8:9]
	global_store_dwordx2 v171, v[108:109], s[8:9] offset:512
	global_store_dwordx2 v171, v[112:113], s[8:9] offset:1024
	global_store_dwordx2 v171, v[116:117], s[8:9] offset:1536
	v_mov_b32_e32 v172, 0xc000
	s_mov_b64 exec, 1
	global_store_dwordx2 v172, v[184:185], s[38:39]
	s_mov_b64 exec, -1
	s_waitcnt vmcnt(45)
	v_add_f32_e32 v180, v120, v121
	v_add_f32_e32 v181, v124, v125
	v_add_f32_e32 v182, v128, v129
	v_add_f32_e32 v183, v132, v133
	v_add_f32_e32 v180, v180, v122
	v_add_f32_e32 v181, v181, v126
	v_add_f32_e32 v182, v182, v130
	v_add_f32_e32 v183, v183, v134
	v_add_f32_e32 v180, v180, v123
	v_add_f32_e32 v181, v181, v127
	v_add_f32_e32 v182, v182, v131
	v_add_f32_e32 v183, v183, v135
	v_add_f32_e32 v180, v180, v181
	v_add_f32_e32 v182, v182, v183
	v_add_f32_e32 v180, v180, v182
	s_nop 1
	v_add_f32_dpp v180, v180, v180 quad_perm:[1,0,3,2] row_mask:0xf bank_mask:0xf
	s_nop 1
	v_add_f32_dpp v180, v180, v180 quad_perm:[2,3,0,1] row_mask:0xf bank_mask:0xf
	s_nop 1
	v_add_f32_dpp v180, v180, v180 row_half_mirror row_mask:0xf bank_mask:0xf
	s_nop 1
	v_add_f32_dpp v180, v180, v180 row_mirror row_mask:0xf bank_mask:0xf
	s_nop 1
	v_add_f32_dpp v180, v180, v180 row_bcast:15 row_mask:0xa bank_mask:0xf
	s_nop 1
	v_add_f32_dpp v180, v180, v180 row_bcast:31 row_mask:0xc bank_mask:0xf
	s_nop 0
	v_readlane_b32 s20, v180, 63
	s_nop 1
	v_mul_f32_e32 v184, s20, v2
	v_sub_f32_e32 v120, v120, v184
	v_sub_f32_e32 v121, v121, v184
	v_sub_f32_e32 v122, v122, v184
	v_sub_f32_e32 v123, v123, v184
	v_sub_f32_e32 v124, v124, v184
	v_sub_f32_e32 v125, v125, v184
	v_sub_f32_e32 v126, v126, v184
	v_sub_f32_e32 v127, v127, v184
	v_sub_f32_e32 v128, v128, v184
	v_sub_f32_e32 v129, v129, v184
	v_sub_f32_e32 v130, v130, v184
	v_sub_f32_e32 v131, v131, v184
	v_sub_f32_e32 v132, v132, v184
	v_sub_f32_e32 v133, v133, v184
	v_sub_f32_e32 v134, v134, v184
	v_sub_f32_e32 v135, v135, v184
	v_mul_f32_e32 v180, v120, v120
	v_mul_f32_e32 v181, v124, v124
	v_mul_f32_e32 v182, v128, v128
	v_mul_f32_e32 v183, v132, v132
	v_fmac_f32_e32 v180, v121, v121
	v_fmac_f32_e32 v181, v125, v125
	v_fmac_f32_e32 v182, v129, v129
	v_fmac_f32_e32 v183, v133, v133
	v_fmac_f32_e32 v180, v122, v122
	v_fmac_f32_e32 v181, v126, v126
	v_fmac_f32_e32 v182, v130, v130
	v_fmac_f32_e32 v183, v134, v134
	v_fmac_f32_e32 v180, v123, v123
	v_fmac_f32_e32 v181, v127, v127
	v_fmac_f32_e32 v182, v131, v131
	v_fmac_f32_e32 v183, v135, v135
	v_add_f32_e32 v180, v180, v181
	v_add_f32_e32 v182, v182, v183
	v_add_f32_e32 v180, v180, v182
	s_nop 1
	v_add_f32_dpp v180, v180, v180 quad_perm:[1,0,3,2] row_mask:0xf bank_mask:0xf
	s_nop 1
	v_add_f32_dpp v180, v180, v180 quad_perm:[2,3,0,1] row_mask:0xf bank_mask:0xf
	s_nop 1
	v_add_f32_dpp v180, v180, v180 row_half_mirror row_mask:0xf bank_mask:0xf
	s_nop 1
	v_add_f32_dpp v180, v180, v180 row_mirror row_mask:0xf bank_mask:0xf
	s_nop 1
	v_add_f32_dpp v180, v180, v180 row_bcast:15 row_mask:0xa bank_mask:0xf
	s_nop 1
	v_add_f32_dpp v180, v180, v180 row_bcast:31 row_mask:0xc bank_mask:0xf
	s_nop 0
	v_readlane_b32 s20, v180, 63
	s_nop 1
	v_mov_b32_e32 v185, s20
	v_fma_f32 v185, v185, v2, v4
	v_rsq_f32_e32 v185, v185
	s_nop 0
	v_mul_f32_e32 v120, v120, v185
	v_mul_f32_e32 v121, v121, v185
	v_mul_f32_e32 v122, v122, v185
	v_mul_f32_e32 v123, v123, v185
	v_mul_f32_e32 v124, v124, v185
	v_mul_f32_e32 v125, v125, v185
	v_mul_f32_e32 v126, v126, v185
	v_mul_f32_e32 v127, v127, v185
	v_mul_f32_e32 v128, v128, v185
	v_mul_f32_e32 v129, v129, v185
	v_mul_f32_e32 v130, v130, v185
	v_mul_f32_e32 v131, v131, v185
	v_mul_f32_e32 v132, v132, v185
	v_mul_f32_e32 v133, v133, v185
	v_mul_f32_e32 v134, v134, v185
	v_mul_f32_e32 v135, v135, v185
	v_fma_f32 v120, v120, v8, v24
	v_fma_f32 v121, v121, v9, v25
	v_fma_f32 v122, v122, v10, v26
	v_fma_f32 v123, v123, v11, v27
	v_fma_f32 v124, v124, v12, v28
	v_fma_f32 v125, v125, v13, v29
	v_fma_f32 v126, v126, v14, v30
	v_fma_f32 v127, v127, v15, v31
	v_fma_f32 v128, v128, v16, v32
	v_fma_f32 v129, v129, v17, v33
	v_fma_f32 v130, v130, v18, v34
	v_fma_f32 v131, v131, v19, v35
	v_fma_f32 v132, v132, v20, v36
	v_fma_f32 v133, v133, v21, v37
	v_fma_f32 v134, v134, v22, v38
	v_fma_f32 v135, v135, v23, v39
	v_cvt_pk_bf16_f32 v120, v120, v121
	v_cvt_pk_bf16_f32 v121, v122, v123
	v_cvt_pk_bf16_f32 v124, v124, v125
	v_cvt_pk_bf16_f32 v125, v126, v127
	v_cvt_pk_bf16_f32 v128, v128, v129
	v_cvt_pk_bf16_f32 v129, v130, v131
	v_cvt_pk_bf16_f32 v132, v132, v133
	v_cvt_pk_bf16_f32 v133, v134, v135
	v_add_u32_e32 v171, 0xf00000, v5
	global_store_dwordx2 v171, v[120:121], s[8:9]
	global_store_dwordx2 v171, v[124:125], s[8:9] offset:512
	global_store_dwordx2 v171, v[128:129], s[8:9] offset:1024
	global_store_dwordx2 v171, v[132:133], s[8:9] offset:1536
	v_mov_b32_e32 v172, 0xf000
	s_mov_b64 exec, 1
	global_store_dwordx2 v172, v[184:185], s[38:39]
	s_mov_b64 exec, -1
	s_waitcnt vmcnt(46)
	v_add_f32_e32 v180, v136, v137
	v_add_f32_e32 v181, v140, v141
	v_add_f32_e32 v182, v144, v145
	v_add_f32_e32 v183, v148, v149
	v_add_f32_e32 v180, v180, v138
	v_add_f32_e32 v181, v181, v142
	v_add_f32_e32 v182, v182, v146
	v_add_f32_e32 v183, v183, v150
	v_add_f32_e32 v180, v180, v139
	v_add_f32_e32 v181, v181, v143
	v_add_f32_e32 v182, v182, v147
	v_add_f32_e32 v183, v183, v151
	v_add_f32_e32 v180, v180, v181
	v_add_f32_e32 v182, v182, v183
	v_add_f32_e32 v180, v180, v182
	s_nop 1
	v_add_f32_dpp v180, v180, v180 quad_perm:[1,0,3,2] row_mask:0xf bank_mask:0xf
	s_nop 1
	v_add_f32_dpp v180, v180, v180 quad_perm:[2,3,0,1] row_mask:0xf bank_mask:0xf
	s_nop 1
	v_add_f32_dpp v180, v180, v180 row_half_mirror row_mask:0xf bank_mask:0xf
	s_nop 1
	v_add_f32_dpp v180, v180, v180 row_mirror row_mask:0xf bank_mask:0xf
	s_nop 1
	v_add_f32_dpp v180, v180, v180 row_bcast:15 row_mask:0xa bank_mask:0xf
	s_nop 1
	v_add_f32_dpp v180, v180, v180 row_bcast:31 row_mask:0xc bank_mask:0xf
	s_nop 0
	v_readlane_b32 s20, v180, 63
	s_nop 1
	v_mul_f32_e32 v184, s20, v2
	v_sub_f32_e32 v136, v136, v184
	v_sub_f32_e32 v137, v137, v184
	v_sub_f32_e32 v138, v138, v184
	v_sub_f32_e32 v139, v139, v184
	v_sub_f32_e32 v140, v140, v184
	v_sub_f32_e32 v141, v141, v184
	v_sub_f32_e32 v142, v142, v184
	v_sub_f32_e32 v143, v143, v184
	v_sub_f32_e32 v144, v144, v184
	v_sub_f32_e32 v145, v145, v184
	v_sub_f32_e32 v146, v146, v184
	v_sub_f32_e32 v147, v147, v184
	v_sub_f32_e32 v148, v148, v184
	v_sub_f32_e32 v149, v149, v184
	v_sub_f32_e32 v150, v150, v184
	v_sub_f32_e32 v151, v151, v184
	v_mul_f32_e32 v180, v136, v136
	v_mul_f32_e32 v181, v140, v140
	v_mul_f32_e32 v182, v144, v144
	v_mul_f32_e32 v183, v148, v148
	v_fmac_f32_e32 v180, v137, v137
	v_fmac_f32_e32 v181, v141, v141
	v_fmac_f32_e32 v182, v145, v145
	v_fmac_f32_e32 v183, v149, v149
	v_fmac_f32_e32 v180, v138, v138
	v_fmac_f32_e32 v181, v142, v142
	v_fmac_f32_e32 v182, v146, v146
	v_fmac_f32_e32 v183, v150, v150
	v_fmac_f32_e32 v180, v139, v139
	v_fmac_f32_e32 v181, v143, v143
	v_fmac_f32_e32 v182, v147, v147
	v_fmac_f32_e32 v183, v151, v151
	v_add_f32_e32 v180, v180, v181
	v_add_f32_e32 v182, v182, v183
	v_add_f32_e32 v180, v180, v182
	s_nop 1
	v_add_f32_dpp v180, v180, v180 quad_perm:[1,0,3,2] row_mask:0xf bank_mask:0xf
	s_nop 1
	v_add_f32_dpp v180, v180, v180 quad_perm:[2,3,0,1] row_mask:0xf bank_mask:0xf
	s_nop 1
	v_add_f32_dpp v180, v180, v180 row_half_mirror row_mask:0xf bank_mask:0xf
	s_nop 1
	v_add_f32_dpp v180, v180, v180 row_mirror row_mask:0xf bank_mask:0xf
	s_nop 1
	v_add_f32_dpp v180, v180, v180 row_bcast:15 row_mask:0xa bank_mask:0xf
	s_nop 1
	v_add_f32_dpp v180, v180, v180 row_bcast:31 row_mask:0xc bank_mask:0xf
	s_nop 0
	v_readlane_b32 s20, v180, 63
	s_nop 1
	v_mov_b32_e32 v185, s20
	v_fma_f32 v185, v185, v2, v4
	v_rsq_f32_e32 v185, v185
	s_nop 0
	v_mul_f32_e32 v136, v136, v185
	v_mul_f32_e32 v137, v137, v185
	v_mul_f32_e32 v138, v138, v185
	v_mul_f32_e32 v139, v139, v185
	v_mul_f32_e32 v140, v140, v185
	v_mul_f32_e32 v141, v141, v185
	v_mul_f32_e32 v142, v142, v185
	v_mul_f32_e32 v143, v143, v185
	v_mul_f32_e32 v144, v144, v185
	v_mul_f32_e32 v145, v145, v185
	v_mul_f32_e32 v146, v146, v185
	v_mul_f32_e32 v147, v147, v185
	v_mul_f32_e32 v148, v148, v185
	v_mul_f32_e32 v149, v149, v185
	v_mul_f32_e32 v150, v150, v185
	v_mul_f32_e32 v151, v151, v185
	v_fma_f32 v136, v136, v8, v24
	v_fma_f32 v137, v137, v9, v25
	v_fma_f32 v138, v138, v10, v26
	v_fma_f32 v139, v139, v11, v27
	v_fma_f32 v140, v140, v12, v28
	v_fma_f32 v141, v141, v13, v29
	v_fma_f32 v142, v142, v14, v30
	v_fma_f32 v143, v143, v15, v31
	v_fma_f32 v144, v144, v16, v32
	v_fma_f32 v145, v145, v17, v33
	v_fma_f32 v146, v146, v18, v34
	v_fma_f32 v147, v147, v19, v35
	v_fma_f32 v148, v148, v20, v36
	v_fma_f32 v149, v149, v21, v37
	v_fma_f32 v150, v150, v22, v38
	v_fma_f32 v151, v151, v23, v39
	v_cvt_pk_bf16_f32 v136, v136, v137
	v_cvt_pk_bf16_f32 v137, v138, v139
	v_cvt_pk_bf16_f32 v140, v140, v141
	v_cvt_pk_bf16_f32 v141, v142, v143
	v_cvt_pk_bf16_f32 v144, v144, v145
	v_cvt_pk_bf16_f32 v145, v146, v147
	v_cvt_pk_bf16_f32 v148, v148, v149
	v_cvt_pk_bf16_f32 v149, v150, v151
	v_add_u32_e32 v171, 0x1200000, v5
	global_store_dwordx2 v171, v[136:137], s[8:9]
	global_store_dwordx2 v171, v[140:141], s[8:9] offset:512
	global_store_dwordx2 v171, v[144:145], s[8:9] offset:1024
	global_store_dwordx2 v171, v[148:149], s[8:9] offset:1536
	v_mov_b32_e32 v172, 0x12000
	s_mov_b64 exec, 1
	global_store_dwordx2 v172, v[184:185], s[38:39]
	s_mov_b64 exec, -1
	s_waitcnt vmcnt(47)
	v_add_f32_e32 v180, v152, v153
	v_add_f32_e32 v181, v156, v157
	v_add_f32_e32 v182, v160, v161
	v_add_f32_e32 v183, v164, v165
	v_add_f32_e32 v180, v180, v154
	v_add_f32_e32 v181, v181, v158
	v_add_f32_e32 v182, v182, v162
	v_add_f32_e32 v183, v183, v166
	v_add_f32_e32 v180, v180, v155
	v_add_f32_e32 v181, v181, v159
	v_add_f32_e32 v182, v182, v163
	v_add_f32_e32 v183, v183, v167
	v_add_f32_e32 v180, v180, v181
	v_add_f32_e32 v182, v182, v183
	v_add_f32_e32 v180, v180, v182
	s_nop 1
	v_add_f32_dpp v180, v180, v180 quad_perm:[1,0,3,2] row_mask:0xf bank_mask:0xf
	s_nop 1
	v_add_f32_dpp v180, v180, v180 quad_perm:[2,3,0,1] row_mask:0xf bank_mask:0xf
	s_nop 1
	v_add_f32_dpp v180, v180, v180 row_half_mirror row_mask:0xf bank_mask:0xf
	s_nop 1
	v_add_f32_dpp v180, v180, v180 row_mirror row_mask:0xf bank_mask:0xf
	s_nop 1
	v_add_f32_dpp v180, v180, v180 row_bcast:15 row_mask:0xa bank_mask:0xf
	s_nop 1
	v_add_f32_dpp v180, v180, v180 row_bcast:31 row_mask:0xc bank_mask:0xf
	s_nop 0
	v_readlane_b32 s20, v180, 63
	s_nop 1
	v_mul_f32_e32 v184, s20, v2
	v_sub_f32_e32 v152, v152, v184
	v_sub_f32_e32 v153, v153, v184
	v_sub_f32_e32 v154, v154, v184
	v_sub_f32_e32 v155, v155, v184
	v_sub_f32_e32 v156, v156, v184
	v_sub_f32_e32 v157, v157, v184
	v_sub_f32_e32 v158, v158, v184
	v_sub_f32_e32 v159, v159, v184
	v_sub_f32_e32 v160, v160, v184
	v_sub_f32_e32 v161, v161, v184
	v_sub_f32_e32 v162, v162, v184
	v_sub_f32_e32 v163, v163, v184
	v_sub_f32_e32 v164, v164, v184
	v_sub_f32_e32 v165, v165, v184
	v_sub_f32_e32 v166, v166, v184
	v_sub_f32_e32 v167, v167, v184
	v_mul_f32_e32 v180, v152, v152
	v_mul_f32_e32 v181, v156, v156
	v_mul_f32_e32 v182, v160, v160
	v_mul_f32_e32 v183, v164, v164
	v_fmac_f32_e32 v180, v153, v153
	v_fmac_f32_e32 v181, v157, v157
	v_fmac_f32_e32 v182, v161, v161
	v_fmac_f32_e32 v183, v165, v165
	v_fmac_f32_e32 v180, v154, v154
	v_fmac_f32_e32 v181, v158, v158
	v_fmac_f32_e32 v182, v162, v162
	v_fmac_f32_e32 v183, v166, v166
	v_fmac_f32_e32 v180, v155, v155
	v_fmac_f32_e32 v181, v159, v159
	v_fmac_f32_e32 v182, v163, v163
	v_fmac_f32_e32 v183, v167, v167
	v_add_f32_e32 v180, v180, v181
	v_add_f32_e32 v182, v182, v183
	v_add_f32_e32 v180, v180, v182
	s_nop 1
	v_add_f32_dpp v180, v180, v180 quad_perm:[1,0,3,2] row_mask:0xf bank_mask:0xf
	s_nop 1
	v_add_f32_dpp v180, v180, v180 quad_perm:[2,3,0,1] row_mask:0xf bank_mask:0xf
	s_nop 1
	v_add_f32_dpp v180, v180, v180 row_half_mirror row_mask:0xf bank_mask:0xf
	s_nop 1
	v_add_f32_dpp v180, v180, v180 row_mirror row_mask:0xf bank_mask:0xf
	s_nop 1
	v_add_f32_dpp v180, v180, v180 row_bcast:15 row_mask:0xa bank_mask:0xf
	s_nop 1
	v_add_f32_dpp v180, v180, v180 row_bcast:31 row_mask:0xc bank_mask:0xf
	s_nop 0
	v_readlane_b32 s20, v180, 63
	s_nop 1
	v_mov_b32_e32 v185, s20
	v_fma_f32 v185, v185, v2, v4
	v_rsq_f32_e32 v185, v185
	s_nop 0
	v_mul_f32_e32 v152, v152, v185
	v_mul_f32_e32 v153, v153, v185
	v_mul_f32_e32 v154, v154, v185
	v_mul_f32_e32 v155, v155, v185
	v_mul_f32_e32 v156, v156, v185
	v_mul_f32_e32 v157, v157, v185
	v_mul_f32_e32 v158, v158, v185
	v_mul_f32_e32 v159, v159, v185
	v_mul_f32_e32 v160, v160, v185
	v_mul_f32_e32 v161, v161, v185
	v_mul_f32_e32 v162, v162, v185
	v_mul_f32_e32 v163, v163, v185
	v_mul_f32_e32 v164, v164, v185
	v_mul_f32_e32 v165, v165, v185
	v_mul_f32_e32 v166, v166, v185
	v_mul_f32_e32 v167, v167, v185
	v_fma_f32 v152, v152, v8, v24
	v_fma_f32 v153, v153, v9, v25
	v_fma_f32 v154, v154, v10, v26
	v_fma_f32 v155, v155, v11, v27
	v_fma_f32 v156, v156, v12, v28
	v_fma_f32 v157, v157, v13, v29
	v_fma_f32 v158, v158, v14, v30
	v_fma_f32 v159, v159, v15, v31
	v_fma_f32 v160, v160, v16, v32
	v_fma_f32 v161, v161, v17, v33
	v_fma_f32 v162, v162, v18, v34
	v_fma_f32 v163, v163, v19, v35
	v_fma_f32 v164, v164, v20, v36
	v_fma_f32 v165, v165, v21, v37
	v_fma_f32 v166, v166, v22, v38
	v_fma_f32 v167, v167, v23, v39
	v_cvt_pk_bf16_f32 v152, v152, v153
	v_cvt_pk_bf16_f32 v153, v154, v155
	v_cvt_pk_bf16_f32 v156, v156, v157
	v_cvt_pk_bf16_f32 v157, v158, v159
	v_cvt_pk_bf16_f32 v160, v160, v161
	v_cvt_pk_bf16_f32 v161, v162, v163
	v_cvt_pk_bf16_f32 v164, v164, v165
	v_cvt_pk_bf16_f32 v165, v166, v167
	v_add_u32_e32 v171, 0x1500000, v5
	global_store_dwordx2 v171, v[152:153], s[8:9]
	global_store_dwordx2 v171, v[156:157], s[8:9] offset:512
	global_store_dwordx2 v171, v[160:161], s[8:9] offset:1024
	global_store_dwordx2 v171, v[164:165], s[8:9] offset:1536
	v_mov_b32_e32 v172, 0x15000
	s_mov_b64 exec, 1
	global_store_dwordx2 v172, v[184:185], s[38:39]
	s_mov_b64 exec, -1
	s_waitcnt vmcnt(43)
	v_add_f32_e32 v180, v40, v41
	v_add_f32_e32 v181, v44, v45
	v_add_f32_e32 v182, v48, v49
	v_add_f32_e32 v183, v52, v53
	v_add_f32_e32 v180, v180, v42
	v_add_f32_e32 v181, v181, v46
	v_add_f32_e32 v182, v182, v50
	v_add_f32_e32 v183, v183, v54
	v_add_f32_e32 v180, v180, v43
	v_add_f32_e32 v181, v181, v47
	v_add_f32_e32 v182, v182, v51
	v_add_f32_e32 v183, v183, v55
	v_add_f32_e32 v180, v180, v181
	v_add_f32_e32 v182, v182, v183
	v_add_f32_e32 v180, v180, v182
	s_nop 1
	v_add_f32_dpp v180, v180, v180 quad_perm:[1,0,3,2] row_mask:0xf bank_mask:0xf
	s_nop 1
	v_add_f32_dpp v180, v180, v180 quad_perm:[2,3,0,1] row_mask:0xf bank_mask:0xf
	s_nop 1
	v_add_f32_dpp v180, v180, v180 row_half_mirror row_mask:0xf bank_mask:0xf
	s_nop 1
	v_add_f32_dpp v180, v180, v180 row_mirror row_mask:0xf bank_mask:0xf
	s_nop 1
	v_add_f32_dpp v180, v180, v180 row_bcast:15 row_mask:0xa bank_mask:0xf
	s_nop 1
	v_add_f32_dpp v180, v180, v180 row_bcast:31 row_mask:0xc bank_mask:0xf
	s_nop 0
	v_readlane_b32 s20, v180, 63
	s_nop 1
	v_mul_f32_e32 v184, s20, v2
	v_sub_f32_e32 v40, v40, v184
	v_sub_f32_e32 v41, v41, v184
	v_sub_f32_e32 v42, v42, v184
	v_sub_f32_e32 v43, v43, v184
	v_sub_f32_e32 v44, v44, v184
	v_sub_f32_e32 v45, v45, v184
	v_sub_f32_e32 v46, v46, v184
	v_sub_f32_e32 v47, v47, v184
	v_sub_f32_e32 v48, v48, v184
	v_sub_f32_e32 v49, v49, v184
	v_sub_f32_e32 v50, v50, v184
	v_sub_f32_e32 v51, v51, v184
	v_sub_f32_e32 v52, v52, v184
	v_sub_f32_e32 v53, v53, v184
	v_sub_f32_e32 v54, v54, v184
	v_sub_f32_e32 v55, v55, v184
	v_mul_f32_e32 v180, v40, v40
	v_mul_f32_e32 v181, v44, v44
	v_mul_f32_e32 v182, v48, v48
	v_mul_f32_e32 v183, v52, v52
	v_fmac_f32_e32 v180, v41, v41
	v_fmac_f32_e32 v181, v45, v45
	v_fmac_f32_e32 v182, v49, v49
	v_fmac_f32_e32 v183, v53, v53
	v_fmac_f32_e32 v180, v42, v42
	v_fmac_f32_e32 v181, v46, v46
	v_fmac_f32_e32 v182, v50, v50
	v_fmac_f32_e32 v183, v54, v54
	v_fmac_f32_e32 v180, v43, v43
	v_fmac_f32_e32 v181, v47, v47
	v_fmac_f32_e32 v182, v51, v51
	v_fmac_f32_e32 v183, v55, v55
	v_add_f32_e32 v180, v180, v181
	v_add_f32_e32 v182, v182, v183
	v_add_f32_e32 v180, v180, v182
	s_nop 1
	v_add_f32_dpp v180, v180, v180 quad_perm:[1,0,3,2] row_mask:0xf bank_mask:0xf
	s_nop 1
	v_add_f32_dpp v180, v180, v180 quad_perm:[2,3,0,1] row_mask:0xf bank_mask:0xf
	s_nop 1
	v_add_f32_dpp v180, v180, v180 row_half_mirror row_mask:0xf bank_mask:0xf
	s_nop 1
	v_add_f32_dpp v180, v180, v180 row_mirror row_mask:0xf bank_mask:0xf
	s_nop 1
	v_add_f32_dpp v180, v180, v180 row_bcast:15 row_mask:0xa bank_mask:0xf
	s_nop 1
	v_add_f32_dpp v180, v180, v180 row_bcast:31 row_mask:0xc bank_mask:0xf
	s_nop 0
	v_readlane_b32 s20, v180, 63
	s_nop 1
	v_mov_b32_e32 v185, s20
	v_fma_f32 v185, v185, v2, v4
	v_rsq_f32_e32 v185, v185
	s_nop 0
	v_mul_f32_e32 v40, v40, v185
	v_mul_f32_e32 v41, v41, v185
	v_mul_f32_e32 v42, v42, v185
	v_mul_f32_e32 v43, v43, v185
	v_mul_f32_e32 v44, v44, v185
	v_mul_f32_e32 v45, v45, v185
	v_mul_f32_e32 v46, v46, v185
	v_mul_f32_e32 v47, v47, v185
	v_mul_f32_e32 v48, v48, v185
	v_mul_f32_e32 v49, v49, v185
	v_mul_f32_e32 v50, v50, v185
	v_mul_f32_e32 v51, v51, v185
	v_mul_f32_e32 v52, v52, v185
	v_mul_f32_e32 v53, v53, v185
	v_mul_f32_e32 v54, v54, v185
	v_mul_f32_e32 v55, v55, v185
	v_fma_f32 v40, v40, v8, v24
	v_fma_f32 v41, v41, v9, v25
	v_fma_f32 v42, v42, v10, v26
	v_fma_f32 v43, v43, v11, v27
	v_fma_f32 v44, v44, v12, v28
	v_fma_f32 v45, v45, v13, v29
	v_fma_f32 v46, v46, v14, v30
	v_fma_f32 v47, v47, v15, v31
	v_fma_f32 v48, v48, v16, v32
	v_fma_f32 v49, v49, v17, v33
	v_fma_f32 v50, v50, v18, v34
	v_fma_f32 v51, v51, v19, v35
	v_fma_f32 v52, v52, v20, v36
	v_fma_f32 v53, v53, v21, v37
	v_fma_f32 v54, v54, v22, v38
	v_fma_f32 v55, v55, v23, v39
	v_cvt_pk_bf16_f32 v40, v40, v41
	v_cvt_pk_bf16_f32 v41, v42, v43
	v_cvt_pk_bf16_f32 v44, v44, v45
	v_cvt_pk_bf16_f32 v45, v46, v47
	v_cvt_pk_bf16_f32 v48, v48, v49
	v_cvt_pk_bf16_f32 v49, v50, v51
	v_cvt_pk_bf16_f32 v52, v52, v53
	v_cvt_pk_bf16_f32 v53, v54, v55
	v_add_u32_e32 v171, 0x1800000, v5
	global_store_dwordx2 v171, v[40:41], s[8:9]
	global_store_dwordx2 v171, v[44:45], s[8:9] offset:512
	global_store_dwordx2 v171, v[48:49], s[8:9] offset:1024
	global_store_dwordx2 v171, v[52:53], s[8:9] offset:1536
	v_mov_b32_e32 v172, 0x18000
	s_mov_b64 exec, 1
	global_store_dwordx2 v172, v[184:185], s[38:39]
	s_mov_b64 exec, -1
	s_waitcnt vmcnt(39)
	v_add_f32_e32 v180, v56, v57
	v_add_f32_e32 v181, v60, v61
	v_add_f32_e32 v182, v64, v65
	v_add_f32_e32 v183, v68, v69
	v_add_f32_e32 v180, v180, v58
	v_add_f32_e32 v181, v181, v62
	v_add_f32_e32 v182, v182, v66
	v_add_f32_e32 v183, v183, v70
	v_add_f32_e32 v180, v180, v59
	v_add_f32_e32 v181, v181, v63
	v_add_f32_e32 v182, v182, v67
	v_add_f32_e32 v183, v183, v71
	v_add_f32_e32 v180, v180, v181
	v_add_f32_e32 v182, v182, v183
	v_add_f32_e32 v180, v180, v182
	s_nop 1
	v_add_f32_dpp v180, v180, v180 quad_perm:[1,0,3,2] row_mask:0xf bank_mask:0xf
	s_nop 1
	v_add_f32_dpp v180, v180, v180 quad_perm:[2,3,0,1] row_mask:0xf bank_mask:0xf
	s_nop 1
	v_add_f32_dpp v180, v180, v180 row_half_mirror row_mask:0xf bank_mask:0xf
	s_nop 1
	v_add_f32_dpp v180, v180, v180 row_mirror row_mask:0xf bank_mask:0xf
	s_nop 1
	v_add_f32_dpp v180, v180, v180 row_bcast:15 row_mask:0xa bank_mask:0xf
	s_nop 1
	v_add_f32_dpp v180, v180, v180 row_bcast:31 row_mask:0xc bank_mask:0xf
	s_nop 0
	v_readlane_b32 s20, v180, 63
	s_nop 1
	v_mul_f32_e32 v184, s20, v2
	v_sub_f32_e32 v56, v56, v184
	v_sub_f32_e32 v57, v57, v184
	v_sub_f32_e32 v58, v58, v184
	v_sub_f32_e32 v59, v59, v184
	v_sub_f32_e32 v60, v60, v184
	v_sub_f32_e32 v61, v61, v184
	v_sub_f32_e32 v62, v62, v184
	v_sub_f32_e32 v63, v63, v184
	v_sub_f32_e32 v64, v64, v184
	v_sub_f32_e32 v65, v65, v184
	v_sub_f32_e32 v66, v66, v184
	v_sub_f32_e32 v67, v67, v184
	v_sub_f32_e32 v68, v68, v184
	v_sub_f32_e32 v69, v69, v184
	v_sub_f32_e32 v70, v70, v184
	v_sub_f32_e32 v71, v71, v184
	v_mul_f32_e32 v180, v56, v56
	v_mul_f32_e32 v181, v60, v60
	v_mul_f32_e32 v182, v64, v64
	v_mul_f32_e32 v183, v68, v68
	v_fmac_f32_e32 v180, v57, v57
	v_fmac_f32_e32 v181, v61, v61
	v_fmac_f32_e32 v182, v65, v65
	v_fmac_f32_e32 v183, v69, v69
	v_fmac_f32_e32 v180, v58, v58
	v_fmac_f32_e32 v181, v62, v62
	v_fmac_f32_e32 v182, v66, v66
	v_fmac_f32_e32 v183, v70, v70
	v_fmac_f32_e32 v180, v59, v59
	v_fmac_f32_e32 v181, v63, v63
	v_fmac_f32_e32 v182, v67, v67
	v_fmac_f32_e32 v183, v71, v71
	v_add_f32_e32 v180, v180, v181
	v_add_f32_e32 v182, v182, v183
	v_add_f32_e32 v180, v180, v182
	s_nop 1
	v_add_f32_dpp v180, v180, v180 quad_perm:[1,0,3,2] row_mask:0xf bank_mask:0xf
	s_nop 1
	v_add_f32_dpp v180, v180, v180 quad_perm:[2,3,0,1] row_mask:0xf bank_mask:0xf
	s_nop 1
	v_add_f32_dpp v180, v180, v180 row_half_mirror row_mask:0xf bank_mask:0xf
	s_nop 1
	v_add_f32_dpp v180, v180, v180 row_mirror row_mask:0xf bank_mask:0xf
	s_nop 1
	v_add_f32_dpp v180, v180, v180 row_bcast:15 row_mask:0xa bank_mask:0xf
	s_nop 1
	v_add_f32_dpp v180, v180, v180 row_bcast:31 row_mask:0xc bank_mask:0xf
	s_nop 0
	v_readlane_b32 s20, v180, 63
	s_nop 1
	v_mov_b32_e32 v185, s20
	v_fma_f32 v185, v185, v2, v4
	v_rsq_f32_e32 v185, v185
	s_nop 0
	v_mul_f32_e32 v56, v56, v185
	v_mul_f32_e32 v57, v57, v185
	v_mul_f32_e32 v58, v58, v185
	v_mul_f32_e32 v59, v59, v185
	v_mul_f32_e32 v60, v60, v185
	v_mul_f32_e32 v61, v61, v185
	v_mul_f32_e32 v62, v62, v185
	v_mul_f32_e32 v63, v63, v185
	v_mul_f32_e32 v64, v64, v185
	v_mul_f32_e32 v65, v65, v185
	v_mul_f32_e32 v66, v66, v185
	v_mul_f32_e32 v67, v67, v185
	v_mul_f32_e32 v68, v68, v185
	v_mul_f32_e32 v69, v69, v185
	v_mul_f32_e32 v70, v70, v185
	v_mul_f32_e32 v71, v71, v185
	v_fma_f32 v56, v56, v8, v24
	v_fma_f32 v57, v57, v9, v25
	v_fma_f32 v58, v58, v10, v26
	v_fma_f32 v59, v59, v11, v27
	v_fma_f32 v60, v60, v12, v28
	v_fma_f32 v61, v61, v13, v29
	v_fma_f32 v62, v62, v14, v30
	v_fma_f32 v63, v63, v15, v31
	v_fma_f32 v64, v64, v16, v32
	v_fma_f32 v65, v65, v17, v33
	v_fma_f32 v66, v66, v18, v34
	v_fma_f32 v67, v67, v19, v35
	v_fma_f32 v68, v68, v20, v36
	v_fma_f32 v69, v69, v21, v37
	v_fma_f32 v70, v70, v22, v38
	v_fma_f32 v71, v71, v23, v39
	v_cvt_pk_bf16_f32 v56, v56, v57
	v_cvt_pk_bf16_f32 v57, v58, v59
	v_cvt_pk_bf16_f32 v60, v60, v61
	v_cvt_pk_bf16_f32 v61, v62, v63
	v_cvt_pk_bf16_f32 v64, v64, v65
	v_cvt_pk_bf16_f32 v65, v66, v67
	v_cvt_pk_bf16_f32 v68, v68, v69
	v_cvt_pk_bf16_f32 v69, v70, v71
	v_add_u32_e32 v171, 0x1b00000, v5
	global_store_dwordx2 v171, v[56:57], s[8:9]
	global_store_dwordx2 v171, v[60:61], s[8:9] offset:512
	global_store_dwordx2 v171, v[64:65], s[8:9] offset:1024
	global_store_dwordx2 v171, v[68:69], s[8:9] offset:1536
	v_mov_b32_e32 v172, 0x1b000
	s_mov_b64 exec, 1
	global_store_dwordx2 v172, v[184:185], s[38:39]
	s_mov_b64 exec, -1
	s_waitcnt vmcnt(35)
	v_add_f32_e32 v180, v72, v73
	v_add_f32_e32 v181, v76, v77
	v_add_f32_e32 v182, v80, v81
	v_add_f32_e32 v183, v84, v85
	v_add_f32_e32 v180, v180, v74
	v_add_f32_e32 v181, v181, v78
	v_add_f32_e32 v182, v182, v82
	v_add_f32_e32 v183, v183, v86
	v_add_f32_e32 v180, v180, v75
	v_add_f32_e32 v181, v181, v79
	v_add_f32_e32 v182, v182, v83
	v_add_f32_e32 v183, v183, v87
	v_add_f32_e32 v180, v180, v181
	v_add_f32_e32 v182, v182, v183
	v_add_f32_e32 v180, v180, v182
	s_nop 1
	v_add_f32_dpp v180, v180, v180 quad_perm:[1,0,3,2] row_mask:0xf bank_mask:0xf
	s_nop 1
	v_add_f32_dpp v180, v180, v180 quad_perm:[2,3,0,1] row_mask:0xf bank_mask:0xf
	s_nop 1
	v_add_f32_dpp v180, v180, v180 row_half_mirror row_mask:0xf bank_mask:0xf
	s_nop 1
	v_add_f32_dpp v180, v180, v180 row_mirror row_mask:0xf bank_mask:0xf
	s_nop 1
	v_add_f32_dpp v180, v180, v180 row_bcast:15 row_mask:0xa bank_mask:0xf
	s_nop 1
	v_add_f32_dpp v180, v180, v180 row_bcast:31 row_mask:0xc bank_mask:0xf
	s_nop 0
	v_readlane_b32 s20, v180, 63
	s_nop 1
	v_mul_f32_e32 v184, s20, v2
	v_sub_f32_e32 v72, v72, v184
	v_sub_f32_e32 v73, v73, v184
	v_sub_f32_e32 v74, v74, v184
	v_sub_f32_e32 v75, v75, v184
	v_sub_f32_e32 v76, v76, v184
	v_sub_f32_e32 v77, v77, v184
	v_sub_f32_e32 v78, v78, v184
	v_sub_f32_e32 v79, v79, v184
	v_sub_f32_e32 v80, v80, v184
	v_sub_f32_e32 v81, v81, v184
	v_sub_f32_e32 v82, v82, v184
	v_sub_f32_e32 v83, v83, v184
	v_sub_f32_e32 v84, v84, v184
	v_sub_f32_e32 v85, v85, v184
	v_sub_f32_e32 v86, v86, v184
	v_sub_f32_e32 v87, v87, v184
	v_mul_f32_e32 v180, v72, v72
	v_mul_f32_e32 v181, v76, v76
	v_mul_f32_e32 v182, v80, v80
	v_mul_f32_e32 v183, v84, v84
	v_fmac_f32_e32 v180, v73, v73
	v_fmac_f32_e32 v181, v77, v77
	v_fmac_f32_e32 v182, v81, v81
	v_fmac_f32_e32 v183, v85, v85
	v_fmac_f32_e32 v180, v74, v74
	v_fmac_f32_e32 v181, v78, v78
	v_fmac_f32_e32 v182, v82, v82
	v_fmac_f32_e32 v183, v86, v86
	v_fmac_f32_e32 v180, v75, v75
	v_fmac_f32_e32 v181, v79, v79
	v_fmac_f32_e32 v182, v83, v83
	v_fmac_f32_e32 v183, v87, v87
	v_add_f32_e32 v180, v180, v181
	v_add_f32_e32 v182, v182, v183
	v_add_f32_e32 v180, v180, v182
	s_nop 1
	v_add_f32_dpp v180, v180, v180 quad_perm:[1,0,3,2] row_mask:0xf bank_mask:0xf
	s_nop 1
	v_add_f32_dpp v180, v180, v180 quad_perm:[2,3,0,1] row_mask:0xf bank_mask:0xf
	s_nop 1
	v_add_f32_dpp v180, v180, v180 row_half_mirror row_mask:0xf bank_mask:0xf
	s_nop 1
	v_add_f32_dpp v180, v180, v180 row_mirror row_mask:0xf bank_mask:0xf
	s_nop 1
	v_add_f32_dpp v180, v180, v180 row_bcast:15 row_mask:0xa bank_mask:0xf
	s_nop 1
	v_add_f32_dpp v180, v180, v180 row_bcast:31 row_mask:0xc bank_mask:0xf
	s_nop 0
	v_readlane_b32 s20, v180, 63
	s_nop 1
	v_mov_b32_e32 v185, s20
	v_fma_f32 v185, v185, v2, v4
	v_rsq_f32_e32 v185, v185
	s_nop 0
	v_mul_f32_e32 v72, v72, v185
	v_mul_f32_e32 v73, v73, v185
	v_mul_f32_e32 v74, v74, v185
	v_mul_f32_e32 v75, v75, v185
	v_mul_f32_e32 v76, v76, v185
	v_mul_f32_e32 v77, v77, v185
	v_mul_f32_e32 v78, v78, v185
	v_mul_f32_e32 v79, v79, v185
	v_mul_f32_e32 v80, v80, v185
	v_mul_f32_e32 v81, v81, v185
	v_mul_f32_e32 v82, v82, v185
	v_mul_f32_e32 v83, v83, v185
	v_mul_f32_e32 v84, v84, v185
	v_mul_f32_e32 v85, v85, v185
	v_mul_f32_e32 v86, v86, v185
	v_mul_f32_e32 v87, v87, v185
	v_fma_f32 v72, v72, v8, v24
	v_fma_f32 v73, v73, v9, v25
	v_fma_f32 v74, v74, v10, v26
	v_fma_f32 v75, v75, v11, v27
	v_fma_f32 v76, v76, v12, v28
	v_fma_f32 v77, v77, v13, v29
	v_fma_f32 v78, v78, v14, v30
	v_fma_f32 v79, v79, v15, v31
	v_fma_f32 v80, v80, v16, v32
	v_fma_f32 v81, v81, v17, v33
	v_fma_f32 v82, v82, v18, v34
	v_fma_f32 v83, v83, v19, v35
	v_fma_f32 v84, v84, v20, v36
	v_fma_f32 v85, v85, v21, v37
	v_fma_f32 v86, v86, v22, v38
	v_fma_f32 v87, v87, v23, v39
	v_cvt_pk_bf16_f32 v72, v72, v73
	v_cvt_pk_bf16_f32 v73, v74, v75
	v_cvt_pk_bf16_f32 v76, v76, v77
	v_cvt_pk_bf16_f32 v77, v78, v79
	v_cvt_pk_bf16_f32 v80, v80, v81
	v_cvt_pk_bf16_f32 v81, v82, v83
	v_cvt_pk_bf16_f32 v84, v84, v85
	v_cvt_pk_bf16_f32 v85, v86, v87
	v_add_u32_e32 v171, 0x1e00000, v5
	global_store_dwordx2 v171, v[72:73], s[8:9]
	global_store_dwordx2 v171, v[76:77], s[8:9] offset:512
	global_store_dwordx2 v171, v[80:81], s[8:9] offset:1024
	global_store_dwordx2 v171, v[84:85], s[8:9] offset:1536
	v_mov_b32_e32 v172, 0x1e000
	s_mov_b64 exec, 1
	global_store_dwordx2 v172, v[184:185], s[38:39]
	s_mov_b64 exec, -1
	s_branch .LBB0_188
.Lln_r10:
	global_load_dwordx4 v[40:43], v1, s[4:5]
	global_load_dwordx4 v[44:47], v1, s[4:5] offset:1024
	global_load_dwordx4 v[48:51], v1, s[4:5] offset:2048
	global_load_dwordx4 v[52:55], v1, s[4:5] offset:3072
	global_load_dwordx4 v[8:11], v1, s[40:41]
	global_load_dwordx4 v[12:15], v1, s[40:41] offset:1024
	global_load_dwordx4 v[16:19], v1, s[40:41] offset:2048
	global_load_dwordx4 v[20:23], v1, s[40:41] offset:3072
	global_load_dwordx4 v[24:27], v1, s[42:43]
	global_load_dwordx4 v[28:31], v1, s[42:43] offset:1024
	global_load_dwordx4 v[32:35], v1, s[42:43] offset:2048
	global_load_dwordx4 v[36:39], v1, s[42:43] offset:3072
	v_add_u32_e32 v170, 0x600000, v1
	global_load_dwordx4 v[56:59], v170, s[4:5]
	global_load_dwordx4 v[60:63], v170, s[4:5] offset:1024
	global_load_dwordx4 v[64:67], v170, s[4:5] offset:2048
	global_load_dwordx4 v[68:71], v170, s[4:5] offset:3072
	v_add_u32_e32 v170, 0xc00000, v1
	global_load_dwordx4 v[72:75], v170, s[4:5]
	global_load_dwordx4 v[76:79], v170, s[4:5] offset:1024
	global_load_dwordx4 v[80:83], v170, s[4:5] offset:2048
	global_load_dwordx4 v[84:87], v170, s[4:5] offset:3072
	v_add_u32_e32 v170, 0x1200000, v1
	global_load_dwordx4 v[88:91], v170, s[4:5]
	global_load_dwordx4 v[92:95], v170, s[4:5] offset:1024
	global_load_dwordx4 v[96:99], v170, s[4:5] offset:2048
	global_load_dwordx4 v[100:103], v170, s[4:5] offset:3072
	v_add_u32_e32 v170, 0x1800000, v1
	global_load_dwordx4 v[104:107], v170, s[4:5]
	global_load_dwordx4 v[108:111], v170, s[4:5] offset:1024
	global_load_dwordx4 v[112:115], v170, s[4:5] offset:2048
	global_load_dwordx4 v[116:119], v170, s[4:5] offset:3072
	v_add_u32_e32 v170, 0x1e00000, v1
	global_load_dwordx4 v[120:123], v170, s[4:5]
	global_load_dwordx4 v[124:127], v170, s[4:5] offset:1024
	global_load_dwordx4 v[128:131], v170, s[4:5] offset:2048
	global_load_dwordx4 v[132:135], v170, s[4:5] offset:3072
	v_add_u32_e32 v170, 0x2400000, v1
	global_load_dwordx4 v[136:139], v170, s[4:5]
	global_load_dwordx4 v[140:143], v170, s[4:5] offset:1024
	global_load_dwordx4 v[144:147], v170, s[4:5] offset:2048
	global_load_dwordx4 v[148:151], v170, s[4:5] offset:3072
	v_add_u32_e32 v170, 0x2a00000, v1
	global_load_dwordx4 v[152:155], v170, s[4:5]
	global_load_dwordx4 v[156:159], v170, s[4:5] offset:1024
	global_load_dwordx4 v[160:163], v170, s[4:5] offset:2048
	global_load_dwordx4 v[164:167], v170, s[4:5] offset:3072
	s_waitcnt vmcnt(36)
	v_add_f32_e32 v180, v40, v41
	v_add_f32_e32 v181, v44, v45
	v_add_f32_e32 v182, v48, v49
	v_add_f32_e32 v183, v52, v53
	v_add_f32_e32 v180, v180, v42
	v_add_f32_e32 v181, v181, v46
	v_add_f32_e32 v182, v182, v50
	v_add_f32_e32 v183, v183, v54
	v_add_f32_e32 v180, v180, v43
	v_add_f32_e32 v181, v181, v47
	v_add_f32_e32 v182, v182, v51
	v_add_f32_e32 v183, v183, v55
	v_add_f32_e32 v180, v180, v181
	v_add_f32_e32 v182, v182, v183
	v_add_f32_e32 v180, v180, v182
	s_nop 1
	v_add_f32_dpp v180, v180, v180 quad_perm:[1,0,3,2] row_mask:0xf bank_mask:0xf
	s_nop 1
	v_add_f32_dpp v180, v180, v180 quad_perm:[2,3,0,1] row_mask:0xf bank_mask:0xf
	s_nop 1
	v_add_f32_dpp v180, v180, v180 row_half_mirror row_mask:0xf bank_mask:0xf
	s_nop 1
	v_add_f32_dpp v180, v180, v180 row_mirror row_mask:0xf bank_mask:0xf
	s_nop 1
	v_add_f32_dpp v180, v180, v180 row_bcast:15 row_mask:0xa bank_mask:0xf
	s_nop 1
	v_add_f32_dpp v180, v180, v180 row_bcast:31 row_mask:0xc bank_mask:0xf
	s_nop 0
	v_readlane_b32 s20, v180, 63
	s_nop 1
	v_mul_f32_e32 v184, s20, v2
	v_sub_f32_e32 v40, v40, v184
	v_sub_f32_e32 v41, v41, v184
	v_sub_f32_e32 v42, v42, v184
	v_sub_f32_e32 v43, v43, v184
	v_sub_f32_e32 v44, v44, v184
	v_sub_f32_e32 v45, v45, v184
	v_sub_f32_e32 v46, v46, v184
	v_sub_f32_e32 v47, v47, v184
	v_sub_f32_e32 v48, v48, v184
	v_sub_f32_e32 v49, v49, v184
	v_sub_f32_e32 v50, v50, v184
	v_sub_f32_e32 v51, v51, v184
	v_sub_f32_e32 v52, v52, v184
	v_sub_f32_e32 v53, v53, v184
	v_sub_f32_e32 v54, v54, v184
	v_sub_f32_e32 v55, v55, v184
	v_mul_f32_e32 v180, v40, v40
	v_mul_f32_e32 v181, v44, v44
	v_mul_f32_e32 v182, v48, v48
	v_mul_f32_e32 v183, v52, v52
	v_fmac_f32_e32 v180, v41, v41
	v_fmac_f32_e32 v181, v45, v45
	v_fmac_f32_e32 v182, v49, v49
	v_fmac_f32_e32 v183, v53, v53
	v_fmac_f32_e32 v180, v42, v42
	v_fmac_f32_e32 v181, v46, v46
	v_fmac_f32_e32 v182, v50, v50
	v_fmac_f32_e32 v183, v54, v54
	v_fmac_f32_e32 v180, v43, v43
	v_fmac_f32_e32 v181, v47, v47
	v_fmac_f32_e32 v182, v51, v51
	v_fmac_f32_e32 v183, v55, v55
	v_add_f32_e32 v180, v180, v181
	v_add_f32_e32 v182, v182, v183
	v_add_f32_e32 v180, v180, v182
	s_nop 1
	v_add_f32_dpp v180, v180, v180 quad_perm:[1,0,3,2] row_mask:0xf bank_mask:0xf
	s_nop 1
	v_add_f32_dpp v180, v180, v180 quad_perm:[2,3,0,1] row_mask:0xf bank_mask:0xf
	s_nop 1
	v_add_f32_dpp v180, v180, v180 row_half_mirror row_mask:0xf bank_mask:0xf
	s_nop 1
	v_add_f32_dpp v180, v180, v180 row_mirror row_mask:0xf bank_mask:0xf
	s_nop 1
	v_add_f32_dpp v180, v180, v180 row_bcast:15 row_mask:0xa bank_mask:0xf
	s_nop 1
	v_add_f32_dpp v180, v180, v180 row_bcast:31 row_mask:0xc bank_mask:0xf
	s_nop 0
	v_readlane_b32 s20, v180, 63
	s_nop 1
	v_mov_b32_e32 v185, s20
	v_fma_f32 v185, v185, v2, v4
	v_rsq_f32_e32 v185, v185
	s_nop 0
	v_mul_f32_e32 v40, v40, v185
	v_mul_f32_e32 v41, v41, v185
	v_mul_f32_e32 v42, v42, v185
	v_mul_f32_e32 v43, v43, v185
	v_mul_f32_e32 v44, v44, v185
	v_mul_f32_e32 v45, v45, v185
	v_mul_f32_e32 v46, v46, v185
	v_mul_f32_e32 v47, v47, v185
	v_mul_f32_e32 v48, v48, v185
	v_mul_f32_e32 v49, v49, v185
	v_mul_f32_e32 v50, v50, v185
	v_mul_f32_e32 v51, v51, v185
	v_mul_f32_e32 v52, v52, v185
	v_mul_f32_e32 v53, v53, v185
	v_mul_f32_e32 v54, v54, v185
	v_mul_f32_e32 v55, v55, v185
	s_waitcnt vmcnt(28)
	v_fma_f32 v40, v40, v8, v24
	v_fma_f32 v41, v41, v9, v25
	v_fma_f32 v42, v42, v10, v26
	v_fma_f32 v43, v43, v11, v27
	v_fma_f32 v44, v44, v12, v28
	v_fma_f32 v45, v45, v13, v29
	v_fma_f32 v46, v46, v14, v30
	v_fma_f32 v47, v47, v15, v31
	v_fma_f32 v48, v48, v16, v32
	v_fma_f32 v49, v49, v17, v33
	v_fma_f32 v50, v50, v18, v34
	v_fma_f32 v51, v51, v19, v35
	v_fma_f32 v52, v52, v20, v36
	v_fma_f32 v53, v53, v21, v37
	v_fma_f32 v54, v54, v22, v38
	v_fma_f32 v55, v55, v23, v39
	v_cvt_pk_bf16_f32 v40, v40, v41
	v_cvt_pk_bf16_f32 v41, v42, v43
	v_cvt_pk_bf16_f32 v44, v44, v45
	v_cvt_pk_bf16_f32 v45, v46, v47
	v_cvt_pk_bf16_f32 v48, v48, v49
	v_cvt_pk_bf16_f32 v49, v50, v51
	v_cvt_pk_bf16_f32 v52, v52, v53
	v_cvt_pk_bf16_f32 v53, v54, v55
	global_store_dwordx2 v5, v[40:41], s[8:9]
	global_store_dwordx2 v5, v[44:45], s[8:9] offset:512
	global_store_dwordx2 v5, v[48:49], s[8:9] offset:1024
	global_store_dwordx2 v5, v[52:53], s[8:9] offset:1536
	v_mov_b32_e32 v172, 0x0
	s_mov_b64 exec, 1
	global_store_dwordx2 v172, v[184:185], s[38:39]
	s_mov_b64 exec, -1
	s_nop 1
	v_add_u32_e32 v170, 0x3000000, v1
	global_load_dwordx4 v[40:43], v170, s[4:5]
	global_load_dwordx4 v[44:47], v170, s[4:5] offset:1024
	global_load_dwordx4 v[48:51], v170, s[4:5] offset:2048
	global_load_dwordx4 v[52:55], v170, s[4:5] offset:3072
	s_waitcnt vmcnt(33)
	v_add_f32_e32 v180, v56, v57
	v_add_f32_e32 v181, v60, v61
	v_add_f32_e32 v182, v64, v65
	v_add_f32_e32 v183, v68, v69
	v_add_f32_e32 v180, v180, v58
	v_add_f32_e32 v181, v181, v62
	v_add_f32_e32 v182, v182, v66
	v_add_f32_e32 v183, v183, v70
	v_add_f32_e32 v180, v180, v59
	v_add_f32_e32 v181, v181, v63
	v_add_f32_e32 v182, v182, v67
	v_add_f32_e32 v183, v183, v71
	v_add_f32_e32 v180, v180, v181
	v_add_f32_e32 v182, v182, v183
	v_add_f32_e32 v180, v180, v182
	s_nop 1
	v_add_f32_dpp v180, v180, v180 quad_perm:[1,0,3,2] row_mask:0xf bank_mask:0xf
	s_nop 1
	v_add_f32_dpp v180, v180, v180 quad_perm:[2,3,0,1] row_mask:0xf bank_mask:0xf
	s_nop 1
	v_add_f32_dpp v180, v180, v180 row_half_mirror row_mask:0xf bank_mask:0xf
	s_nop 1
	v_add_f32_dpp v180, v180, v180 row_mirror row_mask:0xf bank_mask:0xf
	s_nop 1
	v_add_f32_dpp v180, v180, v180 row_bcast:15 row_mask:0xa bank_mask:0xf
	s_nop 1
	v_add_f32_dpp v180, v180, v180 row_bcast:31 row_mask:0xc bank_mask:0xf
	s_nop 0
	v_readlane_b32 s20, v180, 63
	s_nop 1
	v_mul_f32_e32 v184, s20, v2
	v_sub_f32_e32 v56, v56, v184
	v_sub_f32_e32 v57, v57, v184
	v_sub_f32_e32 v58, v58, v184
	v_sub_f32_e32 v59, v59, v184
	v_sub_f32_e32 v60, v60, v184
	v_sub_f32_e32 v61, v61, v184
	v_sub_f32_e32 v62, v62, v184
	v_sub_f32_e32 v63, v63, v184
	v_sub_f32_e32 v64, v64, v184
	v_sub_f32_e32 v65, v65, v184
	v_sub_f32_e32 v66, v66, v184
	v_sub_f32_e32 v67, v67, v184
	v_sub_f32_e32 v68, v68, v184
	v_sub_f32_e32 v69, v69, v184
	v_sub_f32_e32 v70, v70, v184
	v_sub_f32_e32 v71, v71, v184
	v_mul_f32_e32 v180, v56, v56
	v_mul_f32_e32 v181, v60, v60
	v_mul_f32_e32 v182, v64, v64
	v_mul_f32_e32 v183, v68, v68
	v_fmac_f32_e32 v180, v57, v57
	v_fmac_f32_e32 v181, v61, v61
	v_fmac_f32_e32 v182, v65, v65
	v_fmac_f32_e32 v183, v69, v69
	v_fmac_f32_e32 v180, v58, v58
	v_fmac_f32_e32 v181, v62, v62
	v_fmac_f32_e32 v182, v66, v66
	v_fmac_f32_e32 v183, v70, v70
	v_fmac_f32_e32 v180, v59, v59
	v_fmac_f32_e32 v181, v63, v63
	v_fmac_f32_e32 v182, v67, v67
	v_fmac_f32_e32 v183, v71, v71
	v_add_f32_e32 v180, v180, v181
	v_add_f32_e32 v182, v182, v183
	v_add_f32_e32 v180, v180, v182
	s_nop 1
	v_add_f32_dpp v180, v180, v180 quad_perm:[1,0,3,2] row_mask:0xf bank_mask:0xf
	s_nop 1
	v_add_f32_dpp v180, v180, v180 quad_perm:[2,3,0,1] row_mask:0xf bank_mask:0xf
	s_nop 1
	v_add_f32_dpp v180, v180, v180 row_half_mirror row_mask:0xf bank_mask:0xf
	s_nop 1
	v_add_f32_dpp v180, v180, v180 row_mirror row_mask:0xf bank_mask:0xf
	s_nop 1
	v_add_f32_dpp v180, v180, v180 row_bcast:15 row_mask:0xa bank_mask:0xf
	s_nop 1
	v_add_f32_dpp v180, v180, v180 row_bcast:31 row_mask:0xc bank_mask:0xf
	s_nop 0
	v_readlane_b32 s20, v180, 63
	s_nop 1
	v_mov_b32_e32 v185, s20
	v_fma_f32 v185, v185, v2, v4
	v_rsq_f32_e32 v185, v185
	s_nop 0
	v_mul_f32_e32 v56, v56, v185
	v_mul_f32_e32 v57, v57, v185
	v_mul_f32_e32 v58, v58, v185
	v_mul_f32_e32 v59, v59, v185
	v_mul_f32_e32 v60, v60, v185
	v_mul_f32_e32 v61, v61, v185
	v_mul_f32_e32 v62, v62, v185
	v_mul_f32_e32 v63, v63, v185
	v_mul_f32_e32 v64, v64, v185
	v_mul_f32_e32 v65, v65, v185
	v_mul_f32_e32 v66, v66, v185
	v_mul_f32_e32 v67, v67, v185
	v_mul_f32_e32 v68, v68, v185
	v_mul_f32_e32 v69, v69, v185
	v_mul_f32_e32 v70, v70, v185
	v_mul_f32_e32 v71, v71, v185
	v_fma_f32 v56, v56, v8, v24
	v_fma_f32 v57, v57, v9, v25
	v_fma_f32 v58, v58, v10, v26
	v_fma_f32 v59, v59, v11, v27
	v_fma_f32 v60, v60, v12, v28
	v_fma_f32 v61, v61, v13, v29
	v_fma_f32 v62, v62, v14, v30
	v_fma_f32 v63, v63, v15, v31
	v_fma_f32 v64, v64, v16, v32
	v_fma_f32 v65, v65, v17, v33
	v_fma_f32 v66, v66, v18, v34
	v_fma_f32 v67, v67, v19, v35
	v_fma_f32 v68, v68, v20, v36
	v_fma_f32 v69, v69, v21, v37
	v_fma_f32 v70, v70, v22, v38
	v_fma_f32 v71, v71, v23, v39
	v_cvt_pk_bf16_f32 v56, v56, v57
	v_cvt_pk_bf16_f32 v57, v58, v59
	v_cvt_pk_bf16_f32 v60, v60, v61
	v_cvt_pk_bf16_f32 v61, v62, v63
	v_cvt_pk_bf16_f32 v64, v64, v65
	v_cvt_pk_bf16_f32 v65, v66, v67
	v_cvt_pk_bf16_f32 v68, v68, v69
	v_cvt_pk_bf16_f32 v69, v70, v71
	v_add_u32_e32 v171, 0x300000, v5
	global_store_dwordx2 v171, v[56:57], s[8:9]
	global_store_dwordx2 v171, v[60:61], s[8:9] offset:512
	global_store_dwordx2 v171, v[64:65], s[8:9] offset:1024
	global_store_dwordx2 v171, v[68:69], s[8:9] offset:1536
	v_mov_b32_e32 v172, 0x3000
	s_mov_b64 exec, 1
	global_store_dwordx2 v172, v[184:185], s[38:39]
	s_mov_b64 exec, -1
	s_nop 1
	v_add_u32_e32 v170, 0x3600000, v1
	global_load_dwordx4 v[56:59], v170, s[4:5]
	global_load_dwordx4 v[60:63], v170, s[4:5] offset:1024
	global_load_dwordx4 v[64:67], v170, s[4:5] offset:2048
	global_load_dwordx4 v[68:71], v170, s[4:5] offset:3072
	s_waitcnt vmcnt(38)
	v_add_f32_e32 v180, v72, v73
	v_add_f32_e32 v181, v76, v77
	v_add_f32_e32 v182, v80, v81
	v_add_f32_e32 v183, v84, v85
	v_add_f32_e32 v180, v180, v74
	v_add_f32_e32 v181, v181, v78
	v_add_f32_e32 v182, v182, v82
	v_add_f32_e32 v183, v183, v86
	v_add_f32_e32 v180, v180, v75
	v_add_f32_e32 v181, v181, v79
	v_add_f32_e32 v182, v182, v83
	v_add_f32_e32 v183, v183, v87
	v_add_f32_e32 v180, v180, v181
	v_add_f32_e32 v182, v182, v183
	v_add_f32_e32 v180, v180, v182
	s_nop 1
	v_add_f32_dpp v180, v180, v180 quad_perm:[1,0,3,2] row_mask:0xf bank_mask:0xf
	s_nop 1
	v_add_f32_dpp v180, v180, v180 quad_perm:[2,3,0,1] row_mask:0xf bank_mask:0xf
	s_nop 1
	v_add_f32_dpp v180, v180, v180 row_half_mirror row_mask:0xf bank_mask:0xf
	s_nop 1
	v_add_f32_dpp v180, v180, v180 row_mirror row_mask:0xf bank_mask:0xf
	s_nop 1
	v_add_f32_dpp v180, v180, v180 row_bcast:15 row_mask:0xa bank_mask:0xf
	s_nop 1
	v_add_f32_dpp v180, v180, v180 row_bcast:31 row_mask:0xc bank_mask:0xf
	s_nop 0
	v_readlane_b32 s20, v180, 63
	s_nop 1
	v_mul_f32_e32 v184, s20, v2
	v_sub_f32_e32 v72, v72, v184
	v_sub_f32_e32 v73, v73, v184
	v_sub_f32_e32 v74, v74, v184
	v_sub_f32_e32 v75, v75, v184
	v_sub_f32_e32 v76, v76, v184
	v_sub_f32_e32 v77, v77, v184
	v_sub_f32_e32 v78, v78, v184
	v_sub_f32_e32 v79, v79, v184
	v_sub_f32_e32 v80, v80, v184
	v_sub_f32_e32 v81, v81, v184
	v_sub_f32_e32 v82, v82, v184
	v_sub_f32_e32 v83, v83, v184
	v_sub_f32_e32 v84, v84, v184
	v_sub_f32_e32 v85, v85, v184
	v_sub_f32_e32 v86, v86, v184
	v_sub_f32_e32 v87, v87, v184
	v_mul_f32_e32 v180, v72, v72
	v_mul_f32_e32 v181, v76, v76
	v_mul_f32_e32 v182, v80, v80
	v_mul_f32_e32 v183, v84, v84
	v_fmac_f32_e32 v180, v73, v73
	v_fmac_f32_e32 v181, v77, v77
	v_fmac_f32_e32 v182, v81, v81
	v_fmac_f32_e32 v183, v85, v85
	v_fmac_f32_e32 v180, v74, v74
	v_fmac_f32_e32 v181, v78, v78
	v_fmac_f32_e32 v182, v82, v82
	v_fmac_f32_e32 v183, v86, v86
	v_fmac_f32_e32 v180, v75, v75
	v_fmac_f32_e32 v181, v79, v79
	v_fmac_f32_e32 v182, v83, v83
	v_fmac_f32_e32 v183, v87, v87
	v_add_f32_e32 v180, v180, v181
	v_add_f32_e32 v182, v182, v183
	v_add_f32_e32 v180, v180, v182
	s_nop 1
	v_add_f32_dpp v180, v180, v180 quad_perm:[1,0,3,2] row_mask:0xf bank_mask:0xf
	s_nop 1
	v_add_f32_dpp v180, v180, v180 quad_perm:[2,3,0,1] row_mask:0xf bank_mask:0xf
	s_nop 1
	v_add_f32_dpp v180, v180, v180 row_half_mirror row_mask:0xf bank_mask:0xf
	s_nop 1
	v_add_f32_dpp v180, v180, v180 row_mirror row_mask:0xf bank_mask:0xf
	s_nop 1
	v_add_f32_dpp v180, v180, v180 row_bcast:15 row_mask:0xa bank_mask:0xf
	s_nop 1
	v_add_f32_dpp v180, v180, v180 row_bcast:31 row_mask:0xc bank_mask:0xf
	s_nop 0
	v_readlane_b32 s20, v180, 63
	s_nop 1
	v_mov_b32_e32 v185, s20
	v_fma_f32 v185, v185, v2, v4
	v_rsq_f32_e32 v185, v185
	s_nop 0
	v_mul_f32_e32 v72, v72, v185
	v_mul_f32_e32 v73, v73, v185
	v_mul_f32_e32 v74, v74, v185
	v_mul_f32_e32 v75, v75, v185
	v_mul_f32_e32 v76, v76, v185
	v_mul_f32_e32 v77, v77, v185
	v_mul_f32_e32 v78, v78, v185
	v_mul_f32_e32 v79, v79, v185
	v_mul_f32_e32 v80, v80, v185
	v_mul_f32_e32 v81, v81, v185
	v_mul_f32_e32 v82, v82, v185
	v_mul_f32_e32 v83, v83, v185
	v_mul_f32_e32 v84, v84, v185
	v_mul_f32_e32 v85, v85, v185
	v_mul_f32_e32 v86, v86, v185
	v_mul_f32_e32 v87, v87, v185
	v_fma_f32 v72, v72, v8, v24
	v_fma_f32 v73, v73, v9, v25
	v_fma_f32 v74, v74, v10, v26
	v_fma_f32 v75, v75, v11, v27
	v_fma_f32 v76, v76, v12, v28
	v_fma_f32 v77, v77, v13, v29
	v_fma_f32 v78, v78, v14, v30
	v_fma_f32 v79, v79, v15, v31
	v_fma_f32 v80, v80, v16, v32
	v_fma_f32 v81, v81, v17, v33
	v_fma_f32 v82, v82, v18, v34
	v_fma_f32 v83, v83, v19, v35
	v_fma_f32 v84, v84, v20, v36
	v_fma_f32 v85, v85, v21, v37
	v_fma_f32 v86, v86, v22, v38
	v_fma_f32 v87, v87, v23, v39
	v_cvt_pk_bf16_f32 v72, v72, v73
	v_cvt_pk_bf16_f32 v73, v74, v75
	v_cvt_pk_bf16_f32 v76, v76, v77
	v_cvt_pk_bf16_f32 v77, v78, v79
	v_cvt_pk_bf16_f32 v80, v80, v81
	v_cvt_pk_bf16_f32 v81, v82, v83
	v_cvt_pk_bf16_f32 v84, v84, v85
	v_cvt_pk_bf16_f32 v85, v86, v87
	v_add_u32_e32 v171, 0x600000, v5
	global_store_dwordx2 v171, v[72:73], s[8:9]
	global_store_dwordx2 v171, v[76:77], s[8:9] offset:512
	global_store_dwordx2 v171, v[80:81], s[8:9] offset:1024
	global_store_dwordx2 v171, v[84:85], s[8:9] offset:1536
	v_mov_b32_e32 v172, 0x6000
	s_mov_b64 exec, 1
	global_store_dwordx2 v172, v[184:185], s[38:39]
	s_mov_b64 exec, -1
	s_waitcnt vmcnt(39)
	v_add_f32_e32 v180, v88, v89
	v_add_f32_e32 v181, v92, v93
	v_add_f32_e32 v182, v96, v97
	v_add_f32_e32 v183, v100, v101
	v_add_f32_e32 v180, v180, v90
	v_add_f32_e32 v181, v181, v94
	v_add_f32_e32 v182, v182, v98
	v_add_f32_e32 v183, v183, v102
	v_add_f32_e32 v180, v180, v91
	v_add_f32_e32 v181, v181, v95
	v_add_f32_e32 v182, v182, v99
	v_add_f32_e32 v183, v183, v103
	v_add_f32_e32 v180, v180, v181
	v_add_f32_e32 v182, v182, v183
	v_add_f32_e32 v180, v180, v182
	s_nop 1
	v_add_f32_dpp v180, v180, v180 quad_perm:[1,0,3,2] row_mask:0xf bank_mask:0xf
	s_nop 1
	v_add_f32_dpp v180, v180, v180 quad_perm:[2,3,0,1] row_mask:0xf bank_mask:0xf
	s_nop 1
	v_add_f32_dpp v180, v180, v180 row_half_mirror row_mask:0xf bank_mask:0xf
	s_nop 1
	v_add_f32_dpp v180, v180, v180 row_mirror row_mask:0xf bank_mask:0xf
	s_nop 1
	v_add_f32_dpp v180, v180, v180 row_bcast:15 row_mask:0xa bank_mask:0xf
	s_nop 1
	v_add_f32_dpp v180, v180, v180 row_bcast:31 row_mask:0xc bank_mask:0xf
	s_nop 0
	v_readlane_b32 s20, v180, 63
	s_nop 1
	v_mul_f32_e32 v184, s20, v2
	v_sub_f32_e32 v88, v88, v184
	v_sub_f32_e32 v89, v89, v184
	v_sub_f32_e32 v90, v90, v184
	v_sub_f32_e32 v91, v91, v184
	v_sub_f32_e32 v92, v92, v184
	v_sub_f32_e32 v93, v93, v184
	v_sub_f32_e32 v94, v94, v184
	v_sub_f32_e32 v95, v95, v184
	v_sub_f32_e32 v96, v96, v184
	v_sub_f32_e32 v97, v97, v184
	v_sub_f32_e32 v98, v98, v184
	v_sub_f32_e32 v99, v99, v184
	v_sub_f32_e32 v100, v100, v184
	v_sub_f32_e32 v101, v101, v184
	v_sub_f32_e32 v102, v102, v184
	v_sub_f32_e32 v103, v103, v184
	v_mul_f32_e32 v180, v88, v88
	v_mul_f32_e32 v181, v92, v92
	v_mul_f32_e32 v182, v96, v96
	v_mul_f32_e32 v183, v100, v100
	v_fmac_f32_e32 v180, v89, v89
	v_fmac_f32_e32 v181, v93, v93
	v_fmac_f32_e32 v182, v97, v97
	v_fmac_f32_e32 v183, v101, v101
	v_fmac_f32_e32 v180, v90, v90
	v_fmac_f32_e32 v181, v94, v94
	v_fmac_f32_e32 v182, v98, v98
	v_fmac_f32_e32 v183, v102, v102
	v_fmac_f32_e32 v180, v91, v91
	v_fmac_f32_e32 v181, v95, v95
	v_fmac_f32_e32 v182, v99, v99
	v_fmac_f32_e32 v183, v103, v103
	v_add_f32_e32 v180, v180, v181
	v_add_f32_e32 v182, v182, v183
	v_add_f32_e32 v180, v180, v182
	s_nop 1
	v_add_f32_dpp v180, v180, v180 quad_perm:[1,0,3,2] row_mask:0xf bank_mask:0xf
	s_nop 1
	v_add_f32_dpp v180, v180, v180 quad_perm:[2,3,0,1] row_mask:0xf bank_mask:0xf
	s_nop 1
	v_add_f32_dpp v180, v180, v180 row_half_mirror row_mask:0xf bank_mask:0xf
	s_nop 1
	v_add_f32_dpp v180, v180, v180 row_mirror row_mask:0xf bank_mask:0xf
	s_nop 1
	v_add_f32_dpp v180, v180, v180 row_bcast:15 row_mask:0xa bank_mask:0xf
	s_nop 1
	v_add_f32_dpp v180, v180, v180 row_bcast:31 row_mask:0xc bank_mask:0xf
	s_nop 0
	v_readlane_b32 s20, v180, 63
	s_nop 1
	v_mov_b32_e32 v185, s20
	v_fma_f32 v185, v185, v2, v4
	v_rsq_f32_e32 v185, v185
	s_nop 0
	v_mul_f32_e32 v88, v88, v185
	v_mul_f32_e32 v89, v89, v185
	v_mul_f32_e32 v90, v90, v185
	v_mul_f32_e32 v91, v91, v185
	v_mul_f32_e32 v92, v92, v185
	v_mul_f32_e32 v93, v93, v185
	v_mul_f32_e32 v94, v94, v185
	v_mul_f32_e32 v95, v95, v185
	v_mul_f32_e32 v96, v96, v185
	v_mul_f32_e32 v97, v97, v185
	v_mul_f32_e32 v98, v98, v185
	v_mul_f32_e32 v99, v99, v185
	v_mul_f32_e32 v100, v100, v185
	v_mul_f32_e32 v101, v101, v185
	v_mul_f32_e32 v102, v102, v185
	v_mul_f32_e32 v103, v103, v185
	v_fma_f32 v88, v88, v8, v24
	v_fma_f32 v89, v89, v9, v25
	v_fma_f32 v90, v90, v10, v26
	v_fma_f32 v91, v91, v11, v27
	v_fma_f32 v92, v92, v12, v28
	v_fma_f32 v93, v93, v13, v29
	v_fma_f32 v94, v94, v14, v30
	v_fma_f32 v95, v95, v15, v31
	v_fma_f32 v96, v96, v16, v32
	v_fma_f32 v97, v97, v17, v33
	v_fma_f32 v98, v98, v18, v34
	v_fma_f32 v99, v99, v19, v35
	v_fma_f32 v100, v100, v20, v36
	v_fma_f32 v101, v101, v21, v37
	v_fma_f32 v102, v102, v22, v38
	v_fma_f32 v103, v103, v23, v39
	v_cvt_pk_bf16_f32 v88, v88, v89
	v_cvt_pk_bf16_f32 v89, v90, v91
	v_cvt_pk_bf16_f32 v92, v92, v93
	v_cvt_pk_bf16_f32 v93, v94, v95
	v_cvt_pk_bf16_f32 v96, v96, v97
	v_cvt_pk_bf16_f32 v97, v98, v99
	v_cvt_pk_bf16_f32 v100, v100, v101
	v_cvt_pk_bf16_f32 v101, v102, v103
	v_add_u32_e32 v171, 0x900000, v5
	global_store_dwordx2 v171, v[88:89], s[8:9]
	global_store_dwordx2 v171, v[92:93], s[8:9] offset:512
	global_store_dwordx2 v171, v[96:97], s[8:9] offset:1024
	global_store_dwordx2 v171, v[100:101], s[8:9] offset:1536
	v_mov_b32_e32 v172, 0x9000
	s_mov_b64 exec, 1
	global_store_dwordx2 v172, v[184:185], s[38:39]
	s_mov_b64 exec, -1
	s_waitcnt vmcnt(40)
	v_add_f32_e32 v180, v104, v105
	v_add_f32_e32 v181, v108, v109
	v_add_f32_e32 v182, v112, v113
	v_add_f32_e32 v183, v116, v117
	v_add_f32_e32 v180, v180, v106
	v_add_f32_e32 v181, v181, v110
	v_add_f32_e32 v182, v182, v114
	v_add_f32_e32 v183, v183, v118
	v_add_f32_e32 v180, v180, v107
	v_add_f32_e32 v181, v181, v111
	v_add_f32_e32 v182, v182, v115
	v_add_f32_e32 v183, v183, v119
	v_add_f32_e32 v180, v180, v181
	v_add_f32_e32 v182, v182, v183
	v_add_f32_e32 v180, v180, v182
	s_nop 1
	v_add_f32_dpp v180, v180, v180 quad_perm:[1,0,3,2] row_mask:0xf bank_mask:0xf
	s_nop 1
	v_add_f32_dpp v180, v180, v180 quad_perm:[2,3,0,1] row_mask:0xf bank_mask:0xf
	s_nop 1
	v_add_f32_dpp v180, v180, v180 row_half_mirror row_mask:0xf bank_mask:0xf
	s_nop 1
	v_add_f32_dpp v180, v180, v180 row_mirror row_mask:0xf bank_mask:0xf
	s_nop 1
	v_add_f32_dpp v180, v180, v180 row_bcast:15 row_mask:0xa bank_mask:0xf
	s_nop 1
	v_add_f32_dpp v180, v180, v180 row_bcast:31 row_mask:0xc bank_mask:0xf
	s_nop 0
	v_readlane_b32 s20, v180, 63
	s_nop 1
	v_mul_f32_e32 v184, s20, v2
	v_sub_f32_e32 v104, v104, v184
	v_sub_f32_e32 v105, v105, v184
	v_sub_f32_e32 v106, v106, v184
	v_sub_f32_e32 v107, v107, v184
	v_sub_f32_e32 v108, v108, v184
	v_sub_f32_e32 v109, v109, v184
	v_sub_f32_e32 v110, v110, v184
	v_sub_f32_e32 v111, v111, v184
	v_sub_f32_e32 v112, v112, v184
	v_sub_f32_e32 v113, v113, v184
	v_sub_f32_e32 v114, v114, v184
	v_sub_f32_e32 v115, v115, v184
	v_sub_f32_e32 v116, v116, v184
	v_sub_f32_e32 v117, v117, v184
	v_sub_f32_e32 v118, v118, v184
	v_sub_f32_e32 v119, v119, v184
	v_mul_f32_e32 v180, v104, v104
	v_mul_f32_e32 v181, v108, v108
	v_mul_f32_e32 v182, v112, v112
	v_mul_f32_e32 v183, v116, v116
	v_fmac_f32_e32 v180, v105, v105
	v_fmac_f32_e32 v181, v109, v109
	v_fmac_f32_e32 v182, v113, v113
	v_fmac_f32_e32 v183, v117, v117
	v_fmac_f32_e32 v180, v106, v106
	v_fmac_f32_e32 v181, v110, v110
	v_fmac_f32_e32 v182, v114, v114
	v_fmac_f32_e32 v183, v118, v118
	v_fmac_f32_e32 v180, v107, v107
	v_fmac_f32_e32 v181, v111, v111
	v_fmac_f32_e32 v182, v115, v115
	v_fmac_f32_e32 v183, v119, v119
	v_add_f32_e32 v180, v180, v181
	v_add_f32_e32 v182, v182, v183
	v_add_f32_e32 v180, v180, v182
	s_nop 1
	v_add_f32_dpp v180, v180, v180 quad_perm:[1,0,3,2] row_mask:0xf bank_mask:0xf
	s_nop 1
	v_add_f32_dpp v180, v180, v180 quad_perm:[2,3,0,1] row_mask:0xf bank_mask:0xf
	s_nop 1
	v_add_f32_dpp v180, v180, v180 row_half_mirror row_mask:0xf bank_mask:0xf
	s_nop 1
	v_add_f32_dpp v180, v180, v180 row_mirror row_mask:0xf bank_mask:0xf
	s_nop 1
	v_add_f32_dpp v180, v180, v180 row_bcast:15 row_mask:0xa bank_mask:0xf
	s_nop 1
	v_add_f32_dpp v180, v180, v180 row_bcast:31 row_mask:0xc bank_mask:0xf
	s_nop 0
	v_readlane_b32 s20, v180, 63
	s_nop 1
	v_mov_b32_e32 v185, s20
	v_fma_f32 v185, v185, v2, v4
	v_rsq_f32_e32 v185, v185
	s_nop 0
	v_mul_f32_e32 v104, v104, v185
	v_mul_f32_e32 v105, v105, v185
	v_mul_f32_e32 v106, v106, v185
	v_mul_f32_e32 v107, v107, v185
	v_mul_f32_e32 v108, v108, v185
	v_mul_f32_e32 v109, v109, v185
	v_mul_f32_e32 v110, v110, v185
	v_mul_f32_e32 v111, v111, v185
	v_mul_f32_e32 v112, v112, v185
	v_mul_f32_e32 v113, v113, v185
	v_mul_f32_e32 v114, v114, v185
	v_mul_f32_e32 v115, v115, v185
	v_mul_f32_e32 v116, v116, v185
	v_mul_f32_e32 v117, v117, v185
	v_mul_f32_e32 v118, v118, v185
	v_mul_f32_e32 v119, v119, v185
	v_fma_f32 v104, v104, v8, v24
	v_fma_f32 v105, v105, v9, v25
	v_fma_f32 v106, v106, v10, v26
	v_fma_f32 v107, v107, v11, v27
	v_fma_f32 v108, v108, v12, v28
	v_fma_f32 v109, v109, v13, v29
	v_fma_f32 v110, v110, v14, v30
	v_fma_f32 v111, v111, v15, v31
	v_fma_f32 v112, v112, v16, v32
	v_fma_f32 v113, v113, v17, v33
	v_fma_f32 v114, v114, v18, v34
	v_fma_f32 v115, v115, v19, v35
	v_fma_f32 v116, v116, v20, v36
	v_fma_f32 v117, v117, v21, v37
	v_fma_f32 v118, v118, v22, v38
	v_fma_f32 v119, v119, v23, v39
	v_cvt_pk_bf16_f32 v104, v104, v105
	v_cvt_pk_bf16_f32 v105, v106, v107
	v_cvt_pk_bf16_f32 v108, v108, v109
	v_cvt_pk_bf16_f32 v109, v110, v111
	v_cvt_pk_bf16_f32 v112, v112, v113
	v_cvt_pk_bf16_f32 v113, v114, v115
	v_cvt_pk_bf16_f32 v116, v116, v117
	v_cvt_pk_bf16_f32 v117, v118, v119
	v_add_u32_e32 v171, 0xc00000, v5
	global_store_dwordx2 v171, v[104:105], s[8:9]
	global_store_dwordx2 v171, v[108:109], s[8:9] offset:512
	global_store_dwordx2 v171, v[112:113], s[8:9] offset:1024
	global_store_dwordx2 v171, v[116:117], s[8:9] offset:1536
	v_mov_b32_e32 v172, 0xc000
	s_mov_b64 exec, 1
	global_store_dwordx2 v172, v[184:185], s[38:39]
	s_mov_b64 exec, -1
	s_waitcnt vmcnt(41)
	v_add_f32_e32 v180, v120, v121
	v_add_f32_e32 v181, v124, v125
	v_add_f32_e32 v182, v128, v129
	v_add_f32_e32 v183, v132, v133
	v_add_f32_e32 v180, v180, v122
	v_add_f32_e32 v181, v181, v126
	v_add_f32_e32 v182, v182, v130
	v_add_f32_e32 v183, v183, v134
	v_add_f32_e32 v180, v180, v123
	v_add_f32_e32 v181, v181, v127
	v_add_f32_e32 v182, v182, v131
	v_add_f32_e32 v183, v183, v135
	v_add_f32_e32 v180, v180, v181
	v_add_f32_e32 v182, v182, v183
	v_add_f32_e32 v180, v180, v182
	s_nop 1
	v_add_f32_dpp v180, v180, v180 quad_perm:[1,0,3,2] row_mask:0xf bank_mask:0xf
	s_nop 1
	v_add_f32_dpp v180, v180, v180 quad_perm:[2,3,0,1] row_mask:0xf bank_mask:0xf
	s_nop 1
	v_add_f32_dpp v180, v180, v180 row_half_mirror row_mask:0xf bank_mask:0xf
	s_nop 1
	v_add_f32_dpp v180, v180, v180 row_mirror row_mask:0xf bank_mask:0xf
	s_nop 1
	v_add_f32_dpp v180, v180, v180 row_bcast:15 row_mask:0xa bank_mask:0xf
	s_nop 1
	v_add_f32_dpp v180, v180, v180 row_bcast:31 row_mask:0xc bank_mask:0xf
	s_nop 0
	v_readlane_b32 s20, v180, 63
	s_nop 1
	v_mul_f32_e32 v184, s20, v2
	v_sub_f32_e32 v120, v120, v184
	v_sub_f32_e32 v121, v121, v184
	v_sub_f32_e32 v122, v122, v184
	v_sub_f32_e32 v123, v123, v184
	v_sub_f32_e32 v124, v124, v184
	v_sub_f32_e32 v125, v125, v184
	v_sub_f32_e32 v126, v126, v184
	v_sub_f32_e32 v127, v127, v184
	v_sub_f32_e32 v128, v128, v184
	v_sub_f32_e32 v129, v129, v184
	v_sub_f32_e32 v130, v130, v184
	v_sub_f32_e32 v131, v131, v184
	v_sub_f32_e32 v132, v132, v184
	v_sub_f32_e32 v133, v133, v184
	v_sub_f32_e32 v134, v134, v184
	v_sub_f32_e32 v135, v135, v184
	v_mul_f32_e32 v180, v120, v120
	v_mul_f32_e32 v181, v124, v124
	v_mul_f32_e32 v182, v128, v128
	v_mul_f32_e32 v183, v132, v132
	v_fmac_f32_e32 v180, v121, v121
	v_fmac_f32_e32 v181, v125, v125
	v_fmac_f32_e32 v182, v129, v129
	v_fmac_f32_e32 v183, v133, v133
	v_fmac_f32_e32 v180, v122, v122
	v_fmac_f32_e32 v181, v126, v126
	v_fmac_f32_e32 v182, v130, v130
	v_fmac_f32_e32 v183, v134, v134
	v_fmac_f32_e32 v180, v123, v123
	v_fmac_f32_e32 v181, v127, v127
	v_fmac_f32_e32 v182, v131, v131
	v_fmac_f32_e32 v183, v135, v135
	v_add_f32_e32 v180, v180, v181
	v_add_f32_e32 v182, v182, v183
	v_add_f32_e32 v180, v180, v182
	s_nop 1
	v_add_f32_dpp v180, v180, v180 quad_perm:[1,0,3,2] row_mask:0xf bank_mask:0xf
	s_nop 1
	v_add_f32_dpp v180, v180, v180 quad_perm:[2,3,0,1] row_mask:0xf bank_mask:0xf
	s_nop 1
	v_add_f32_dpp v180, v180, v180 row_half_mirror row_mask:0xf bank_mask:0xf
	s_nop 1
	v_add_f32_dpp v180, v180, v180 row_mirror row_mask:0xf bank_mask:0xf
	s_nop 1
	v_add_f32_dpp v180, v180, v180 row_bcast:15 row_mask:0xa bank_mask:0xf
	s_nop 1
	v_add_f32_dpp v180, v180, v180 row_bcast:31 row_mask:0xc bank_mask:0xf
	s_nop 0
	v_readlane_b32 s20, v180, 63
	s_nop 1
	v_mov_b32_e32 v185, s20
	v_fma_f32 v185, v185, v2, v4
	v_rsq_f32_e32 v185, v185
	s_nop 0
	v_mul_f32_e32 v120, v120, v185
	v_mul_f32_e32 v121, v121, v185
	v_mul_f32_e32 v122, v122, v185
	v_mul_f32_e32 v123, v123, v185
	v_mul_f32_e32 v124, v124, v185
	v_mul_f32_e32 v125, v125, v185
	v_mul_f32_e32 v126, v126, v185
	v_mul_f32_e32 v127, v127, v185
	v_mul_f32_e32 v128, v128, v185
	v_mul_f32_e32 v129, v129, v185
	v_mul_f32_e32 v130, v130, v185
	v_mul_f32_e32 v131, v131, v185
	v_mul_f32_e32 v132, v132, v185
	v_mul_f32_e32 v133, v133, v185
	v_mul_f32_e32 v134, v134, v185
	v_mul_f32_e32 v135, v135, v185
	v_fma_f32 v120, v120, v8, v24
	v_fma_f32 v121, v121, v9, v25
	v_fma_f32 v122, v122, v10, v26
	v_fma_f32 v123, v123, v11, v27
	v_fma_f32 v124, v124, v12, v28
	v_fma_f32 v125, v125, v13, v29
	v_fma_f32 v126, v126, v14, v30
	v_fma_f32 v127, v127, v15, v31
	v_fma_f32 v128, v128, v16, v32
	v_fma_f32 v129, v129, v17, v33
	v_fma_f32 v130, v130, v18, v34
	v_fma_f32 v131, v131, v19, v35
	v_fma_f32 v132, v132, v20, v36
	v_fma_f32 v133, v133, v21, v37
	v_fma_f32 v134, v134, v22, v38
	v_fma_f32 v135, v135, v23, v39
	v_cvt_pk_bf16_f32 v120, v120, v121
	v_cvt_pk_bf16_f32 v121, v122, v123
	v_cvt_pk_bf16_f32 v124, v124, v125
	v_cvt_pk_bf16_f32 v125, v126, v127
	v_cvt_pk_bf16_f32 v128, v128, v129
	v_cvt_pk_bf16_f32 v129, v130, v131
	v_cvt_pk_bf16_f32 v132, v132, v133
	v_cvt_pk_bf16_f32 v133, v134, v135
	v_add_u32_e32 v171, 0xf00000, v5
	global_store_dwordx2 v171, v[120:121], s[8:9]
	global_store_dwordx2 v171, v[124:125], s[8:9] offset:512
	global_store_dwordx2 v171, v[128:129], s[8:9] offset:1024
	global_store_dwordx2 v171, v[132:133], s[8:9] offset:1536
	v_mov_b32_e32 v172, 0xf000
	s_mov_b64 exec, 1
	global_store_dwordx2 v172, v[184:185], s[38:39]
	s_mov_b64 exec, -1
	s_waitcnt vmcnt(42)
	v_add_f32_e32 v180, v136, v137
	v_add_f32_e32 v181, v140, v141
	v_add_f32_e32 v182, v144, v145
	v_add_f32_e32 v183, v148, v149
	v_add_f32_e32 v180, v180, v138
	v_add_f32_e32 v181, v181, v142
	v_add_f32_e32 v182, v182, v146
	v_add_f32_e32 v183, v183, v150
	v_add_f32_e32 v180, v180, v139
	v_add_f32_e32 v181, v181, v143
	v_add_f32_e32 v182, v182, v147
	v_add_f32_e32 v183, v183, v151
	v_add_f32_e32 v180, v180, v181
	v_add_f32_e32 v182, v182, v183
	v_add_f32_e32 v180, v180, v182
	s_nop 1
	v_add_f32_dpp v180, v180, v180 quad_perm:[1,0,3,2] row_mask:0xf bank_mask:0xf
	s_nop 1
	v_add_f32_dpp v180, v180, v180 quad_perm:[2,3,0,1] row_mask:0xf bank_mask:0xf
	s_nop 1
	v_add_f32_dpp v180, v180, v180 row_half_mirror row_mask:0xf bank_mask:0xf
	s_nop 1
	v_add_f32_dpp v180, v180, v180 row_mirror row_mask:0xf bank_mask:0xf
	s_nop 1
	v_add_f32_dpp v180, v180, v180 row_bcast:15 row_mask:0xa bank_mask:0xf
	s_nop 1
	v_add_f32_dpp v180, v180, v180 row_bcast:31 row_mask:0xc bank_mask:0xf
	s_nop 0
	v_readlane_b32 s20, v180, 63
	s_nop 1
	v_mul_f32_e32 v184, s20, v2
	v_sub_f32_e32 v136, v136, v184
	v_sub_f32_e32 v137, v137, v184
	v_sub_f32_e32 v138, v138, v184
	v_sub_f32_e32 v139, v139, v184
	v_sub_f32_e32 v140, v140, v184
	v_sub_f32_e32 v141, v141, v184
	v_sub_f32_e32 v142, v142, v184
	v_sub_f32_e32 v143, v143, v184
	v_sub_f32_e32 v144, v144, v184
	v_sub_f32_e32 v145, v145, v184
	v_sub_f32_e32 v146, v146, v184
	v_sub_f32_e32 v147, v147, v184
	v_sub_f32_e32 v148, v148, v184
	v_sub_f32_e32 v149, v149, v184
	v_sub_f32_e32 v150, v150, v184
	v_sub_f32_e32 v151, v151, v184
	v_mul_f32_e32 v180, v136, v136
	v_mul_f32_e32 v181, v140, v140
	v_mul_f32_e32 v182, v144, v144
	v_mul_f32_e32 v183, v148, v148
	v_fmac_f32_e32 v180, v137, v137
	v_fmac_f32_e32 v181, v141, v141
	v_fmac_f32_e32 v182, v145, v145
	v_fmac_f32_e32 v183, v149, v149
	v_fmac_f32_e32 v180, v138, v138
	v_fmac_f32_e32 v181, v142, v142
	v_fmac_f32_e32 v182, v146, v146
	v_fmac_f32_e32 v183, v150, v150
	v_fmac_f32_e32 v180, v139, v139
	v_fmac_f32_e32 v181, v143, v143
	v_fmac_f32_e32 v182, v147, v147
	v_fmac_f32_e32 v183, v151, v151
	v_add_f32_e32 v180, v180, v181
	v_add_f32_e32 v182, v182, v183
	v_add_f32_e32 v180, v180, v182
	s_nop 1
	v_add_f32_dpp v180, v180, v180 quad_perm:[1,0,3,2] row_mask:0xf bank_mask:0xf
	s_nop 1
	v_add_f32_dpp v180, v180, v180 quad_perm:[2,3,0,1] row_mask:0xf bank_mask:0xf
	s_nop 1
	v_add_f32_dpp v180, v180, v180 row_half_mirror row_mask:0xf bank_mask:0xf
	s_nop 1
	v_add_f32_dpp v180, v180, v180 row_mirror row_mask:0xf bank_mask:0xf
	s_nop 1
	v_add_f32_dpp v180, v180, v180 row_bcast:15 row_mask:0xa bank_mask:0xf
	s_nop 1
	v_add_f32_dpp v180, v180, v180 row_bcast:31 row_mask:0xc bank_mask:0xf
	s_nop 0
	v_readlane_b32 s20, v180, 63
	s_nop 1
	v_mov_b32_e32 v185, s20
	v_fma_f32 v185, v185, v2, v4
	v_rsq_f32_e32 v185, v185
	s_nop 0
	v_mul_f32_e32 v136, v136, v185
	v_mul_f32_e32 v137, v137, v185
	v_mul_f32_e32 v138, v138, v185
	v_mul_f32_e32 v139, v139, v185
	v_mul_f32_e32 v140, v140, v185
	v_mul_f32_e32 v141, v141, v185
	v_mul_f32_e32 v142, v142, v185
	v_mul_f32_e32 v143, v143, v185
	v_mul_f32_e32 v144, v144, v185
	v_mul_f32_e32 v145, v145, v185
	v_mul_f32_e32 v146, v146, v185
	v_mul_f32_e32 v147, v147, v185
	v_mul_f32_e32 v148, v148, v185
	v_mul_f32_e32 v149, v149, v185
	v_mul_f32_e32 v150, v150, v185
	v_mul_f32_e32 v151, v151, v185
	v_fma_f32 v136, v136, v8, v24
	v_fma_f32 v137, v137, v9, v25
	v_fma_f32 v138, v138, v10, v26
	v_fma_f32 v139, v139, v11, v27
	v_fma_f32 v140, v140, v12, v28
	v_fma_f32 v141, v141, v13, v29
	v_fma_f32 v142, v142, v14, v30
	v_fma_f32 v143, v143, v15, v31
	v_fma_f32 v144, v144, v16, v32
	v_fma_f32 v145, v145, v17, v33
	v_fma_f32 v146, v146, v18, v34
	v_fma_f32 v147, v147, v19, v35
	v_fma_f32 v148, v148, v20, v36
	v_fma_f32 v149, v149, v21, v37
	v_fma_f32 v150, v150, v22, v38
	v_fma_f32 v151, v151, v23, v39
	v_cvt_pk_bf16_f32 v136, v136, v137
	v_cvt_pk_bf16_f32 v137, v138, v139
	v_cvt_pk_bf16_f32 v140, v140, v141
	v_cvt_pk_bf16_f32 v141, v142, v143
	v_cvt_pk_bf16_f32 v144, v144, v145
	v_cvt_pk_bf16_f32 v145, v146, v147
	v_cvt_pk_bf16_f32 v148, v148, v149
	v_cvt_pk_bf16_f32 v149, v150, v151
	v_add_u32_e32 v171, 0x1200000, v5
	global_store_dwordx2 v171, v[136:137], s[8:9]
	global_store_dwordx2 v171, v[140:141], s[8:9] offset:512
	global_store_dwordx2 v171, v[144:145], s[8:9] offset:1024
	global_store_dwordx2 v171, v[148:149], s[8:9] offset:1536
	v_mov_b32_e32 v172, 0x12000
	s_mov_b64 exec, 1
	global_store_dwordx2 v172, v[184:185], s[38:39]
	s_mov_b64 exec, -1
	s_waitcnt vmcnt(43)
	v_add_f32_e32 v180, v152, v153
	v_add_f32_e32 v181, v156, v157
	v_add_f32_e32 v182, v160, v161
	v_add_f32_e32 v183, v164, v165
	v_add_f32_e32 v180, v180, v154
	v_add_f32_e32 v181, v181, v158
	v_add_f32_e32 v182, v182, v162
	v_add_f32_e32 v183, v183, v166
	v_add_f32_e32 v180, v180, v155
	v_add_f32_e32 v181, v181, v159
	v_add_f32_e32 v182, v182, v163
	v_add_f32_e32 v183, v183, v167
	v_add_f32_e32 v180, v180, v181
	v_add_f32_e32 v182, v182, v183
	v_add_f32_e32 v180, v180, v182
	s_nop 1
	v_add_f32_dpp v180, v180, v180 quad_perm:[1,0,3,2] row_mask:0xf bank_mask:0xf
	s_nop 1
	v_add_f32_dpp v180, v180, v180 quad_perm:[2,3,0,1] row_mask:0xf bank_mask:0xf
	s_nop 1
	v_add_f32_dpp v180, v180, v180 row_half_mirror row_mask:0xf bank_mask:0xf
	s_nop 1
	v_add_f32_dpp v180, v180, v180 row_mirror row_mask:0xf bank_mask:0xf
	s_nop 1
	v_add_f32_dpp v180, v180, v180 row_bcast:15 row_mask:0xa bank_mask:0xf
	s_nop 1
	v_add_f32_dpp v180, v180, v180 row_bcast:31 row_mask:0xc bank_mask:0xf
	s_nop 0
	v_readlane_b32 s20, v180, 63
	s_nop 1
	v_mul_f32_e32 v184, s20, v2
	v_sub_f32_e32 v152, v152, v184
	v_sub_f32_e32 v153, v153, v184
	v_sub_f32_e32 v154, v154, v184
	v_sub_f32_e32 v155, v155, v184
	v_sub_f32_e32 v156, v156, v184
	v_sub_f32_e32 v157, v157, v184
	v_sub_f32_e32 v158, v158, v184
	v_sub_f32_e32 v159, v159, v184
	v_sub_f32_e32 v160, v160, v184
	v_sub_f32_e32 v161, v161, v184
	v_sub_f32_e32 v162, v162, v184
	v_sub_f32_e32 v163, v163, v184
	v_sub_f32_e32 v164, v164, v184
	v_sub_f32_e32 v165, v165, v184
	v_sub_f32_e32 v166, v166, v184
	v_sub_f32_e32 v167, v167, v184
	v_mul_f32_e32 v180, v152, v152
	v_mul_f32_e32 v181, v156, v156
	v_mul_f32_e32 v182, v160, v160
	v_mul_f32_e32 v183, v164, v164
	v_fmac_f32_e32 v180, v153, v153
	v_fmac_f32_e32 v181, v157, v157
	v_fmac_f32_e32 v182, v161, v161
	v_fmac_f32_e32 v183, v165, v165
	v_fmac_f32_e32 v180, v154, v154
	v_fmac_f32_e32 v181, v158, v158
	v_fmac_f32_e32 v182, v162, v162
	v_fmac_f32_e32 v183, v166, v166
	v_fmac_f32_e32 v180, v155, v155
	v_fmac_f32_e32 v181, v159, v159
	v_fmac_f32_e32 v182, v163, v163
	v_fmac_f32_e32 v183, v167, v167
	v_add_f32_e32 v180, v180, v181
	v_add_f32_e32 v182, v182, v183
	v_add_f32_e32 v180, v180, v182
	s_nop 1
	v_add_f32_dpp v180, v180, v180 quad_perm:[1,0,3,2] row_mask:0xf bank_mask:0xf
	s_nop 1
	v_add_f32_dpp v180, v180, v180 quad_perm:[2,3,0,1] row_mask:0xf bank_mask:0xf
	s_nop 1
	v_add_f32_dpp v180, v180, v180 row_half_mirror row_mask:0xf bank_mask:0xf
	s_nop 1
	v_add_f32_dpp v180, v180, v180 row_mirror row_mask:0xf bank_mask:0xf
	s_nop 1
	v_add_f32_dpp v180, v180, v180 row_bcast:15 row_mask:0xa bank_mask:0xf
	s_nop 1
	v_add_f32_dpp v180, v180, v180 row_bcast:31 row_mask:0xc bank_mask:0xf
	s_nop 0
	v_readlane_b32 s20, v180, 63
	s_nop 1
	v_mov_b32_e32 v185, s20
	v_fma_f32 v185, v185, v2, v4
	v_rsq_f32_e32 v185, v185
	s_nop 0
	v_mul_f32_e32 v152, v152, v185
	v_mul_f32_e32 v153, v153, v185
	v_mul_f32_e32 v154, v154, v185
	v_mul_f32_e32 v155, v155, v185
	v_mul_f32_e32 v156, v156, v185
	v_mul_f32_e32 v157, v157, v185
	v_mul_f32_e32 v158, v158, v185
	v_mul_f32_e32 v159, v159, v185
	v_mul_f32_e32 v160, v160, v185
	v_mul_f32_e32 v161, v161, v185
	v_mul_f32_e32 v162, v162, v185
	v_mul_f32_e32 v163, v163, v185
	v_mul_f32_e32 v164, v164, v185
	v_mul_f32_e32 v165, v165, v185
	v_mul_f32_e32 v166, v166, v185
	v_mul_f32_e32 v167, v167, v185
	v_fma_f32 v152, v152, v8, v24
	v_fma_f32 v153, v153, v9, v25
	v_fma_f32 v154, v154, v10, v26
	v_fma_f32 v155, v155, v11, v27
	v_fma_f32 v156, v156, v12, v28
	v_fma_f32 v157, v157, v13, v29
	v_fma_f32 v158, v158, v14, v30
	v_fma_f32 v159, v159, v15, v31
	v_fma_f32 v160, v160, v16, v32
	v_fma_f32 v161, v161, v17, v33
	v_fma_f32 v162, v162, v18, v34
	v_fma_f32 v163, v163, v19, v35
	v_fma_f32 v164, v164, v20, v36
	v_fma_f32 v165, v165, v21, v37
	v_fma_f32 v166, v166, v22, v38
	v_fma_f32 v167, v167, v23, v39
	v_cvt_pk_bf16_f32 v152, v152, v153
	v_cvt_pk_bf16_f32 v153, v154, v155
	v_cvt_pk_bf16_f32 v156, v156, v157
	v_cvt_pk_bf16_f32 v157, v158, v159
	v_cvt_pk_bf16_f32 v160, v160, v161
	v_cvt_pk_bf16_f32 v161, v162, v163
	v_cvt_pk_bf16_f32 v164, v164, v165
	v_cvt_pk_bf16_f32 v165, v166, v167
	v_add_u32_e32 v171, 0x1500000, v5
	global_store_dwordx2 v171, v[152:153], s[8:9]
	global_store_dwordx2 v171, v[156:157], s[8:9] offset:512
	global_store_dwordx2 v171, v[160:161], s[8:9] offset:1024
	global_store_dwordx2 v171, v[164:165], s[8:9] offset:1536
	v_mov_b32_e32 v172, 0x15000
	s_mov_b64 exec, 1
	global_store_dwordx2 v172, v[184:185], s[38:39]
	s_mov_b64 exec, -1
	s_waitcnt vmcnt(39)
	v_add_f32_e32 v180, v40, v41
	v_add_f32_e32 v181, v44, v45
	v_add_f32_e32 v182, v48, v49
	v_add_f32_e32 v183, v52, v53
	v_add_f32_e32 v180, v180, v42
	v_add_f32_e32 v181, v181, v46
	v_add_f32_e32 v182, v182, v50
	v_add_f32_e32 v183, v183, v54
	v_add_f32_e32 v180, v180, v43
	v_add_f32_e32 v181, v181, v47
	v_add_f32_e32 v182, v182, v51
	v_add_f32_e32 v183, v183, v55
	v_add_f32_e32 v180, v180, v181
	v_add_f32_e32 v182, v182, v183
	v_add_f32_e32 v180, v180, v182
	s_nop 1
	v_add_f32_dpp v180, v180, v180 quad_perm:[1,0,3,2] row_mask:0xf bank_mask:0xf
	s_nop 1
	v_add_f32_dpp v180, v180, v180 quad_perm:[2,3,0,1] row_mask:0xf bank_mask:0xf
	s_nop 1
	v_add_f32_dpp v180, v180, v180 row_half_mirror row_mask:0xf bank_mask:0xf
	s_nop 1
	v_add_f32_dpp v180, v180, v180 row_mirror row_mask:0xf bank_mask:0xf
	s_nop 1
	v_add_f32_dpp v180, v180, v180 row_bcast:15 row_mask:0xa bank_mask:0xf
	s_nop 1
	v_add_f32_dpp v180, v180, v180 row_bcast:31 row_mask:0xc bank_mask:0xf
	s_nop 0
	v_readlane_b32 s20, v180, 63
	s_nop 1
	v_mul_f32_e32 v184, s20, v2
	v_sub_f32_e32 v40, v40, v184
	v_sub_f32_e32 v41, v41, v184
	v_sub_f32_e32 v42, v42, v184
	v_sub_f32_e32 v43, v43, v184
	v_sub_f32_e32 v44, v44, v184
	v_sub_f32_e32 v45, v45, v184
	v_sub_f32_e32 v46, v46, v184
	v_sub_f32_e32 v47, v47, v184
	v_sub_f32_e32 v48, v48, v184
	v_sub_f32_e32 v49, v49, v184
	v_sub_f32_e32 v50, v50, v184
	v_sub_f32_e32 v51, v51, v184
	v_sub_f32_e32 v52, v52, v184
	v_sub_f32_e32 v53, v53, v184
	v_sub_f32_e32 v54, v54, v184
	v_sub_f32_e32 v55, v55, v184
	v_mul_f32_e32 v180, v40, v40
	v_mul_f32_e32 v181, v44, v44
	v_mul_f32_e32 v182, v48, v48
	v_mul_f32_e32 v183, v52, v52
	v_fmac_f32_e32 v180, v41, v41
	v_fmac_f32_e32 v181, v45, v45
	v_fmac_f32_e32 v182, v49, v49
	v_fmac_f32_e32 v183, v53, v53
	v_fmac_f32_e32 v180, v42, v42
	v_fmac_f32_e32 v181, v46, v46
	v_fmac_f32_e32 v182, v50, v50
	v_fmac_f32_e32 v183, v54, v54
	v_fmac_f32_e32 v180, v43, v43
	v_fmac_f32_e32 v181, v47, v47
	v_fmac_f32_e32 v182, v51, v51
	v_fmac_f32_e32 v183, v55, v55
	v_add_f32_e32 v180, v180, v181
	v_add_f32_e32 v182, v182, v183
	v_add_f32_e32 v180, v180, v182
	s_nop 1
	v_add_f32_dpp v180, v180, v180 quad_perm:[1,0,3,2] row_mask:0xf bank_mask:0xf
	s_nop 1
	v_add_f32_dpp v180, v180, v180 quad_perm:[2,3,0,1] row_mask:0xf bank_mask:0xf
	s_nop 1
	v_add_f32_dpp v180, v180, v180 row_half_mirror row_mask:0xf bank_mask:0xf
	s_nop 1
	v_add_f32_dpp v180, v180, v180 row_mirror row_mask:0xf bank_mask:0xf
	s_nop 1
	v_add_f32_dpp v180, v180, v180 row_bcast:15 row_mask:0xa bank_mask:0xf
	s_nop 1
	v_add_f32_dpp v180, v180, v180 row_bcast:31 row_mask:0xc bank_mask:0xf
	s_nop 0
	v_readlane_b32 s20, v180, 63
	s_nop 1
	v_mov_b32_e32 v185, s20
	v_fma_f32 v185, v185, v2, v4
	v_rsq_f32_e32 v185, v185
	s_nop 0
	v_mul_f32_e32 v40, v40, v185
	v_mul_f32_e32 v41, v41, v185
	v_mul_f32_e32 v42, v42, v185
	v_mul_f32_e32 v43, v43, v185
	v_mul_f32_e32 v44, v44, v185
	v_mul_f32_e32 v45, v45, v185
	v_mul_f32_e32 v46, v46, v185
	v_mul_f32_e32 v47, v47, v185
	v_mul_f32_e32 v48, v48, v185
	v_mul_f32_e32 v49, v49, v185
	v_mul_f32_e32 v50, v50, v185
	v_mul_f32_e32 v51, v51, v185
	v_mul_f32_e32 v52, v52, v185
	v_mul_f32_e32 v53, v53, v185
	v_mul_f32_e32 v54, v54, v185
	v_mul_f32_e32 v55, v55, v185
	v_fma_f32 v40, v40, v8, v24
	v_fma_f32 v41, v41, v9, v25
	v_fma_f32 v42, v42, v10, v26
	v_fma_f32 v43, v43, v11, v27
	v_fma_f32 v44, v44, v12, v28
	v_fma_f32 v45, v45, v13, v29
	v_fma_f32 v46, v46, v14, v30
	v_fma_f32 v47, v47, v15, v31
	v_fma_f32 v48, v48, v16, v32
	v_fma_f32 v49, v49, v17, v33
	v_fma_f32 v50, v50, v18, v34
	v_fma_f32 v51, v51, v19, v35
	v_fma_f32 v52, v52, v20, v36
	v_fma_f32 v53, v53, v21, v37
	v_fma_f32 v54, v54, v22, v38
	v_fma_f32 v55, v55, v23, v39
	v_cvt_pk_bf16_f32 v40, v40, v41
	v_cvt_pk_bf16_f32 v41, v42, v43
	v_cvt_pk_bf16_f32 v44, v44, v45
	v_cvt_pk_bf16_f32 v45, v46, v47
	v_cvt_pk_bf16_f32 v48, v48, v49
	v_cvt_pk_bf16_f32 v49, v50, v51
	v_cvt_pk_bf16_f32 v52, v52, v53
	v_cvt_pk_bf16_f32 v53, v54, v55
	v_add_u32_e32 v171, 0x1800000, v5
	global_store_dwordx2 v171, v[40:41], s[8:9]
	global_store_dwordx2 v171, v[44:45], s[8:9] offset:512
	global_store_dwordx2 v171, v[48:49], s[8:9] offset:1024
	global_store_dwordx2 v171, v[52:53], s[8:9] offset:1536
	v_mov_b32_e32 v172, 0x18000
	s_mov_b64 exec, 1
	global_store_dwordx2 v172, v[184:185], s[38:39]
	s_mov_b64 exec, -1
	s_waitcnt vmcnt(35)
	v_add_f32_e32 v180, v56, v57
	v_add_f32_e32 v181, v60, v61
	v_add_f32_e32 v182, v64, v65
	v_add_f32_e32 v183, v68, v69
	v_add_f32_e32 v180, v180, v58
	v_add_f32_e32 v181, v181, v62
	v_add_f32_e32 v182, v182, v66
	v_add_f32_e32 v183, v183, v70
	v_add_f32_e32 v180, v180, v59
	v_add_f32_e32 v181, v181, v63
	v_add_f32_e32 v182, v182, v67
	v_add_f32_e32 v183, v183, v71
	v_add_f32_e32 v180, v180, v181
	v_add_f32_e32 v182, v182, v183
	v_add_f32_e32 v180, v180, v182
	s_nop 1
	v_add_f32_dpp v180, v180, v180 quad_perm:[1,0,3,2] row_mask:0xf bank_mask:0xf
	s_nop 1
	v_add_f32_dpp v180, v180, v180 quad_perm:[2,3,0,1] row_mask:0xf bank_mask:0xf
	s_nop 1
	v_add_f32_dpp v180, v180, v180 row_half_mirror row_mask:0xf bank_mask:0xf
	s_nop 1
	v_add_f32_dpp v180, v180, v180 row_mirror row_mask:0xf bank_mask:0xf
	s_nop 1
	v_add_f32_dpp v180, v180, v180 row_bcast:15 row_mask:0xa bank_mask:0xf
	s_nop 1
	v_add_f32_dpp v180, v180, v180 row_bcast:31 row_mask:0xc bank_mask:0xf
	s_nop 0
	v_readlane_b32 s20, v180, 63
	s_nop 1
	v_mul_f32_e32 v184, s20, v2
	v_sub_f32_e32 v56, v56, v184
	v_sub_f32_e32 v57, v57, v184
	v_sub_f32_e32 v58, v58, v184
	v_sub_f32_e32 v59, v59, v184
	v_sub_f32_e32 v60, v60, v184
	v_sub_f32_e32 v61, v61, v184
	v_sub_f32_e32 v62, v62, v184
	v_sub_f32_e32 v63, v63, v184
	v_sub_f32_e32 v64, v64, v184
	v_sub_f32_e32 v65, v65, v184
	v_sub_f32_e32 v66, v66, v184
	v_sub_f32_e32 v67, v67, v184
	v_sub_f32_e32 v68, v68, v184
	v_sub_f32_e32 v69, v69, v184
	v_sub_f32_e32 v70, v70, v184
	v_sub_f32_e32 v71, v71, v184
	v_mul_f32_e32 v180, v56, v56
	v_mul_f32_e32 v181, v60, v60
	v_mul_f32_e32 v182, v64, v64
	v_mul_f32_e32 v183, v68, v68
	v_fmac_f32_e32 v180, v57, v57
	v_fmac_f32_e32 v181, v61, v61
	v_fmac_f32_e32 v182, v65, v65
	v_fmac_f32_e32 v183, v69, v69
	v_fmac_f32_e32 v180, v58, v58
	v_fmac_f32_e32 v181, v62, v62
	v_fmac_f32_e32 v182, v66, v66
	v_fmac_f32_e32 v183, v70, v70
	v_fmac_f32_e32 v180, v59, v59
	v_fmac_f32_e32 v181, v63, v63
	v_fmac_f32_e32 v182, v67, v67
	v_fmac_f32_e32 v183, v71, v71
	v_add_f32_e32 v180, v180, v181
	v_add_f32_e32 v182, v182, v183
	v_add_f32_e32 v180, v180, v182
	s_nop 1
	v_add_f32_dpp v180, v180, v180 quad_perm:[1,0,3,2] row_mask:0xf bank_mask:0xf
	s_nop 1
	v_add_f32_dpp v180, v180, v180 quad_perm:[2,3,0,1] row_mask:0xf bank_mask:0xf
	s_nop 1
	v_add_f32_dpp v180, v180, v180 row_half_mirror row_mask:0xf bank_mask:0xf
	s_nop 1
	v_add_f32_dpp v180, v180, v180 row_mirror row_mask:0xf bank_mask:0xf
	s_nop 1
	v_add_f32_dpp v180, v180, v180 row_bcast:15 row_mask:0xa bank_mask:0xf
	s_nop 1
	v_add_f32_dpp v180, v180, v180 row_bcast:31 row_mask:0xc bank_mask:0xf
	s_nop 0
	v_readlane_b32 s20, v180, 63
	s_nop 1
	v_mov_b32_e32 v185, s20
	v_fma_f32 v185, v185, v2, v4
	v_rsq_f32_e32 v185, v185
	s_nop 0
	v_mul_f32_e32 v56, v56, v185
	v_mul_f32_e32 v57, v57, v185
	v_mul_f32_e32 v58, v58, v185
	v_mul_f32_e32 v59, v59, v185
	v_mul_f32_e32 v60, v60, v185
	v_mul_f32_e32 v61, v61, v185
	v_mul_f32_e32 v62, v62, v185
	v_mul_f32_e32 v63, v63, v185
	v_mul_f32_e32 v64, v64, v185
	v_mul_f32_e32 v65, v65, v185
	v_mul_f32_e32 v66, v66, v185
	v_mul_f32_e32 v67, v67, v185
	v_mul_f32_e32 v68, v68, v185
	v_mul_f32_e32 v69, v69, v185
	v_mul_f32_e32 v70, v70, v185
	v_mul_f32_e32 v71, v71, v185
	v_fma_f32 v56, v56, v8, v24
	v_fma_f32 v57, v57, v9, v25
	v_fma_f32 v58, v58, v10, v26
	v_fma_f32 v59, v59, v11, v27
	v_fma_f32 v60, v60, v12, v28
	v_fma_f32 v61, v61, v13, v29
	v_fma_f32 v62, v62, v14, v30
	v_fma_f32 v63, v63, v15, v31
	v_fma_f32 v64, v64, v16, v32
	v_fma_f32 v65, v65, v17, v33
	v_fma_f32 v66, v66, v18, v34
	v_fma_f32 v67, v67, v19, v35
	v_fma_f32 v68, v68, v20, v36
	v_fma_f32 v69, v69, v21, v37
	v_fma_f32 v70, v70, v22, v38
	v_fma_f32 v71, v71, v23, v39
	v_cvt_pk_bf16_f32 v56, v56, v57
	v_cvt_pk_bf16_f32 v57, v58, v59
	v_cvt_pk_bf16_f32 v60, v60, v61
	v_cvt_pk_bf16_f32 v61, v62, v63
	v_cvt_pk_bf16_f32 v64, v64, v65
	v_cvt_pk_bf16_f32 v65, v66, v67
	v_cvt_pk_bf16_f32 v68, v68, v69
	v_cvt_pk_bf16_f32 v69, v70, v71
	v_add_u32_e32 v171, 0x1b00000, v5
	global_store_dwordx2 v171, v[56:57], s[8:9]
	global_store_dwordx2 v171, v[60:61], s[8:9] offset:512
	global_store_dwordx2 v171, v[64:65], s[8:9] offset:1024
	global_store_dwordx2 v171, v[68:69], s[8:9] offset:1536
	v_mov_b32_e32 v172, 0x1b000
	s_mov_b64 exec, 1
	global_store_dwordx2 v172, v[184:185], s[38:39]
	s_mov_b64 exec, -1
	s_branch .LBB0_188
.Lln_generic:
	s_branch .LBB0_179

.LBB0_745:
	s_or_b64 exec, exec, s[0:1]
	s_mov_b64 s[4:5], s[88:89]
	s_waitcnt lgkmcnt(0)
	s_barrier
	s_cmpk_lg_u32 s56, 0x100
	s_cbranch_scc1 .Llo_generic
	s_load_dwordx2 s[6:7], s[4:5], 0xa0
	s_load_dwordx4 s[40:43], s[4:5], 0x90
	v_mbcnt_lo_u32_b32 v0, -1, 0
	v_mbcnt_hi_u32_b32 v0, -1, v0
	v_lshlrev_b32_e32 v1, 4, v0
	s_lshr_b32 s0, s29, 6
	s_lshl_b32 s96, s92, 24
	s_lshl_b64 s[8:9], s[96:97], 2
	v_mov_b32_e32 v2, 0x3a800000
	v_mov_b32_e32 v4, 0x3727c5ac
	s_waitcnt lgkmcnt(0)
	s_add_u32 s4, s6, s8
	s_addc_u32 s5, s7, s9
	s_cmp_lt_u32 s86, 64
	s_cbranch_scc1 .Llo_small
	s_sub_u32 s1, s86, 64
	s_lshl_b32 s1, s1, 3
	s_add_i32 s0, s0, s1
	s_mul_i32 s0, s0, 0xa000
	s_add_u32 s0, s0, 0x400000
	s_add_u32 s4, s4, s0
	s_addc_u32 s5, s5, 0
	global_load_dwordx4 v[40:43], v1, s[4:5]
	global_load_dwordx4 v[44:47], v1, s[4:5] offset:1024
	global_load_dwordx4 v[48:51], v1, s[4:5] offset:2048
	global_load_dwordx4 v[52:55], v1, s[4:5] offset:3072
	global_load_dwordx4 v[8:11], v1, s[40:41]
	global_load_dwordx4 v[12:15], v1, s[40:41] offset:1024
	global_load_dwordx4 v[16:19], v1, s[40:41] offset:2048
	global_load_dwordx4 v[20:23], v1, s[40:41] offset:3072
	global_load_dwordx4 v[24:27], v1, s[42:43]
	global_load_dwordx4 v[28:31], v1, s[42:43] offset:1024
	global_load_dwordx4 v[32:35], v1, s[42:43] offset:2048
	global_load_dwordx4 v[36:39], v1, s[42:43] offset:3072
	v_add_u32_e32 v170, 0x1000, v1
	global_load_dwordx4 v[56:59], v170, s[4:5]
	global_load_dwordx4 v[60:63], v170, s[4:5] offset:1024
	global_load_dwordx4 v[64:67], v170, s[4:5] offset:2048
	global_load_dwordx4 v[68:71], v170, s[4:5] offset:3072
	v_add_u32_e32 v170, 0x2000, v1
	global_load_dwordx4 v[72:75], v170, s[4:5]
	global_load_dwordx4 v[76:79], v170, s[4:5] offset:1024
	global_load_dwordx4 v[80:83], v170, s[4:5] offset:2048
	global_load_dwordx4 v[84:87], v170, s[4:5] offset:3072
	v_add_u32_e32 v170, 0x3000, v1
	global_load_dwordx4 v[88:91], v170, s[4:5]
	global_load_dwordx4 v[92:95], v170, s[4:5] offset:1024
	global_load_dwordx4 v[96:99], v170, s[4:5] offset:2048
	global_load_dwordx4 v[100:103], v170, s[4:5] offset:3072
	v_add_u32_e32 v170, 0x4000, v1
	global_load_dwordx4 v[104:107], v170, s[4:5]
	global_load_dwordx4 v[108:111], v170, s[4:5] offset:1024
	global_load_dwordx4 v[112:115], v170, s[4:5] offset:2048
	global_load_dwordx4 v[116:119], v170, s[4:5] offset:3072
	v_add_u32_e32 v170, 0x5000, v1
	global_load_dwordx4 v[120:123], v170, s[4:5]
	global_load_dwordx4 v[124:127], v170, s[4:5] offset:1024
	global_load_dwordx4 v[128:131], v170, s[4:5] offset:2048
	global_load_dwordx4 v[132:135], v170, s[4:5] offset:3072
	v_add_u32_e32 v170, 0x6000, v1
	global_load_dwordx4 v[136:139], v170, s[4:5]
	global_load_dwordx4 v[140:143], v170, s[4:5] offset:1024
	global_load_dwordx4 v[144:147], v170, s[4:5] offset:2048
	global_load_dwordx4 v[148:151], v170, s[4:5] offset:3072
	v_add_u32_e32 v170, 0x7000, v1
	global_load_dwordx4 v[152:155], v170, s[4:5]
	global_load_dwordx4 v[156:159], v170, s[4:5] offset:1024
	global_load_dwordx4 v[160:163], v170, s[4:5] offset:2048
	global_load_dwordx4 v[164:167], v170, s[4:5] offset:3072
	s_waitcnt vmcnt(36)
	v_add_f32_e32 v180, v40, v41
	v_add_f32_e32 v181, v44, v45
	v_add_f32_e32 v182, v48, v49
	v_add_f32_e32 v183, v52, v53
	v_add_f32_e32 v180, v180, v42
	v_add_f32_e32 v181, v181, v46
	v_add_f32_e32 v182, v182, v50
	v_add_f32_e32 v183, v183, v54
	v_add_f32_e32 v180, v180, v43
	v_add_f32_e32 v181, v181, v47
	v_add_f32_e32 v182, v182, v51
	v_add_f32_e32 v183, v183, v55
	v_add_f32_e32 v180, v180, v181
	v_add_f32_e32 v182, v182, v183
	v_add_f32_e32 v180, v180, v182
	s_nop 1
	v_add_f32_dpp v180, v180, v180 quad_perm:[1,0,3,2] row_mask:0xf bank_mask:0xf
	s_nop 1
	v_add_f32_dpp v180, v180, v180 quad_perm:[2,3,0,1] row_mask:0xf bank_mask:0xf
	s_nop 1
	v_add_f32_dpp v180, v180, v180 row_half_mirror row_mask:0xf bank_mask:0xf
	s_nop 1
	v_add_f32_dpp v180, v180, v180 row_mirror row_mask:0xf bank_mask:0xf
	s_nop 1
	v_add_f32_dpp v180, v180, v180 row_bcast:15 row_mask:0xa bank_mask:0xf
	s_nop 1
	v_add_f32_dpp v180, v180, v180 row_bcast:31 row_mask:0xc bank_mask:0xf
	s_nop 0
	v_readlane_b32 s20, v180, 63
	s_nop 1
	v_mul_f32_e32 v184, s20, v2
	v_sub_f32_e32 v40, v40, v184
	v_sub_f32_e32 v41, v41, v184
	v_sub_f32_e32 v42, v42, v184
	v_sub_f32_e32 v43, v43, v184
	v_sub_f32_e32 v44, v44, v184
	v_sub_f32_e32 v45, v45, v184
	v_sub_f32_e32 v46, v46, v184
	v_sub_f32_e32 v47, v47, v184
	v_sub_f32_e32 v48, v48, v184
	v_sub_f32_e32 v49, v49, v184
	v_sub_f32_e32 v50, v50, v184
	v_sub_f32_e32 v51, v51, v184
	v_sub_f32_e32 v52, v52, v184
	v_sub_f32_e32 v53, v53, v184
	v_sub_f32_e32 v54, v54, v184
	v_sub_f32_e32 v55, v55, v184
	v_mul_f32_e32 v180, v40, v40
	v_mul_f32_e32 v181, v44, v44
	v_mul_f32_e32 v182, v48, v48
	v_mul_f32_e32 v183, v52, v52
	v_fmac_f32_e32 v180, v41, v41
	v_fmac_f32_e32 v181, v45, v45
	v_fmac_f32_e32 v182, v49, v49
	v_fmac_f32_e32 v183, v53, v53
	v_fmac_f32_e32 v180, v42, v42
	v_fmac_f32_e32 v181, v46, v46
	v_fmac_f32_e32 v182, v50, v50
	v_fmac_f32_e32 v183, v54, v54
	v_fmac_f32_e32 v180, v43, v43
	v_fmac_f32_e32 v181, v47, v47
	v_fmac_f32_e32 v182, v51, v51
	v_fmac_f32_e32 v183, v55, v55
	v_add_f32_e32 v180, v180, v181
	v_add_f32_e32 v182, v182, v183
	v_add_f32_e32 v180, v180, v182
	s_nop 1
	v_add_f32_dpp v180, v180, v180 quad_perm:[1,0,3,2] row_mask:0xf bank_mask:0xf
	s_nop 1
	v_add_f32_dpp v180, v180, v180 quad_perm:[2,3,0,1] row_mask:0xf bank_mask:0xf
	s_nop 1
	v_add_f32_dpp v180, v180, v180 row_half_mirror row_mask:0xf bank_mask:0xf
	s_nop 1
	v_add_f32_dpp v180, v180, v180 row_mirror row_mask:0xf bank_mask:0xf
	s_nop 1
	v_add_f32_dpp v180, v180, v180 row_bcast:15 row_mask:0xa bank_mask:0xf
	s_nop 1
	v_add_f32_dpp v180, v180, v180 row_bcast:31 row_mask:0xc bank_mask:0xf
	s_nop 0
	v_readlane_b32 s20, v180, 63
	s_nop 1
	v_mov_b32_e32 v185, s20
	v_fma_f32 v185, v185, v2, v4
	v_rsq_f32_e32 v185, v185
	s_nop 0
	v_mul_f32_e32 v40, v40, v185
	v_mul_f32_e32 v41, v41, v185
	v_mul_f32_e32 v42, v42, v185
	v_mul_f32_e32 v43, v43, v185
	v_mul_f32_e32 v44, v44, v185
	v_mul_f32_e32 v45, v45, v185
	v_mul_f32_e32 v46, v46, v185
	v_mul_f32_e32 v47, v47, v185
	v_mul_f32_e32 v48, v48, v185
	v_mul_f32_e32 v49, v49, v185
	v_mul_f32_e32 v50, v50, v185
	v_mul_f32_e32 v51, v51, v185
	v_mul_f32_e32 v52, v52, v185
	v_mul_f32_e32 v53, v53, v185
	v_mul_f32_e32 v54, v54, v185
	v_mul_f32_e32 v55, v55, v185
	s_waitcnt vmcnt(28)
	v_fma_f32 v40, v40, v8, v24
	v_fma_f32 v41, v41, v9, v25
	v_fma_f32 v42, v42, v10, v26
	v_fma_f32 v43, v43, v11, v27
	v_fma_f32 v44, v44, v12, v28
	v_fma_f32 v45, v45, v13, v29
	v_fma_f32 v46, v46, v14, v30
	v_fma_f32 v47, v47, v15, v31
	v_fma_f32 v48, v48, v16, v32
	v_fma_f32 v49, v49, v17, v33
	v_fma_f32 v50, v50, v18, v34
	v_fma_f32 v51, v51, v19, v35
	v_fma_f32 v52, v52, v20, v36
	v_fma_f32 v53, v53, v21, v37
	v_fma_f32 v54, v54, v22, v38
	v_fma_f32 v55, v55, v23, v39
	global_store_dwordx4 v1, v[40:43], s[4:5]
	global_store_dwordx4 v1, v[44:47], s[4:5] offset:1024
	global_store_dwordx4 v1, v[48:51], s[4:5] offset:2048
	global_store_dwordx4 v1, v[52:55], s[4:5] offset:3072
	s_nop 1
	v_add_u32_e32 v170, 0x8000, v1
	global_load_dwordx4 v[40:43], v170, s[4:5]
	global_load_dwordx4 v[44:47], v170, s[4:5] offset:1024
	global_load_dwordx4 v[48:51], v170, s[4:5] offset:2048
	global_load_dwordx4 v[52:55], v170, s[4:5] offset:3072
	s_waitcnt vmcnt(32)
	v_add_f32_e32 v180, v56, v57
	v_add_f32_e32 v181, v60, v61
	v_add_f32_e32 v182, v64, v65
	v_add_f32_e32 v183, v68, v69
	v_add_f32_e32 v180, v180, v58
	v_add_f32_e32 v181, v181, v62
	v_add_f32_e32 v182, v182, v66
	v_add_f32_e32 v183, v183, v70
	v_add_f32_e32 v180, v180, v59
	v_add_f32_e32 v181, v181, v63
	v_add_f32_e32 v182, v182, v67
	v_add_f32_e32 v183, v183, v71
	v_add_f32_e32 v180, v180, v181
	v_add_f32_e32 v182, v182, v183
	v_add_f32_e32 v180, v180, v182
	s_nop 1
	v_add_f32_dpp v180, v180, v180 quad_perm:[1,0,3,2] row_mask:0xf bank_mask:0xf
	s_nop 1
	v_add_f32_dpp v180, v180, v180 quad_perm:[2,3,0,1] row_mask:0xf bank_mask:0xf
	s_nop 1
	v_add_f32_dpp v180, v180, v180 row_half_mirror row_mask:0xf bank_mask:0xf
	s_nop 1
	v_add_f32_dpp v180, v180, v180 row_mirror row_mask:0xf bank_mask:0xf
	s_nop 1
	v_add_f32_dpp v180, v180, v180 row_bcast:15 row_mask:0xa bank_mask:0xf
	s_nop 1
	v_add_f32_dpp v180, v180, v180 row_bcast:31 row_mask:0xc bank_mask:0xf
	s_nop 0
	v_readlane_b32 s20, v180, 63
	s_nop 1
	v_mul_f32_e32 v184, s20, v2
	v_sub_f32_e32 v56, v56, v184
	v_sub_f32_e32 v57, v57, v184
	v_sub_f32_e32 v58, v58, v184
	v_sub_f32_e32 v59, v59, v184
	v_sub_f32_e32 v60, v60, v184
	v_sub_f32_e32 v61, v61, v184
	v_sub_f32_e32 v62, v62, v184
	v_sub_f32_e32 v63, v63, v184
	v_sub_f32_e32 v64, v64, v184
	v_sub_f32_e32 v65, v65, v184
	v_sub_f32_e32 v66, v66, v184
	v_sub_f32_e32 v67, v67, v184
	v_sub_f32_e32 v68, v68, v184
	v_sub_f32_e32 v69, v69, v184
	v_sub_f32_e32 v70, v70, v184
	v_sub_f32_e32 v71, v71, v184
	v_mul_f32_e32 v180, v56, v56
	v_mul_f32_e32 v181, v60, v60
	v_mul_f32_e32 v182, v64, v64
	v_mul_f32_e32 v183, v68, v68
	v_fmac_f32_e32 v180, v57, v57
	v_fmac_f32_e32 v181, v61, v61
	v_fmac_f32_e32 v182, v65, v65
	v_fmac_f32_e32 v183, v69, v69
	v_fmac_f32_e32 v180, v58, v58
	v_fmac_f32_e32 v181, v62, v62
	v_fmac_f32_e32 v182, v66, v66
	v_fmac_f32_e32 v183, v70, v70
	v_fmac_f32_e32 v180, v59, v59
	v_fmac_f32_e32 v181, v63, v63
	v_fmac_f32_e32 v182, v67, v67
	v_fmac_f32_e32 v183, v71, v71
	v_add_f32_e32 v180, v180, v181
	v_add_f32_e32 v182, v182, v183
	v_add_f32_e32 v180, v180, v182
	s_nop 1
	v_add_f32_dpp v180, v180, v180 quad_perm:[1,0,3,2] row_mask:0xf bank_mask:0xf
	s_nop 1
	v_add_f32_dpp v180, v180, v180 quad_perm:[2,3,0,1] row_mask:0xf bank_mask:0xf
	s_nop 1
	v_add_f32_dpp v180, v180, v180 row_half_mirror row_mask:0xf bank_mask:0xf
	s_nop 1
	v_add_f32_dpp v180, v180, v180 row_mirror row_mask:0xf bank_mask:0xf
	s_nop 1
	v_add_f32_dpp v180, v180, v180 row_bcast:15 row_mask:0xa bank_mask:0xf
	s_nop 1
	v_add_f32_dpp v180, v180, v180 row_bcast:31 row_mask:0xc bank_mask:0xf
	s_nop 0
	v_readlane_b32 s20, v180, 63
	s_nop 1
	v_mov_b32_e32 v185, s20
	v_fma_f32 v185, v185, v2, v4
	v_rsq_f32_e32 v185, v185
	s_nop 0
	v_mul_f32_e32 v56, v56, v185
	v_mul_f32_e32 v57, v57, v185
	v_mul_f32_e32 v58, v58, v185
	v_mul_f32_e32 v59, v59, v185
	v_mul_f32_e32 v60, v60, v185
	v_mul_f32_e32 v61, v61, v185
	v_mul_f32_e32 v62, v62, v185
	v_mul_f32_e32 v63, v63, v185
	v_mul_f32_e32 v64, v64, v185
	v_mul_f32_e32 v65, v65, v185
	v_mul_f32_e32 v66, v66, v185
	v_mul_f32_e32 v67, v67, v185
	v_mul_f32_e32 v68, v68, v185
	v_mul_f32_e32 v69, v69, v185
	v_mul_f32_e32 v70, v70, v185
	v_mul_f32_e32 v71, v71, v185
	v_fma_f32 v56, v56, v8, v24
	v_fma_f32 v57, v57, v9, v25
	v_fma_f32 v58, v58, v10, v26
	v_fma_f32 v59, v59, v11, v27
	v_fma_f32 v60, v60, v12, v28
	v_fma_f32 v61, v61, v13, v29
	v_fma_f32 v62, v62, v14, v30
	v_fma_f32 v63, v63, v15, v31
	v_fma_f32 v64, v64, v16, v32
	v_fma_f32 v65, v65, v17, v33
	v_fma_f32 v66, v66, v18, v34
	v_fma_f32 v67, v67, v19, v35
	v_fma_f32 v68, v68, v20, v36
	v_fma_f32 v69, v69, v21, v37
	v_fma_f32 v70, v70, v22, v38
	v_fma_f32 v71, v71, v23, v39
	v_add_u32_e32 v171, 0x1000, v1
	global_store_dwordx4 v171, v[56:59], s[4:5]
	global_store_dwordx4 v171, v[60:63], s[4:5] offset:1024
	global_store_dwordx4 v171, v[64:67], s[4:5] offset:2048
	global_store_dwordx4 v171, v[68:71], s[4:5] offset:3072
	s_nop 1
	v_add_u32_e32 v170, 0x9000, v1
	global_load_dwordx4 v[56:59], v170, s[4:5]
	global_load_dwordx4 v[60:63], v170, s[4:5] offset:1024
	global_load_dwordx4 v[64:67], v170, s[4:5] offset:2048
	global_load_dwordx4 v[68:71], v170, s[4:5] offset:3072
	s_waitcnt vmcnt(36)
	v_add_f32_e32 v180, v72, v73
	v_add_f32_e32 v181, v76, v77
	v_add_f32_e32 v182, v80, v81
	v_add_f32_e32 v183, v84, v85
	v_add_f32_e32 v180, v180, v74
	v_add_f32_e32 v181, v181, v78
	v_add_f32_e32 v182, v182, v82
	v_add_f32_e32 v183, v183, v86
	v_add_f32_e32 v180, v180, v75
	v_add_f32_e32 v181, v181, v79
	v_add_f32_e32 v182, v182, v83
	v_add_f32_e32 v183, v183, v87
	v_add_f32_e32 v180, v180, v181
	v_add_f32_e32 v182, v182, v183
	v_add_f32_e32 v180, v180, v182
	s_nop 1
	v_add_f32_dpp v180, v180, v180 quad_perm:[1,0,3,2] row_mask:0xf bank_mask:0xf
	s_nop 1
	v_add_f32_dpp v180, v180, v180 quad_perm:[2,3,0,1] row_mask:0xf bank_mask:0xf
	s_nop 1
	v_add_f32_dpp v180, v180, v180 row_half_mirror row_mask:0xf bank_mask:0xf
	s_nop 1
	v_add_f32_dpp v180, v180, v180 row_mirror row_mask:0xf bank_mask:0xf
	s_nop 1
	v_add_f32_dpp v180, v180, v180 row_bcast:15 row_mask:0xa bank_mask:0xf
	s_nop 1
	v_add_f32_dpp v180, v180, v180 row_bcast:31 row_mask:0xc bank_mask:0xf
	s_nop 0
	v_readlane_b32 s20, v180, 63
	s_nop 1
	v_mul_f32_e32 v184, s20, v2
	v_sub_f32_e32 v72, v72, v184
	v_sub_f32_e32 v73, v73, v184
	v_sub_f32_e32 v74, v74, v184
	v_sub_f32_e32 v75, v75, v184
	v_sub_f32_e32 v76, v76, v184
	v_sub_f32_e32 v77, v77, v184
	v_sub_f32_e32 v78, v78, v184
	v_sub_f32_e32 v79, v79, v184
	v_sub_f32_e32 v80, v80, v184
	v_sub_f32_e32 v81, v81, v184
	v_sub_f32_e32 v82, v82, v184
	v_sub_f32_e32 v83, v83, v184
	v_sub_f32_e32 v84, v84, v184
	v_sub_f32_e32 v85, v85, v184
	v_sub_f32_e32 v86, v86, v184
	v_sub_f32_e32 v87, v87, v184
	v_mul_f32_e32 v180, v72, v72
	v_mul_f32_e32 v181, v76, v76
	v_mul_f32_e32 v182, v80, v80
	v_mul_f32_e32 v183, v84, v84
	v_fmac_f32_e32 v180, v73, v73
	v_fmac_f32_e32 v181, v77, v77
	v_fmac_f32_e32 v182, v81, v81
	v_fmac_f32_e32 v183, v85, v85
	v_fmac_f32_e32 v180, v74, v74
	v_fmac_f32_e32 v181, v78, v78
	v_fmac_f32_e32 v182, v82, v82
	v_fmac_f32_e32 v183, v86, v86
	v_fmac_f32_e32 v180, v75, v75
	v_fmac_f32_e32 v181, v79, v79
	v_fmac_f32_e32 v182, v83, v83
	v_fmac_f32_e32 v183, v87, v87
	v_add_f32_e32 v180, v180, v181
	v_add_f32_e32 v182, v182, v183
	v_add_f32_e32 v180, v180, v182
	s_nop 1
	v_add_f32_dpp v180, v180, v180 quad_perm:[1,0,3,2] row_mask:0xf bank_mask:0xf
	s_nop 1
	v_add_f32_dpp v180, v180, v180 quad_perm:[2,3,0,1] row_mask:0xf bank_mask:0xf
	s_nop 1
	v_add_f32_dpp v180, v180, v180 row_half_mirror row_mask:0xf bank_mask:0xf
	s_nop 1
	v_add_f32_dpp v180, v180, v180 row_mirror row_mask:0xf bank_mask:0xf
	s_nop 1
	v_add_f32_dpp v180, v180, v180 row_bcast:15 row_mask:0xa bank_mask:0xf
	s_nop 1
	v_add_f32_dpp v180, v180, v180 row_bcast:31 row_mask:0xc bank_mask:0xf
	s_nop 0
	v_readlane_b32 s20, v180, 63
	s_nop 1
	v_mov_b32_e32 v185, s20
	v_fma_f32 v185, v185, v2, v4
	v_rsq_f32_e32 v185, v185
	s_nop 0
	v_mul_f32_e32 v72, v72, v185
	v_mul_f32_e32 v73, v73, v185
	v_mul_f32_e32 v74, v74, v185
	v_mul_f32_e32 v75, v75, v185
	v_mul_f32_e32 v76, v76, v185
	v_mul_f32_e32 v77, v77, v185
	v_mul_f32_e32 v78, v78, v185
	v_mul_f32_e32 v79, v79, v185
	v_mul_f32_e32 v80, v80, v185
	v_mul_f32_e32 v81, v81, v185
	v_mul_f32_e32 v82, v82, v185
	v_mul_f32_e32 v83, v83, v185
	v_mul_f32_e32 v84, v84, v185
	v_mul_f32_e32 v85, v85, v185
	v_mul_f32_e32 v86, v86, v185
	v_mul_f32_e32 v87, v87, v185
	v_fma_f32 v72, v72, v8, v24
	v_fma_f32 v73, v73, v9, v25
	v_fma_f32 v74, v74, v10, v26
	v_fma_f32 v75, v75, v11, v27
	v_fma_f32 v76, v76, v12, v28
	v_fma_f32 v77, v77, v13, v29
	v_fma_f32 v78, v78, v14, v30
	v_fma_f32 v79, v79, v15, v31
	v_fma_f32 v80, v80, v16, v32
	v_fma_f32 v81, v81, v17, v33
	v_fma_f32 v82, v82, v18, v34
	v_fma_f32 v83, v83, v19, v35
	v_fma_f32 v84, v84, v20, v36
	v_fma_f32 v85, v85, v21, v37
	v_fma_f32 v86, v86, v22, v38
	v_fma_f32 v87, v87, v23, v39
	v_add_u32_e32 v171, 0x2000, v1
	global_store_dwordx4 v171, v[72:75], s[4:5]
	global_store_dwordx4 v171, v[76:79], s[4:5] offset:1024
	global_store_dwordx4 v171, v[80:83], s[4:5] offset:2048
	global_store_dwordx4 v171, v[84:87], s[4:5] offset:3072
	s_waitcnt vmcnt(36)
	v_add_f32_e32 v180, v88, v89
	v_add_f32_e32 v181, v92, v93
	v_add_f32_e32 v182, v96, v97
	v_add_f32_e32 v183, v100, v101
	v_add_f32_e32 v180, v180, v90
	v_add_f32_e32 v181, v181, v94
	v_add_f32_e32 v182, v182, v98
	v_add_f32_e32 v183, v183, v102
	v_add_f32_e32 v180, v180, v91
	v_add_f32_e32 v181, v181, v95
	v_add_f32_e32 v182, v182, v99
	v_add_f32_e32 v183, v183, v103
	v_add_f32_e32 v180, v180, v181
	v_add_f32_e32 v182, v182, v183
	v_add_f32_e32 v180, v180, v182
	s_nop 1
	v_add_f32_dpp v180, v180, v180 quad_perm:[1,0,3,2] row_mask:0xf bank_mask:0xf
	s_nop 1
	v_add_f32_dpp v180, v180, v180 quad_perm:[2,3,0,1] row_mask:0xf bank_mask:0xf
	s_nop 1
	v_add_f32_dpp v180, v180, v180 row_half_mirror row_mask:0xf bank_mask:0xf
	s_nop 1
	v_add_f32_dpp v180, v180, v180 row_mirror row_mask:0xf bank_mask:0xf
	s_nop 1
	v_add_f32_dpp v180, v180, v180 row_bcast:15 row_mask:0xa bank_mask:0xf
	s_nop 1
	v_add_f32_dpp v180, v180, v180 row_bcast:31 row_mask:0xc bank_mask:0xf
	s_nop 0
	v_readlane_b32 s20, v180, 63
	s_nop 1
	v_mul_f32_e32 v184, s20, v2
	v_sub_f32_e32 v88, v88, v184
	v_sub_f32_e32 v89, v89, v184
	v_sub_f32_e32 v90, v90, v184
	v_sub_f32_e32 v91, v91, v184
	v_sub_f32_e32 v92, v92, v184
	v_sub_f32_e32 v93, v93, v184
	v_sub_f32_e32 v94, v94, v184
	v_sub_f32_e32 v95, v95, v184
	v_sub_f32_e32 v96, v96, v184
	v_sub_f32_e32 v97, v97, v184
	v_sub_f32_e32 v98, v98, v184
	v_sub_f32_e32 v99, v99, v184
	v_sub_f32_e32 v100, v100, v184
	v_sub_f32_e32 v101, v101, v184
	v_sub_f32_e32 v102, v102, v184
	v_sub_f32_e32 v103, v103, v184
	v_mul_f32_e32 v180, v88, v88
	v_mul_f32_e32 v181, v92, v92
	v_mul_f32_e32 v182, v96, v96
	v_mul_f32_e32 v183, v100, v100
	v_fmac_f32_e32 v180, v89, v89
	v_fmac_f32_e32 v181, v93, v93
	v_fmac_f32_e32 v182, v97, v97
	v_fmac_f32_e32 v183, v101, v101
	v_fmac_f32_e32 v180, v90, v90
	v_fmac_f32_e32 v181, v94, v94
	v_fmac_f32_e32 v182, v98, v98
	v_fmac_f32_e32 v183, v102, v102
	v_fmac_f32_e32 v180, v91, v91
	v_fmac_f32_e32 v181, v95, v95
	v_fmac_f32_e32 v182, v99, v99
	v_fmac_f32_e32 v183, v103, v103
	v_add_f32_e32 v180, v180, v181
	v_add_f32_e32 v182, v182, v183
	v_add_f32_e32 v180, v180, v182
	s_nop 1
	v_add_f32_dpp v180, v180, v180 quad_perm:[1,0,3,2] row_mask:0xf bank_mask:0xf
	s_nop 1
	v_add_f32_dpp v180, v180, v180 quad_perm:[2,3,0,1] row_mask:0xf bank_mask:0xf
	s_nop 1
	v_add_f32_dpp v180, v180, v180 row_half_mirror row_mask:0xf bank_mask:0xf
	s_nop 1
	v_add_f32_dpp v180, v180, v180 row_mirror row_mask:0xf bank_mask:0xf
	s_nop 1
	v_add_f32_dpp v180, v180, v180 row_bcast:15 row_mask:0xa bank_mask:0xf
	s_nop 1
	v_add_f32_dpp v180, v180, v180 row_bcast:31 row_mask:0xc bank_mask:0xf
	s_nop 0
	v_readlane_b32 s20, v180, 63
	s_nop 1
	v_mov_b32_e32 v185, s20
	v_fma_f32 v185, v185, v2, v4
	v_rsq_f32_e32 v185, v185
	s_nop 0
	v_mul_f32_e32 v88, v88, v185
	v_mul_f32_e32 v89, v89, v185
	v_mul_f32_e32 v90, v90, v185
	v_mul_f32_e32 v91, v91, v185
	v_mul_f32_e32 v92, v92, v185
	v_mul_f32_e32 v93, v93, v185
	v_mul_f32_e32 v94, v94, v185
	v_mul_f32_e32 v95, v95, v185
	v_mul_f32_e32 v96, v96, v185
	v_mul_f32_e32 v97, v97, v185
	v_mul_f32_e32 v98, v98, v185
	v_mul_f32_e32 v99, v99, v185
	v_mul_f32_e32 v100, v100, v185
	v_mul_f32_e32 v101, v101, v185
	v_mul_f32_e32 v102, v102, v185
	v_mul_f32_e32 v103, v103, v185
	v_fma_f32 v88, v88, v8, v24
	v_fma_f32 v89, v89, v9, v25
	v_fma_f32 v90, v90, v10, v26
	v_fma_f32 v91, v91, v11, v27
	v_fma_f32 v92, v92, v12, v28
	v_fma_f32 v93, v93, v13, v29
	v_fma_f32 v94, v94, v14, v30
	v_fma_f32 v95, v95, v15, v31
	v_fma_f32 v96, v96, v16, v32
	v_fma_f32 v97, v97, v17, v33
	v_fma_f32 v98, v98, v18, v34
	v_fma_f32 v99, v99, v19, v35
	v_fma_f32 v100, v100, v20, v36
	v_fma_f32 v101, v101, v21, v37
	v_fma_f32 v102, v102, v22, v38
	v_fma_f32 v103, v103, v23, v39
	v_add_u32_e32 v171, 0x3000, v1
	global_store_dwordx4 v171, v[88:91], s[4:5]
	global_store_dwordx4 v171, v[92:95], s[4:5] offset:1024
	global_store_dwordx4 v171, v[96:99], s[4:5] offset:2048
	global_store_dwordx4 v171, v[100:103], s[4:5] offset:3072
	s_waitcnt vmcnt(36)
	v_add_f32_e32 v180, v104, v105
	v_add_f32_e32 v181, v108, v109
	v_add_f32_e32 v182, v112, v113
	v_add_f32_e32 v183, v116, v117
	v_add_f32_e32 v180, v180, v106
	v_add_f32_e32 v181, v181, v110
	v_add_f32_e32 v182, v182, v114
	v_add_f32_e32 v183, v183, v118
	v_add_f32_e32 v180, v180, v107
	v_add_f32_e32 v181, v181, v111
	v_add_f32_e32 v182, v182, v115
	v_add_f32_e32 v183, v183, v119
	v_add_f32_e32 v180, v180, v181
	v_add_f32_e32 v182, v182, v183
	v_add_f32_e32 v180, v180, v182
	s_nop 1
	v_add_f32_dpp v180, v180, v180 quad_perm:[1,0,3,2] row_mask:0xf bank_mask:0xf
	s_nop 1
	v_add_f32_dpp v180, v180, v180 quad_perm:[2,3,0,1] row_mask:0xf bank_mask:0xf
	s_nop 1
	v_add_f32_dpp v180, v180, v180 row_half_mirror row_mask:0xf bank_mask:0xf
	s_nop 1
	v_add_f32_dpp v180, v180, v180 row_mirror row_mask:0xf bank_mask:0xf
	s_nop 1
	v_add_f32_dpp v180, v180, v180 row_bcast:15 row_mask:0xa bank_mask:0xf
	s_nop 1
	v_add_f32_dpp v180, v180, v180 row_bcast:31 row_mask:0xc bank_mask:0xf
	s_nop 0
	v_readlane_b32 s20, v180, 63
	s_nop 1
	v_mul_f32_e32 v184, s20, v2
	v_sub_f32_e32 v104, v104, v184
	v_sub_f32_e32 v105, v105, v184
	v_sub_f32_e32 v106, v106, v184
	v_sub_f32_e32 v107, v107, v184
	v_sub_f32_e32 v108, v108, v184
	v_sub_f32_e32 v109, v109, v184
	v_sub_f32_e32 v110, v110, v184
	v_sub_f32_e32 v111, v111, v184
	v_sub_f32_e32 v112, v112, v184
	v_sub_f32_e32 v113, v113, v184
	v_sub_f32_e32 v114, v114, v184
	v_sub_f32_e32 v115, v115, v184
	v_sub_f32_e32 v116, v116, v184
	v_sub_f32_e32 v117, v117, v184
	v_sub_f32_e32 v118, v118, v184
	v_sub_f32_e32 v119, v119, v184
	v_mul_f32_e32 v180, v104, v104
	v_mul_f32_e32 v181, v108, v108
	v_mul_f32_e32 v182, v112, v112
	v_mul_f32_e32 v183, v116, v116
	v_fmac_f32_e32 v180, v105, v105
	v_fmac_f32_e32 v181, v109, v109
	v_fmac_f32_e32 v182, v113, v113
	v_fmac_f32_e32 v183, v117, v117
	v_fmac_f32_e32 v180, v106, v106
	v_fmac_f32_e32 v181, v110, v110
	v_fmac_f32_e32 v182, v114, v114
	v_fmac_f32_e32 v183, v118, v118
	v_fmac_f32_e32 v180, v107, v107
	v_fmac_f32_e32 v181, v111, v111
	v_fmac_f32_e32 v182, v115, v115
	v_fmac_f32_e32 v183, v119, v119
	v_add_f32_e32 v180, v180, v181
	v_add_f32_e32 v182, v182, v183
	v_add_f32_e32 v180, v180, v182
	s_nop 1
	v_add_f32_dpp v180, v180, v180 quad_perm:[1,0,3,2] row_mask:0xf bank_mask:0xf
	s_nop 1
	v_add_f32_dpp v180, v180, v180 quad_perm:[2,3,0,1] row_mask:0xf bank_mask:0xf
	s_nop 1
	v_add_f32_dpp v180, v180, v180 row_half_mirror row_mask:0xf bank_mask:0xf
	s_nop 1
	v_add_f32_dpp v180, v180, v180 row_mirror row_mask:0xf bank_mask:0xf
	s_nop 1
	v_add_f32_dpp v180, v180, v180 row_bcast:15 row_mask:0xa bank_mask:0xf
	s_nop 1
	v_add_f32_dpp v180, v180, v180 row_bcast:31 row_mask:0xc bank_mask:0xf
	s_nop 0
	v_readlane_b32 s20, v180, 63
	s_nop 1
	v_mov_b32_e32 v185, s20
	v_fma_f32 v185, v185, v2, v4
	v_rsq_f32_e32 v185, v185
	s_nop 0
	v_mul_f32_e32 v104, v104, v185
	v_mul_f32_e32 v105, v105, v185
	v_mul_f32_e32 v106, v106, v185
	v_mul_f32_e32 v107, v107, v185
	v_mul_f32_e32 v108, v108, v185
	v_mul_f32_e32 v109, v109, v185
	v_mul_f32_e32 v110, v110, v185
	v_mul_f32_e32 v111, v111, v185
	v_mul_f32_e32 v112, v112, v185
	v_mul_f32_e32 v113, v113, v185
	v_mul_f32_e32 v114, v114, v185
	v_mul_f32_e32 v115, v115, v185
	v_mul_f32_e32 v116, v116, v185
	v_mul_f32_e32 v117, v117, v185
	v_mul_f32_e32 v118, v118, v185
	v_mul_f32_e32 v119, v119, v185
	v_fma_f32 v104, v104, v8, v24
	v_fma_f32 v105, v105, v9, v25
	v_fma_f32 v106, v106, v10, v26
	v_fma_f32 v107, v107, v11, v27
	v_fma_f32 v108, v108, v12, v28
	v_fma_f32 v109, v109, v13, v29
	v_fma_f32 v110, v110, v14, v30
	v_fma_f32 v111, v111, v15, v31
	v_fma_f32 v112, v112, v16, v32
	v_fma_f32 v113, v113, v17, v33
	v_fma_f32 v114, v114, v18, v34
	v_fma_f32 v115, v115, v19, v35
	v_fma_f32 v116, v116, v20, v36
	v_fma_f32 v117, v117, v21, v37
	v_fma_f32 v118, v118, v22, v38
	v_fma_f32 v119, v119, v23, v39
	v_add_u32_e32 v171, 0x4000, v1
	global_store_dwordx4 v171, v[104:107], s[4:5]
	global_store_dwordx4 v171, v[108:111], s[4:5] offset:1024
	global_store_dwordx4 v171, v[112:115], s[4:5] offset:2048
	global_store_dwordx4 v171, v[116:119], s[4:5] offset:3072
	s_waitcnt vmcnt(36)
	v_add_f32_e32 v180, v120, v121
	v_add_f32_e32 v181, v124, v125
	v_add_f32_e32 v182, v128, v129
	v_add_f32_e32 v183, v132, v133
	v_add_f32_e32 v180, v180, v122
	v_add_f32_e32 v181, v181, v126
	v_add_f32_e32 v182, v182, v130
	v_add_f32_e32 v183, v183, v134
	v_add_f32_e32 v180, v180, v123
	v_add_f32_e32 v181, v181, v127
	v_add_f32_e32 v182, v182, v131
	v_add_f32_e32 v183, v183, v135
	v_add_f32_e32 v180, v180, v181
	v_add_f32_e32 v182, v182, v183
	v_add_f32_e32 v180, v180, v182
	s_nop 1
	v_add_f32_dpp v180, v180, v180 quad_perm:[1,0,3,2] row_mask:0xf bank_mask:0xf
	s_nop 1
	v_add_f32_dpp v180, v180, v180 quad_perm:[2,3,0,1] row_mask:0xf bank_mask:0xf
	s_nop 1
	v_add_f32_dpp v180, v180, v180 row_half_mirror row_mask:0xf bank_mask:0xf
	s_nop 1
	v_add_f32_dpp v180, v180, v180 row_mirror row_mask:0xf bank_mask:0xf
	s_nop 1
	v_add_f32_dpp v180, v180, v180 row_bcast:15 row_mask:0xa bank_mask:0xf
	s_nop 1
	v_add_f32_dpp v180, v180, v180 row_bcast:31 row_mask:0xc bank_mask:0xf
	s_nop 0
	v_readlane_b32 s20, v180, 63
	s_nop 1
	v_mul_f32_e32 v184, s20, v2
	v_sub_f32_e32 v120, v120, v184
	v_sub_f32_e32 v121, v121, v184
	v_sub_f32_e32 v122, v122, v184
	v_sub_f32_e32 v123, v123, v184
	v_sub_f32_e32 v124, v124, v184
	v_sub_f32_e32 v125, v125, v184
	v_sub_f32_e32 v126, v126, v184
	v_sub_f32_e32 v127, v127, v184
	v_sub_f32_e32 v128, v128, v184
	v_sub_f32_e32 v129, v129, v184
	v_sub_f32_e32 v130, v130, v184
	v_sub_f32_e32 v131, v131, v184
	v_sub_f32_e32 v132, v132, v184
	v_sub_f32_e32 v133, v133, v184
	v_sub_f32_e32 v134, v134, v184
	v_sub_f32_e32 v135, v135, v184
	v_mul_f32_e32 v180, v120, v120
	v_mul_f32_e32 v181, v124, v124
	v_mul_f32_e32 v182, v128, v128
	v_mul_f32_e32 v183, v132, v132
	v_fmac_f32_e32 v180, v121, v121
	v_fmac_f32_e32 v181, v125, v125
	v_fmac_f32_e32 v182, v129, v129
	v_fmac_f32_e32 v183, v133, v133
	v_fmac_f32_e32 v180, v122, v122
	v_fmac_f32_e32 v181, v126, v126
	v_fmac_f32_e32 v182, v130, v130
	v_fmac_f32_e32 v183, v134, v134
	v_fmac_f32_e32 v180, v123, v123
	v_fmac_f32_e32 v181, v127, v127
	v_fmac_f32_e32 v182, v131, v131
	v_fmac_f32_e32 v183, v135, v135
	v_add_f32_e32 v180, v180, v181
	v_add_f32_e32 v182, v182, v183
	v_add_f32_e32 v180, v180, v182
	s_nop 1
	v_add_f32_dpp v180, v180, v180 quad_perm:[1,0,3,2] row_mask:0xf bank_mask:0xf
	s_nop 1
	v_add_f32_dpp v180, v180, v180 quad_perm:[2,3,0,1] row_mask:0xf bank_mask:0xf
	s_nop 1
	v_add_f32_dpp v180, v180, v180 row_half_mirror row_mask:0xf bank_mask:0xf
	s_nop 1
	v_add_f32_dpp v180, v180, v180 row_mirror row_mask:0xf bank_mask:0xf
	s_nop 1
	v_add_f32_dpp v180, v180, v180 row_bcast:15 row_mask:0xa bank_mask:0xf
	s_nop 1
	v_add_f32_dpp v180, v180, v180 row_bcast:31 row_mask:0xc bank_mask:0xf
	s_nop 0
	v_readlane_b32 s20, v180, 63
	s_nop 1
	v_mov_b32_e32 v185, s20
	v_fma_f32 v185, v185, v2, v4
	v_rsq_f32_e32 v185, v185
	s_nop 0
	v_mul_f32_e32 v120, v120, v185
	v_mul_f32_e32 v121, v121, v185
	v_mul_f32_e32 v122, v122, v185
	v_mul_f32_e32 v123, v123, v185
	v_mul_f32_e32 v124, v124, v185
	v_mul_f32_e32 v125, v125, v185
	v_mul_f32_e32 v126, v126, v185
	v_mul_f32_e32 v127, v127, v185
	v_mul_f32_e32 v128, v128, v185
	v_mul_f32_e32 v129, v129, v185
	v_mul_f32_e32 v130, v130, v185
	v_mul_f32_e32 v131, v131, v185
	v_mul_f32_e32 v132, v132, v185
	v_mul_f32_e32 v133, v133, v185
	v_mul_f32_e32 v134, v134, v185
	v_mul_f32_e32 v135, v135, v185
	v_fma_f32 v120, v120, v8, v24
	v_fma_f32 v121, v121, v9, v25
	v_fma_f32 v122, v122, v10, v26
	v_fma_f32 v123, v123, v11, v27
	v_fma_f32 v124, v124, v12, v28
	v_fma_f32 v125, v125, v13, v29
	v_fma_f32 v126, v126, v14, v30
	v_fma_f32 v127, v127, v15, v31
	v_fma_f32 v128, v128, v16, v32
	v_fma_f32 v129, v129, v17, v33
	v_fma_f32 v130, v130, v18, v34
	v_fma_f32 v131, v131, v19, v35
	v_fma_f32 v132, v132, v20, v36
	v_fma_f32 v133, v133, v21, v37
	v_fma_f32 v134, v134, v22, v38
	v_fma_f32 v135, v135, v23, v39
	v_add_u32_e32 v171, 0x5000, v1
	global_store_dwordx4 v171, v[120:123], s[4:5]
	global_store_dwordx4 v171, v[124:127], s[4:5] offset:1024
	global_store_dwordx4 v171, v[128:131], s[4:5] offset:2048
	global_store_dwordx4 v171, v[132:135], s[4:5] offset:3072
	s_waitcnt vmcnt(36)
	v_add_f32_e32 v180, v136, v137
	v_add_f32_e32 v181, v140, v141
	v_add_f32_e32 v182, v144, v145
	v_add_f32_e32 v183, v148, v149
	v_add_f32_e32 v180, v180, v138
	v_add_f32_e32 v181, v181, v142
	v_add_f32_e32 v182, v182, v146
	v_add_f32_e32 v183, v183, v150
	v_add_f32_e32 v180, v180, v139
	v_add_f32_e32 v181, v181, v143
	v_add_f32_e32 v182, v182, v147
	v_add_f32_e32 v183, v183, v151
	v_add_f32_e32 v180, v180, v181
	v_add_f32_e32 v182, v182, v183
	v_add_f32_e32 v180, v180, v182
	s_nop 1
	v_add_f32_dpp v180, v180, v180 quad_perm:[1,0,3,2] row_mask:0xf bank_mask:0xf
	s_nop 1
	v_add_f32_dpp v180, v180, v180 quad_perm:[2,3,0,1] row_mask:0xf bank_mask:0xf
	s_nop 1
	v_add_f32_dpp v180, v180, v180 row_half_mirror row_mask:0xf bank_mask:0xf
	s_nop 1
	v_add_f32_dpp v180, v180, v180 row_mirror row_mask:0xf bank_mask:0xf
	s_nop 1
	v_add_f32_dpp v180, v180, v180 row_bcast:15 row_mask:0xa bank_mask:0xf
	s_nop 1
	v_add_f32_dpp v180, v180, v180 row_bcast:31 row_mask:0xc bank_mask:0xf
	s_nop 0
	v_readlane_b32 s20, v180, 63
	s_nop 1
	v_mul_f32_e32 v184, s20, v2
	v_sub_f32_e32 v136, v136, v184
	v_sub_f32_e32 v137, v137, v184
	v_sub_f32_e32 v138, v138, v184
	v_sub_f32_e32 v139, v139, v184
	v_sub_f32_e32 v140, v140, v184
	v_sub_f32_e32 v141, v141, v184
	v_sub_f32_e32 v142, v142, v184
	v_sub_f32_e32 v143, v143, v184
	v_sub_f32_e32 v144, v144, v184
	v_sub_f32_e32 v145, v145, v184
	v_sub_f32_e32 v146, v146, v184
	v_sub_f32_e32 v147, v147, v184
	v_sub_f32_e32 v148, v148, v184
	v_sub_f32_e32 v149, v149, v184
	v_sub_f32_e32 v150, v150, v184
	v_sub_f32_e32 v151, v151, v184
	v_mul_f32_e32 v180, v136, v136
	v_mul_f32_e32 v181, v140, v140
	v_mul_f32_e32 v182, v144, v144
	v_mul_f32_e32 v183, v148, v148
	v_fmac_f32_e32 v180, v137, v137
	v_fmac_f32_e32 v181, v141, v141
	v_fmac_f32_e32 v182, v145, v145
	v_fmac_f32_e32 v183, v149, v149
	v_fmac_f32_e32 v180, v138, v138
	v_fmac_f32_e32 v181, v142, v142
	v_fmac_f32_e32 v182, v146, v146
	v_fmac_f32_e32 v183, v150, v150
	v_fmac_f32_e32 v180, v139, v139
	v_fmac_f32_e32 v181, v143, v143
	v_fmac_f32_e32 v182, v147, v147
	v_fmac_f32_e32 v183, v151, v151
	v_add_f32_e32 v180, v180, v181
	v_add_f32_e32 v182, v182, v183
	v_add_f32_e32 v180, v180, v182
	s_nop 1
	v_add_f32_dpp v180, v180, v180 quad_perm:[1,0,3,2] row_mask:0xf bank_mask:0xf
	s_nop 1
	v_add_f32_dpp v180, v180, v180 quad_perm:[2,3,0,1] row_mask:0xf bank_mask:0xf
	s_nop 1
	v_add_f32_dpp v180, v180, v180 row_half_mirror row_mask:0xf bank_mask:0xf
	s_nop 1
	v_add_f32_dpp v180, v180, v180 row_mirror row_mask:0xf bank_mask:0xf
	s_nop 1
	v_add_f32_dpp v180, v180, v180 row_bcast:15 row_mask:0xa bank_mask:0xf
	s_nop 1
	v_add_f32_dpp v180, v180, v180 row_bcast:31 row_mask:0xc bank_mask:0xf
	s_nop 0
	v_readlane_b32 s20, v180, 63
	s_nop 1
	v_mov_b32_e32 v185, s20
	v_fma_f32 v185, v185, v2, v4
	v_rsq_f32_e32 v185, v185
	s_nop 0
	v_mul_f32_e32 v136, v136, v185
	v_mul_f32_e32 v137, v137, v185
	v_mul_f32_e32 v138, v138, v185
	v_mul_f32_e32 v139, v139, v185
	v_mul_f32_e32 v140, v140, v185
	v_mul_f32_e32 v141, v141, v185
	v_mul_f32_e32 v142, v142, v185
	v_mul_f32_e32 v143, v143, v185
	v_mul_f32_e32 v144, v144, v185
	v_mul_f32_e32 v145, v145, v185
	v_mul_f32_e32 v146, v146, v185
	v_mul_f32_e32 v147, v147, v185
	v_mul_f32_e32 v148, v148, v185
	v_mul_f32_e32 v149, v149, v185
	v_mul_f32_e32 v150, v150, v185
	v_mul_f32_e32 v151, v151, v185
	v_fma_f32 v136, v136, v8, v24
	v_fma_f32 v137, v137, v9, v25
	v_fma_f32 v138, v138, v10, v26
	v_fma_f32 v139, v139, v11, v27
	v_fma_f32 v140, v140, v12, v28
	v_fma_f32 v141, v141, v13, v29
	v_fma_f32 v142, v142, v14, v30
	v_fma_f32 v143, v143, v15, v31
	v_fma_f32 v144, v144, v16, v32
	v_fma_f32 v145, v145, v17, v33
	v_fma_f32 v146, v146, v18, v34
	v_fma_f32 v147, v147, v19, v35
	v_fma_f32 v148, v148, v20, v36
	v_fma_f32 v149, v149, v21, v37
	v_fma_f32 v150, v150, v22, v38
	v_fma_f32 v151, v151, v23, v39
	v_add_u32_e32 v171, 0x6000, v1
	global_store_dwordx4 v171, v[136:139], s[4:5]
	global_store_dwordx4 v171, v[140:143], s[4:5] offset:1024
	global_store_dwordx4 v171, v[144:147], s[4:5] offset:2048
	global_store_dwordx4 v171, v[148:151], s[4:5] offset:3072
	s_waitcnt vmcnt(36)
	v_add_f32_e32 v180, v152, v153
	v_add_f32_e32 v181, v156, v157
	v_add_f32_e32 v182, v160, v161
	v_add_f32_e32 v183, v164, v165
	v_add_f32_e32 v180, v180, v154
	v_add_f32_e32 v181, v181, v158
	v_add_f32_e32 v182, v182, v162
	v_add_f32_e32 v183, v183, v166
	v_add_f32_e32 v180, v180, v155
	v_add_f32_e32 v181, v181, v159
	v_add_f32_e32 v182, v182, v163
	v_add_f32_e32 v183, v183, v167
	v_add_f32_e32 v180, v180, v181
	v_add_f32_e32 v182, v182, v183
	v_add_f32_e32 v180, v180, v182
	s_nop 1
	v_add_f32_dpp v180, v180, v180 quad_perm:[1,0,3,2] row_mask:0xf bank_mask:0xf
	s_nop 1
	v_add_f32_dpp v180, v180, v180 quad_perm:[2,3,0,1] row_mask:0xf bank_mask:0xf
	s_nop 1
	v_add_f32_dpp v180, v180, v180 row_half_mirror row_mask:0xf bank_mask:0xf
	s_nop 1
	v_add_f32_dpp v180, v180, v180 row_mirror row_mask:0xf bank_mask:0xf
	s_nop 1
	v_add_f32_dpp v180, v180, v180 row_bcast:15 row_mask:0xa bank_mask:0xf
	s_nop 1
	v_add_f32_dpp v180, v180, v180 row_bcast:31 row_mask:0xc bank_mask:0xf
	s_nop 0
	v_readlane_b32 s20, v180, 63
	s_nop 1
	v_mul_f32_e32 v184, s20, v2
	v_sub_f32_e32 v152, v152, v184
	v_sub_f32_e32 v153, v153, v184
	v_sub_f32_e32 v154, v154, v184
	v_sub_f32_e32 v155, v155, v184
	v_sub_f32_e32 v156, v156, v184
	v_sub_f32_e32 v157, v157, v184
	v_sub_f32_e32 v158, v158, v184
	v_sub_f32_e32 v159, v159, v184
	v_sub_f32_e32 v160, v160, v184
	v_sub_f32_e32 v161, v161, v184
	v_sub_f32_e32 v162, v162, v184
	v_sub_f32_e32 v163, v163, v184
	v_sub_f32_e32 v164, v164, v184
	v_sub_f32_e32 v165, v165, v184
	v_sub_f32_e32 v166, v166, v184
	v_sub_f32_e32 v167, v167, v184
	v_mul_f32_e32 v180, v152, v152
	v_mul_f32_e32 v181, v156, v156
	v_mul_f32_e32 v182, v160, v160
	v_mul_f32_e32 v183, v164, v164
	v_fmac_f32_e32 v180, v153, v153
	v_fmac_f32_e32 v181, v157, v157
	v_fmac_f32_e32 v182, v161, v161
	v_fmac_f32_e32 v183, v165, v165
	v_fmac_f32_e32 v180, v154, v154
	v_fmac_f32_e32 v181, v158, v158
	v_fmac_f32_e32 v182, v162, v162
	v_fmac_f32_e32 v183, v166, v166
	v_fmac_f32_e32 v180, v155, v155
	v_fmac_f32_e32 v181, v159, v159
	v_fmac_f32_e32 v182, v163, v163
	v_fmac_f32_e32 v183, v167, v167
	v_add_f32_e32 v180, v180, v181
	v_add_f32_e32 v182, v182, v183
	v_add_f32_e32 v180, v180, v182
	s_nop 1
	v_add_f32_dpp v180, v180, v180 quad_perm:[1,0,3,2] row_mask:0xf bank_mask:0xf
	s_nop 1
	v_add_f32_dpp v180, v180, v180 quad_perm:[2,3,0,1] row_mask:0xf bank_mask:0xf
	s_nop 1
	v_add_f32_dpp v180, v180, v180 row_half_mirror row_mask:0xf bank_mask:0xf
	s_nop 1
	v_add_f32_dpp v180, v180, v180 row_mirror row_mask:0xf bank_mask:0xf
	s_nop 1
	v_add_f32_dpp v180, v180, v180 row_bcast:15 row_mask:0xa bank_mask:0xf
	s_nop 1
	v_add_f32_dpp v180, v180, v180 row_bcast:31 row_mask:0xc bank_mask:0xf
	s_nop 0
	v_readlane_b32 s20, v180, 63
	s_nop 1
	v_mov_b32_e32 v185, s20
	v_fma_f32 v185, v185, v2, v4
	v_rsq_f32_e32 v185, v185
	s_nop 0
	v_mul_f32_e32 v152, v152, v185
	v_mul_f32_e32 v153, v153, v185
	v_mul_f32_e32 v154, v154, v185
	v_mul_f32_e32 v155, v155, v185
	v_mul_f32_e32 v156, v156, v185
	v_mul_f32_e32 v157, v157, v185
	v_mul_f32_e32 v158, v158, v185
	v_mul_f32_e32 v159, v159, v185
	v_mul_f32_e32 v160, v160, v185
	v_mul_f32_e32 v161, v161, v185
	v_mul_f32_e32 v162, v162, v185
	v_mul_f32_e32 v163, v163, v185
	v_mul_f32_e32 v164, v164, v185
	v_mul_f32_e32 v165, v165, v185
	v_mul_f32_e32 v166, v166, v185
	v_mul_f32_e32 v167, v167, v185
	v_fma_f32 v152, v152, v8, v24
	v_fma_f32 v153, v153, v9, v25
	v_fma_f32 v154, v154, v10, v26
	v_fma_f32 v155, v155, v11, v27
	v_fma_f32 v156, v156, v12, v28
	v_fma_f32 v157, v157, v13, v29
	v_fma_f32 v158, v158, v14, v30
	v_fma_f32 v159, v159, v15, v31
	v_fma_f32 v160, v160, v16, v32
	v_fma_f32 v161, v161, v17, v33
	v_fma_f32 v162, v162, v18, v34
	v_fma_f32 v163, v163, v19, v35
	v_fma_f32 v164, v164, v20, v36
	v_fma_f32 v165, v165, v21, v37
	v_fma_f32 v166, v166, v22, v38
	v_fma_f32 v167, v167, v23, v39
	v_add_u32_e32 v171, 0x7000, v1
	global_store_dwordx4 v171, v[152:155], s[4:5]
	global_store_dwordx4 v171, v[156:159], s[4:5] offset:1024
	global_store_dwordx4 v171, v[160:163], s[4:5] offset:2048
	global_store_dwordx4 v171, v[164:167], s[4:5] offset:3072
	s_waitcnt vmcnt(32)
	v_add_f32_e32 v180, v40, v41
	v_add_f32_e32 v181, v44, v45
	v_add_f32_e32 v182, v48, v49
	v_add_f32_e32 v183, v52, v53
	v_add_f32_e32 v180, v180, v42
	v_add_f32_e32 v181, v181, v46
	v_add_f32_e32 v182, v182, v50
	v_add_f32_e32 v183, v183, v54
	v_add_f32_e32 v180, v180, v43
	v_add_f32_e32 v181, v181, v47
	v_add_f32_e32 v182, v182, v51
	v_add_f32_e32 v183, v183, v55
	v_add_f32_e32 v180, v180, v181
	v_add_f32_e32 v182, v182, v183
	v_add_f32_e32 v180, v180, v182
	s_nop 1
	v_add_f32_dpp v180, v180, v180 quad_perm:[1,0,3,2] row_mask:0xf bank_mask:0xf
	s_nop 1
	v_add_f32_dpp v180, v180, v180 quad_perm:[2,3,0,1] row_mask:0xf bank_mask:0xf
	s_nop 1
	v_add_f32_dpp v180, v180, v180 row_half_mirror row_mask:0xf bank_mask:0xf
	s_nop 1
	v_add_f32_dpp v180, v180, v180 row_mirror row_mask:0xf bank_mask:0xf
	s_nop 1
	v_add_f32_dpp v180, v180, v180 row_bcast:15 row_mask:0xa bank_mask:0xf
	s_nop 1
	v_add_f32_dpp v180, v180, v180 row_bcast:31 row_mask:0xc bank_mask:0xf
	s_nop 0
	v_readlane_b32 s20, v180, 63
	s_nop 1
	v_mul_f32_e32 v184, s20, v2
	v_sub_f32_e32 v40, v40, v184
	v_sub_f32_e32 v41, v41, v184
	v_sub_f32_e32 v42, v42, v184
	v_sub_f32_e32 v43, v43, v184
	v_sub_f32_e32 v44, v44, v184
	v_sub_f32_e32 v45, v45, v184
	v_sub_f32_e32 v46, v46, v184
	v_sub_f32_e32 v47, v47, v184
	v_sub_f32_e32 v48, v48, v184
	v_sub_f32_e32 v49, v49, v184
	v_sub_f32_e32 v50, v50, v184
	v_sub_f32_e32 v51, v51, v184
	v_sub_f32_e32 v52, v52, v184
	v_sub_f32_e32 v53, v53, v184
	v_sub_f32_e32 v54, v54, v184
	v_sub_f32_e32 v55, v55, v184
	v_mul_f32_e32 v180, v40, v40
	v_mul_f32_e32 v181, v44, v44
	v_mul_f32_e32 v182, v48, v48
	v_mul_f32_e32 v183, v52, v52
	v_fmac_f32_e32 v180, v41, v41
	v_fmac_f32_e32 v181, v45, v45
	v_fmac_f32_e32 v182, v49, v49
	v_fmac_f32_e32 v183, v53, v53
	v_fmac_f32_e32 v180, v42, v42
	v_fmac_f32_e32 v181, v46, v46
	v_fmac_f32_e32 v182, v50, v50
	v_fmac_f32_e32 v183, v54, v54
	v_fmac_f32_e32 v180, v43, v43
	v_fmac_f32_e32 v181, v47, v47
	v_fmac_f32_e32 v182, v51, v51
	v_fmac_f32_e32 v183, v55, v55
	v_add_f32_e32 v180, v180, v181
	v_add_f32_e32 v182, v182, v183
	v_add_f32_e32 v180, v180, v182
	s_nop 1
	v_add_f32_dpp v180, v180, v180 quad_perm:[1,0,3,2] row_mask:0xf bank_mask:0xf
	s_nop 1
	v_add_f32_dpp v180, v180, v180 quad_perm:[2,3,0,1] row_mask:0xf bank_mask:0xf
	s_nop 1
	v_add_f32_dpp v180, v180, v180 row_half_mirror row_mask:0xf bank_mask:0xf
	s_nop 1
	v_add_f32_dpp v180, v180, v180 row_mirror row_mask:0xf bank_mask:0xf
	s_nop 1
	v_add_f32_dpp v180, v180, v180 row_bcast:15 row_mask:0xa bank_mask:0xf
	s_nop 1
	v_add_f32_dpp v180, v180, v180 row_bcast:31 row_mask:0xc bank_mask:0xf
	s_nop 0
	v_readlane_b32 s20, v180, 63
	s_nop 1
	v_mov_b32_e32 v185, s20
	v_fma_f32 v185, v185, v2, v4
	v_rsq_f32_e32 v185, v185
	s_nop 0
	v_mul_f32_e32 v40, v40, v185
	v_mul_f32_e32 v41, v41, v185
	v_mul_f32_e32 v42, v42, v185
	v_mul_f32_e32 v43, v43, v185
	v_mul_f32_e32 v44, v44, v185
	v_mul_f32_e32 v45, v45, v185
	v_mul_f32_e32 v46, v46, v185
	v_mul_f32_e32 v47, v47, v185
	v_mul_f32_e32 v48, v48, v185
	v_mul_f32_e32 v49, v49, v185
	v_mul_f32_e32 v50, v50, v185
	v_mul_f32_e32 v51, v51, v185
	v_mul_f32_e32 v52, v52, v185
	v_mul_f32_e32 v53, v53, v185
	v_mul_f32_e32 v54, v54, v185
	v_mul_f32_e32 v55, v55, v185
	v_fma_f32 v40, v40, v8, v24
	v_fma_f32 v41, v41, v9, v25
	v_fma_f32 v42, v42, v10, v26
	v_fma_f32 v43, v43, v11, v27
	v_fma_f32 v44, v44, v12, v28
	v_fma_f32 v45, v45, v13, v29
	v_fma_f32 v46, v46, v14, v30
	v_fma_f32 v47, v47, v15, v31
	v_fma_f32 v48, v48, v16, v32
	v_fma_f32 v49, v49, v17, v33
	v_fma_f32 v50, v50, v18, v34
	v_fma_f32 v51, v51, v19, v35
	v_fma_f32 v52, v52, v20, v36
	v_fma_f32 v53, v53, v21, v37
	v_fma_f32 v54, v54, v22, v38
	v_fma_f32 v55, v55, v23, v39
	v_add_u32_e32 v171, 0x8000, v1
	global_store_dwordx4 v171, v[40:43], s[4:5]
	global_store_dwordx4 v171, v[44:47], s[4:5] offset:1024
	global_store_dwordx4 v171, v[48:51], s[4:5] offset:2048
	global_store_dwordx4 v171, v[52:55], s[4:5] offset:3072
	s_waitcnt vmcnt(28)
	v_add_f32_e32 v180, v56, v57
	v_add_f32_e32 v181, v60, v61
	v_add_f32_e32 v182, v64, v65
	v_add_f32_e32 v183, v68, v69
	v_add_f32_e32 v180, v180, v58
	v_add_f32_e32 v181, v181, v62
	v_add_f32_e32 v182, v182, v66
	v_add_f32_e32 v183, v183, v70
	v_add_f32_e32 v180, v180, v59
	v_add_f32_e32 v181, v181, v63
	v_add_f32_e32 v182, v182, v67
	v_add_f32_e32 v183, v183, v71
	v_add_f32_e32 v180, v180, v181
	v_add_f32_e32 v182, v182, v183
	v_add_f32_e32 v180, v180, v182
	s_nop 1
	v_add_f32_dpp v180, v180, v180 quad_perm:[1,0,3,2] row_mask:0xf bank_mask:0xf
	s_nop 1
	v_add_f32_dpp v180, v180, v180 quad_perm:[2,3,0,1] row_mask:0xf bank_mask:0xf
	s_nop 1
	v_add_f32_dpp v180, v180, v180 row_half_mirror row_mask:0xf bank_mask:0xf
	s_nop 1
	v_add_f32_dpp v180, v180, v180 row_mirror row_mask:0xf bank_mask:0xf
	s_nop 1
	v_add_f32_dpp v180, v180, v180 row_bcast:15 row_mask:0xa bank_mask:0xf
	s_nop 1
	v_add_f32_dpp v180, v180, v180 row_bcast:31 row_mask:0xc bank_mask:0xf
	s_nop 0
	v_readlane_b32 s20, v180, 63
	s_nop 1
	v_mul_f32_e32 v184, s20, v2
	v_sub_f32_e32 v56, v56, v184
	v_sub_f32_e32 v57, v57, v184
	v_sub_f32_e32 v58, v58, v184
	v_sub_f32_e32 v59, v59, v184
	v_sub_f32_e32 v60, v60, v184
	v_sub_f32_e32 v61, v61, v184
	v_sub_f32_e32 v62, v62, v184
	v_sub_f32_e32 v63, v63, v184
	v_sub_f32_e32 v64, v64, v184
	v_sub_f32_e32 v65, v65, v184
	v_sub_f32_e32 v66, v66, v184
	v_sub_f32_e32 v67, v67, v184
	v_sub_f32_e32 v68, v68, v184
	v_sub_f32_e32 v69, v69, v184
	v_sub_f32_e32 v70, v70, v184
	v_sub_f32_e32 v71, v71, v184
	v_mul_f32_e32 v180, v56, v56
	v_mul_f32_e32 v181, v60, v60
	v_mul_f32_e32 v182, v64, v64
	v_mul_f32_e32 v183, v68, v68
	v_fmac_f32_e32 v180, v57, v57
	v_fmac_f32_e32 v181, v61, v61
	v_fmac_f32_e32 v182, v65, v65
	v_fmac_f32_e32 v183, v69, v69
	v_fmac_f32_e32 v180, v58, v58
	v_fmac_f32_e32 v181, v62, v62
	v_fmac_f32_e32 v182, v66, v66
	v_fmac_f32_e32 v183, v70, v70
	v_fmac_f32_e32 v180, v59, v59
	v_fmac_f32_e32 v181, v63, v63
	v_fmac_f32_e32 v182, v67, v67
	v_fmac_f32_e32 v183, v71, v71
	v_add_f32_e32 v180, v180, v181
	v_add_f32_e32 v182, v182, v183
	v_add_f32_e32 v180, v180, v182
	s_nop 1
	v_add_f32_dpp v180, v180, v180 quad_perm:[1,0,3,2] row_mask:0xf bank_mask:0xf
	s_nop 1
	v_add_f32_dpp v180, v180, v180 quad_perm:[2,3,0,1] row_mask:0xf bank_mask:0xf
	s_nop 1
	v_add_f32_dpp v180, v180, v180 row_half_mirror row_mask:0xf bank_mask:0xf
	s_nop 1
	v_add_f32_dpp v180, v180, v180 row_mirror row_mask:0xf bank_mask:0xf
	s_nop 1
	v_add_f32_dpp v180, v180, v180 row_bcast:15 row_mask:0xa bank_mask:0xf
	s_nop 1
	v_add_f32_dpp v180, v180, v180 row_bcast:31 row_mask:0xc bank_mask:0xf
	s_nop 0
	v_readlane_b32 s20, v180, 63
	s_nop 1
	v_mov_b32_e32 v185, s20
	v_fma_f32 v185, v185, v2, v4
	v_rsq_f32_e32 v185, v185
	s_nop 0
	v_mul_f32_e32 v56, v56, v185
	v_mul_f32_e32 v57, v57, v185
	v_mul_f32_e32 v58, v58, v185
	v_mul_f32_e32 v59, v59, v185
	v_mul_f32_e32 v60, v60, v185
	v_mul_f32_e32 v61, v61, v185
	v_mul_f32_e32 v62, v62, v185
	v_mul_f32_e32 v63, v63, v185
	v_mul_f32_e32 v64, v64, v185
	v_mul_f32_e32 v65, v65, v185
	v_mul_f32_e32 v66, v66, v185
	v_mul_f32_e32 v67, v67, v185
	v_mul_f32_e32 v68, v68, v185
	v_mul_f32_e32 v69, v69, v185
	v_mul_f32_e32 v70, v70, v185
	v_mul_f32_e32 v71, v71, v185
	v_fma_f32 v56, v56, v8, v24
	v_fma_f32 v57, v57, v9, v25
	v_fma_f32 v58, v58, v10, v26
	v_fma_f32 v59, v59, v11, v27
	v_fma_f32 v60, v60, v12, v28
	v_fma_f32 v61, v61, v13, v29
	v_fma_f32 v62, v62, v14, v30
	v_fma_f32 v63, v63, v15, v31
	v_fma_f32 v64, v64, v16, v32
	v_fma_f32 v65, v65, v17, v33
	v_fma_f32 v66, v66, v18, v34
	v_fma_f32 v67, v67, v19, v35
	v_fma_f32 v68, v68, v20, v36
	v_fma_f32 v69, v69, v21, v37
	v_fma_f32 v70, v70, v22, v38
	v_fma_f32 v71, v71, v23, v39
	v_add_u32_e32 v171, 0x9000, v1
	global_store_dwordx4 v171, v[56:59], s[4:5]
	global_store_dwordx4 v171, v[60:63], s[4:5] offset:1024
	global_store_dwordx4 v171, v[64:67], s[4:5] offset:2048
	global_store_dwordx4 v171, v[68:71], s[4:5] offset:3072
	s_branch .LBB0_29
.Llo_small:
	s_lshl_b32 s1, s86, 3
	s_add_i32 s0, s0, s1
	s_lshl_b32 s0, s0, 13
	s_add_u32 s4, s4, s0
	s_addc_u32 s5, s5, 0
	global_load_dwordx4 v[40:43], v1, s[4:5]
	global_load_dwordx4 v[44:47], v1, s[4:5] offset:1024
	global_load_dwordx4 v[48:51], v1, s[4:5] offset:2048
	global_load_dwordx4 v[52:55], v1, s[4:5] offset:3072
	global_load_dwordx4 v[8:11], v1, s[40:41]
	global_load_dwordx4 v[12:15], v1, s[40:41] offset:1024
	global_load_dwordx4 v[16:19], v1, s[40:41] offset:2048
	global_load_dwordx4 v[20:23], v1, s[40:41] offset:3072
	global_load_dwordx4 v[24:27], v1, s[42:43]
	global_load_dwordx4 v[28:31], v1, s[42:43] offset:1024
	global_load_dwordx4 v[32:35], v1, s[42:43] offset:2048
	global_load_dwordx4 v[36:39], v1, s[42:43] offset:3072
	v_add_u32_e32 v170, 0x1000, v1
	global_load_dwordx4 v[56:59], v170, s[4:5]
	global_load_dwordx4 v[60:63], v170, s[4:5] offset:1024
	global_load_dwordx4 v[64:67], v170, s[4:5] offset:2048
	global_load_dwordx4 v[68:71], v170, s[4:5] offset:3072
	s_waitcnt vmcnt(12)
	v_add_f32_e32 v180, v40, v41
	v_add_f32_e32 v181, v44, v45
	v_add_f32_e32 v182, v48, v49
	v_add_f32_e32 v183, v52, v53
	v_add_f32_e32 v180, v180, v42
	v_add_f32_e32 v181, v181, v46
	v_add_f32_e32 v182, v182, v50
	v_add_f32_e32 v183, v183, v54
	v_add_f32_e32 v180, v180, v43
	v_add_f32_e32 v181, v181, v47
	v_add_f32_e32 v182, v182, v51
	v_add_f32_e32 v183, v183, v55
	v_add_f32_e32 v180, v180, v181
	v_add_f32_e32 v182, v182, v183
	v_add_f32_e32 v180, v180, v182
	s_nop 1
	v_add_f32_dpp v180, v180, v180 quad_perm:[1,0,3,2] row_mask:0xf bank_mask:0xf
	s_nop 1
	v_add_f32_dpp v180, v180, v180 quad_perm:[2,3,0,1] row_mask:0xf bank_mask:0xf
	s_nop 1
	v_add_f32_dpp v180, v180, v180 row_half_mirror row_mask:0xf bank_mask:0xf
	s_nop 1
	v_add_f32_dpp v180, v180, v180 row_mirror row_mask:0xf bank_mask:0xf
	s_nop 1
	v_add_f32_dpp v180, v180, v180 row_bcast:15 row_mask:0xa bank_mask:0xf
	s_nop 1
	v_add_f32_dpp v180, v180, v180 row_bcast:31 row_mask:0xc bank_mask:0xf
	s_nop 0
	v_readlane_b32 s20, v180, 63
	s_nop 1
	v_mul_f32_e32 v184, s20, v2
	v_sub_f32_e32 v40, v40, v184
	v_sub_f32_e32 v41, v41, v184
	v_sub_f32_e32 v42, v42, v184
	v_sub_f32_e32 v43, v43, v184
	v_sub_f32_e32 v44, v44, v184
	v_sub_f32_e32 v45, v45, v184
	v_sub_f32_e32 v46, v46, v184
	v_sub_f32_e32 v47, v47, v184
	v_sub_f32_e32 v48, v48, v184
	v_sub_f32_e32 v49, v49, v184
	v_sub_f32_e32 v50, v50, v184
	v_sub_f32_e32 v51, v51, v184
	v_sub_f32_e32 v52, v52, v184
	v_sub_f32_e32 v53, v53, v184
	v_sub_f32_e32 v54, v54, v184
	v_sub_f32_e32 v55, v55, v184
	v_mul_f32_e32 v180, v40, v40
	v_mul_f32_e32 v181, v44, v44
	v_mul_f32_e32 v182, v48, v48
	v_mul_f32_e32 v183, v52, v52
	v_fmac_f32_e32 v180, v41, v41
	v_fmac_f32_e32 v181, v45, v45
	v_fmac_f32_e32 v182, v49, v49
	v_fmac_f32_e32 v183, v53, v53
	v_fmac_f32_e32 v180, v42, v42
	v_fmac_f32_e32 v181, v46, v46
	v_fmac_f32_e32 v182, v50, v50
	v_fmac_f32_e32 v183, v54, v54
	v_fmac_f32_e32 v180, v43, v43
	v_fmac_f32_e32 v181, v47, v47
	v_fmac_f32_e32 v182, v51, v51
	v_fmac_f32_e32 v183, v55, v55
	v_add_f32_e32 v180, v180, v181
	v_add_f32_e32 v182, v182, v183
	v_add_f32_e32 v180, v180, v182
	s_nop 1
	v_add_f32_dpp v180, v180, v180 quad_perm:[1,0,3,2] row_mask:0xf bank_mask:0xf
	s_nop 1
	v_add_f32_dpp v180, v180, v180 quad_perm:[2,3,0,1] row_mask:0xf bank_mask:0xf
	s_nop 1
	v_add_f32_dpp v180, v180, v180 row_half_mirror row_mask:0xf bank_mask:0xf
	s_nop 1
	v_add_f32_dpp v180, v180, v180 row_mirror row_mask:0xf bank_mask:0xf
	s_nop 1
	v_add_f32_dpp v180, v180, v180 row_bcast:15 row_mask:0xa bank_mask:0xf
	s_nop 1
	v_add_f32_dpp v180, v180, v180 row_bcast:31 row_mask:0xc bank_mask:0xf
	s_nop 0
	v_readlane_b32 s20, v180, 63
	s_nop 1
	v_mov_b32_e32 v185, s20
	v_fma_f32 v185, v185, v2, v4
	v_rsq_f32_e32 v185, v185
	s_nop 0
	v_mul_f32_e32 v40, v40, v185
	v_mul_f32_e32 v41, v41, v185
	v_mul_f32_e32 v42, v42, v185
	v_mul_f32_e32 v43, v43, v185
	v_mul_f32_e32 v44, v44, v185
	v_mul_f32_e32 v45, v45, v185
	v_mul_f32_e32 v46, v46, v185
	v_mul_f32_e32 v47, v47, v185
	v_mul_f32_e32 v48, v48, v185
	v_mul_f32_e32 v49, v49, v185
	v_mul_f32_e32 v50, v50, v185
	v_mul_f32_e32 v51, v51, v185
	v_mul_f32_e32 v52, v52, v185
	v_mul_f32_e32 v53, v53, v185
	v_mul_f32_e32 v54, v54, v185
	v_mul_f32_e32 v55, v55, v185
	s_waitcnt vmcnt(4)
	v_fma_f32 v40, v40, v8, v24
	v_fma_f32 v41, v41, v9, v25
	v_fma_f32 v42, v42, v10, v26
	v_fma_f32 v43, v43, v11, v27
	v_fma_f32 v44, v44, v12, v28
	v_fma_f32 v45, v45, v13, v29
	v_fma_f32 v46, v46, v14, v30
	v_fma_f32 v47, v47, v15, v31
	v_fma_f32 v48, v48, v16, v32
	v_fma_f32 v49, v49, v17, v33
	v_fma_f32 v50, v50, v18, v34
	v_fma_f32 v51, v51, v19, v35
	v_fma_f32 v52, v52, v20, v36
	v_fma_f32 v53, v53, v21, v37
	v_fma_f32 v54, v54, v22, v38
	v_fma_f32 v55, v55, v23, v39
	global_store_dwordx4 v1, v[40:43], s[4:5]
	global_store_dwordx4 v1, v[44:47], s[4:5] offset:1024
	global_store_dwordx4 v1, v[48:51], s[4:5] offset:2048
	global_store_dwordx4 v1, v[52:55], s[4:5] offset:3072
	s_waitcnt vmcnt(4)
	v_add_f32_e32 v180, v56, v57
	v_add_f32_e32 v181, v60, v61
	v_add_f32_e32 v182, v64, v65
	v_add_f32_e32 v183, v68, v69
	v_add_f32_e32 v180, v180, v58
	v_add_f32_e32 v181, v181, v62
	v_add_f32_e32 v182, v182, v66
	v_add_f32_e32 v183, v183, v70
	v_add_f32_e32 v180, v180, v59
	v_add_f32_e32 v181, v181, v63
	v_add_f32_e32 v182, v182, v67
	v_add_f32_e32 v183, v183, v71
	v_add_f32_e32 v180, v180, v181
	v_add_f32_e32 v182, v182, v183
	v_add_f32_e32 v180, v180, v182
	s_nop 1
	v_add_f32_dpp v180, v180, v180 quad_perm:[1,0,3,2] row_mask:0xf bank_mask:0xf
	s_nop 1
	v_add_f32_dpp v180, v180, v180 quad_perm:[2,3,0,1] row_mask:0xf bank_mask:0xf
	s_nop 1
	v_add_f32_dpp v180, v180, v180 row_half_mirror row_mask:0xf bank_mask:0xf
	s_nop 1
	v_add_f32_dpp v180, v180, v180 row_mirror row_mask:0xf bank_mask:0xf
	s_nop 1
	v_add_f32_dpp v180, v180, v180 row_bcast:15 row_mask:0xa bank_mask:0xf
	s_nop 1
	v_add_f32_dpp v180, v180, v180 row_bcast:31 row_mask:0xc bank_mask:0xf
	s_nop 0
	v_readlane_b32 s20, v180, 63
	s_nop 1
	v_mul_f32_e32 v184, s20, v2
	v_sub_f32_e32 v56, v56, v184
	v_sub_f32_e32 v57, v57, v184
	v_sub_f32_e32 v58, v58, v184
	v_sub_f32_e32 v59, v59, v184
	v_sub_f32_e32 v60, v60, v184
	v_sub_f32_e32 v61, v61, v184
	v_sub_f32_e32 v62, v62, v184
	v_sub_f32_e32 v63, v63, v184
	v_sub_f32_e32 v64, v64, v184
	v_sub_f32_e32 v65, v65, v184
	v_sub_f32_e32 v66, v66, v184
	v_sub_f32_e32 v67, v67, v184
	v_sub_f32_e32 v68, v68, v184
	v_sub_f32_e32 v69, v69, v184
	v_sub_f32_e32 v70, v70, v184
	v_sub_f32_e32 v71, v71, v184
	v_mul_f32_e32 v180, v56, v56
	v_mul_f32_e32 v181, v60, v60
	v_mul_f32_e32 v182, v64, v64
	v_mul_f32_e32 v183, v68, v68
	v_fmac_f32_e32 v180, v57, v57
	v_fmac_f32_e32 v181, v61, v61
	v_fmac_f32_e32 v182, v65, v65
	v_fmac_f32_e32 v183, v69, v69
	v_fmac_f32_e32 v180, v58, v58
	v_fmac_f32_e32 v181, v62, v62
	v_fmac_f32_e32 v182, v66, v66
	v_fmac_f32_e32 v183, v70, v70
	v_fmac_f32_e32 v180, v59, v59
	v_fmac_f32_e32 v181, v63, v63
	v_fmac_f32_e32 v182, v67, v67
	v_fmac_f32_e32 v183, v71, v71
	v_add_f32_e32 v180, v180, v181
	v_add_f32_e32 v182, v182, v183
	v_add_f32_e32 v180, v180, v182
	s_nop 1
	v_add_f32_dpp v180, v180, v180 quad_perm:[1,0,3,2] row_mask:0xf bank_mask:0xf
	s_nop 1
	v_add_f32_dpp v180, v180, v180 quad_perm:[2,3,0,1] row_mask:0xf bank_mask:0xf
	s_nop 1
	v_add_f32_dpp v180, v180, v180 row_half_mirror row_mask:0xf bank_mask:0xf
	s_nop 1
	v_add_f32_dpp v180, v180, v180 row_mirror row_mask:0xf bank_mask:0xf
	s_nop 1
	v_add_f32_dpp v180, v180, v180 row_bcast:15 row_mask:0xa bank_mask:0xf
	s_nop 1
	v_add_f32_dpp v180, v180, v180 row_bcast:31 row_mask:0xc bank_mask:0xf
	s_nop 0
	v_readlane_b32 s20, v180, 63
	s_nop 1
	v_mov_b32_e32 v185, s20
	v_fma_f32 v185, v185, v2, v4
	v_rsq_f32_e32 v185, v185
	s_nop 0
	v_mul_f32_e32 v56, v56, v185
	v_mul_f32_e32 v57, v57, v185
	v_mul_f32_e32 v58, v58, v185
	v_mul_f32_e32 v59, v59, v185
	v_mul_f32_e32 v60, v60, v185
	v_mul_f32_e32 v61, v61, v185
	v_mul_f32_e32 v62, v62, v185
	v_mul_f32_e32 v63, v63, v185
	v_mul_f32_e32 v64, v64, v185
	v_mul_f32_e32 v65, v65, v185
	v_mul_f32_e32 v66, v66, v185
	v_mul_f32_e32 v67, v67, v185
	v_mul_f32_e32 v68, v68, v185
	v_mul_f32_e32 v69, v69, v185
	v_mul_f32_e32 v70, v70, v185
	v_mul_f32_e32 v71, v71, v185
	v_fma_f32 v56, v56, v8, v24
	v_fma_f32 v57, v57, v9, v25
	v_fma_f32 v58, v58, v10, v26
	v_fma_f32 v59, v59, v11, v27
	v_fma_f32 v60, v60, v12, v28
	v_fma_f32 v61, v61, v13, v29
	v_fma_f32 v62, v62, v14, v30
	v_fma_f32 v63, v63, v15, v31
	v_fma_f32 v64, v64, v16, v32
	v_fma_f32 v65, v65, v17, v33
	v_fma_f32 v66, v66, v18, v34
	v_fma_f32 v67, v67, v19, v35
	v_fma_f32 v68, v68, v20, v36
	v_fma_f32 v69, v69, v21, v37
	v_fma_f32 v70, v70, v22, v38
	v_fma_f32 v71, v71, v23, v39
	v_add_u32_e32 v171, 0x1000, v1
	global_store_dwordx4 v171, v[56:59], s[4:5]
	global_store_dwordx4 v171, v[60:63], s[4:5] offset:1024
	global_store_dwordx4 v171, v[64:67], s[4:5] offset:2048
	global_store_dwordx4 v171, v[68:71], s[4:5] offset:3072
	s_branch .LBB0_29
.Llo_generic:
	v_mbcnt_lo_u32_b32 v0, -1, 0
	v_mbcnt_hi_u32_b32 v0, -1, v0
	v_readlane_b32 s0, v253, 63
	v_add_u32_e32 v1, s29, v0
	s_nop 0
	v_ashrrev_i32_e32 v0, 6, v1
	v_add_u32_e32 v0, s0, v0
	v_cmp_gt_i32_e32 vcc, s2, v0
	s_and_saveexec_b64 s[0:1], vcc
	v_readlane_b32 s10, v254, 25
	v_readlane_b32 s11, v254, 26
	v_readlane_b32 s20, v254, 42
	s_movk_i32 s11, 0x3fff
	v_readlane_b32 s21, v254, 43
	s_mov_b32 s36, 0x3a800000
	s_cbranch_execz .LBB0_28
	s_load_dwordx2 s[6:7], s[4:5], 0xa0
	s_load_dwordx4 s[40:43], s[4:5], 0x90
	s_lshl_b32 s96, s92, 24
	v_readlane_b32 s8, v254, 44
	v_readlane_b32 s9, v254, 45
	s_lshl_b64 s[4:5], s[96:97], 2
	s_mov_b32 s9, s97
	s_waitcnt lgkmcnt(0)
	s_add_u32 s4, s6, s4
	s_addc_u32 s5, s7, s5
	s_mov_b32 s34, s8
	s_lshl_b64 s[8:9], s[8:9], 2
	s_waitcnt vmcnt(3)
	v_and_b32_e32 v44, 63, v1
	v_ashrrev_i32_e32 v1, 31, v0
	s_add_u32 s6, s6, s8
	v_lshlrev_b64 v[4:5], 12, v[0:1]
	s_addc_u32 s7, s7, s9
	v_writelane_b32 v254, s34, 44
	v_lshl_add_u64 v[4:5], s[6:7], 0, v[4:5]
	s_mov_b64 s[6:7], 0x800
	v_writelane_b32 v254, s35, 45
	v_lshl_add_u64 v[46:47], v[4:5], 0, s[6:7]
	s_mov_b64 s[6:7], 0
